# GEMM main loops, loop-edge edit: trip counter, K-offset update and exit test moved from behind the last MFMA of phase 8 into that phase's load segment
# speedup vs baseline: 1.0113x; 1.0020x over previous
; #define LDA(dst, b, h) for (int m = 0; m < 4; ++m) for (int k = 0; k < 2; ++k) \
;     dst[m][k] = *reinterpret_cast<const bf16x8*>((char*)SA(b, h) + a_thr + (m * 2 + k) * 1024)
; #define LDB(dst, b, h) for (int n = 0; n < 2; ++n) for (int k = 0; k < 2; ++k) \
;     dst[n][k] = *reinterpret_cast<const bf16x8*>((char*)SB(b, h) + b_thr + (n * 2 + k) * 1024)
; #define MMA(ai, bj, At, Btf) do { __builtin_amdgcn_s_setprio(1); \
;     for (int m = 0; m < 4; ++m) for (int n = 0; n < 2; ++n) for (int k = 0; k < 2; ++k) \
;       acc[ai][bj][m][n] = __builtin_amdgcn_mfma_f32_16x16x32_bf16(Btf[n][k], At[m][k], acc[ai][bj][m][n], 0, 0, 0); \
;     __builtin_amdgcn_s_setprio(0); } while (0)
; #define WAIT_V(n) asm volatile("s_waitcnt vmcnt(" #n ")" ::: "memory")
; #define WAIT_L(n) asm volatile("s_waitcnt lgkmcnt(" #n ")" ::: "memory")
; #define BAR __builtin_amdgcn_s_barrier()
; #define SCHED __builtin_amdgcn_sched_barrier(0)
; template <bool OVL, bool PANEL = false, class Epi>
; __device__ __forceinline__ void gemm_phase(const bf16_t* __restrict__ A, long lda, const bf16_t* __restrict__ Bt, long ldb, int nM, int nN, int K,
;                                            const Epi& epi, bf16_t* shm, int w0) {
;     ...
;       LDB(B0, 0, 0); SCHED; LDA(At, 0, 0); STAGE(SA(1, 1), A, lda, aoff, brow + HALF, t + 1);
;       WAIT_L(8); BAR; WAIT_L(0); MMA(0, 0, At, B0); BAR; SCHED;
;       LDB(B1, 0, 1); STAGE(SB(0, 0), Bt, ldb, boff, bcol, t + 2);
;       BAR; WAIT_L(0); MMA(0, 1, At, B1); BAR;
;       LDA(At, 0, 1); STAGE(SA(0, 0), A, lda, aoff, brow, t + 2);
;       BAR; WAIT_L(0); MMA(1, 0, At, B0); BAR; SCHED;
;       STAGE(SB(0, 1), Bt, ldb, boff, bcol + HALF, t + 2);
;       WAIT_V(6); BAR; MMA(1, 1, At, B1); BAR;
.LBB0_125:
	ds_read_b128 v[138:141], v218
	ds_read_b128 v[142:145], v218 offset:1024
	ds_read_b128 v[146:149], v218 offset:2048
	ds_read_b128 v[150:153], v218 offset:3072
	s_add_u32 s8, s4, s6
	s_addc_u32 s9, s5, s7
	ds_read_b128 v[154:157], v213
	ds_read_b128 v[158:161], v213 offset:1024
	ds_read_b128 v[162:165], v213 offset:2048
	ds_read_b128 v[166:169], v213 offset:3072
	ds_read_b128 v[170:173], v213 offset:4096
	ds_read_b128 v[174:177], v213 offset:5120
	ds_read_b128 v[178:181], v213 offset:6144
	ds_read_b128 v[182:185], v213 offset:7168
	s_mov_b32 m0, s25
	s_add_u32 s98, s8, s14
	s_addc_u32 s99, s9, s15
	global_load_lds_dwordx4 v203, s[98:99]
	s_mov_b32 m0, s32
	s_add_u32 s98, s8, s16
	s_addc_u32 s99, s9, s17
	global_load_lds_dwordx4 v203, s[98:99]
	s_waitcnt lgkmcnt(8)
	s_waitcnt vmcnt(10)
	s_barrier
	s_waitcnt lgkmcnt(0)
	s_waitcnt lgkmcnt(0)
	v_mfma_f32_16x16x32_bf16 v[126:129], v[138:141], v[154:157], v[126:129]
	v_mfma_f32_16x16x32_bf16 v[122:125], v[146:149], v[154:157], v[122:125]
	v_mfma_f32_16x16x32_bf16 v[118:121], v[138:141], v[162:165], v[118:121]
	v_mfma_f32_16x16x32_bf16 v[114:117], v[146:149], v[162:165], v[114:117]
	v_mfma_f32_16x16x32_bf16 v[110:113], v[138:141], v[170:173], v[110:113]
	v_mfma_f32_16x16x32_bf16 v[106:109], v[146:149], v[170:173], v[106:109]
	v_mfma_f32_16x16x32_bf16 v[102:105], v[138:141], v[178:181], v[102:105]
	v_mfma_f32_16x16x32_bf16 v[98:101], v[146:149], v[178:181], v[98:101]
	v_mfma_f32_16x16x32_bf16 v[126:129], v[142:145], v[158:161], v[126:129]
	v_mfma_f32_16x16x32_bf16 v[122:125], v[150:153], v[158:161], v[122:125]
	v_mfma_f32_16x16x32_bf16 v[118:121], v[142:145], v[166:169], v[118:121]
	v_mfma_f32_16x16x32_bf16 v[114:117], v[150:153], v[166:169], v[114:117]
	v_mfma_f32_16x16x32_bf16 v[110:113], v[142:145], v[174:177], v[110:113]
	v_mfma_f32_16x16x32_bf16 v[106:109], v[150:153], v[174:177], v[106:109]
	v_mfma_f32_16x16x32_bf16 v[102:105], v[142:145], v[182:185], v[102:105]
	v_mfma_f32_16x16x32_bf16 v[98:101], v[150:153], v[182:185], v[98:101]
	s_barrier
	s_add_u32 vcc_lo, s0, s6
	ds_read_b128 v[186:189], v219
	ds_read_b128 v[190:193], v219 offset:1024
	ds_read_b128 v[194:197], v219 offset:2048
	ds_read_b128 v[198:201], v219 offset:3072
	s_addc_u32 vcc_hi, s1, s7
	s_mov_b32 m0, s44
	s_add_u32 s98, vcc_lo, s34
	s_addc_u32 s99, vcc_hi, s35
	global_load_lds_dwordx4 v203, s[98:99]
	s_mov_b32 m0, s45
	s_add_u32 s98, vcc_lo, s18
	s_addc_u32 s99, vcc_hi, s19
	global_load_lds_dwordx4 v203, s[98:99]
	s_waitcnt vmcnt(10)
	s_barrier
	s_waitcnt lgkmcnt(0)
	s_waitcnt lgkmcnt(0)
	v_mfma_f32_16x16x32_bf16 v[94:97], v[186:189], v[154:157], v[94:97]
	v_mfma_f32_16x16x32_bf16 v[90:93], v[194:197], v[154:157], v[90:93]
	v_mfma_f32_16x16x32_bf16 v[86:89], v[186:189], v[162:165], v[86:89]
	v_mfma_f32_16x16x32_bf16 v[82:85], v[194:197], v[162:165], v[82:85]
	v_mfma_f32_16x16x32_bf16 v[78:81], v[186:189], v[170:173], v[78:81]
	v_mfma_f32_16x16x32_bf16 v[74:77], v[194:197], v[170:173], v[74:77]
	v_mfma_f32_16x16x32_bf16 v[70:73], v[186:189], v[178:181], v[70:73]
	v_mfma_f32_16x16x32_bf16 v[66:69], v[194:197], v[178:181], v[66:69]
	v_mfma_f32_16x16x32_bf16 v[94:97], v[190:193], v[158:161], v[94:97]
	v_mfma_f32_16x16x32_bf16 v[90:93], v[198:201], v[158:161], v[90:93]
	v_mfma_f32_16x16x32_bf16 v[86:89], v[190:193], v[166:169], v[86:89]
	v_mfma_f32_16x16x32_bf16 v[82:85], v[198:201], v[166:169], v[82:85]
	v_mfma_f32_16x16x32_bf16 v[78:81], v[190:193], v[174:177], v[78:81]
	v_mfma_f32_16x16x32_bf16 v[74:77], v[198:201], v[174:177], v[74:77]
	v_mfma_f32_16x16x32_bf16 v[70:73], v[190:193], v[182:185], v[70:73]
	v_mfma_f32_16x16x32_bf16 v[66:69], v[198:201], v[182:185], v[66:69]
	s_barrier
	ds_read_b128 v[154:157], v213 offset:16384
	ds_read_b128 v[158:161], v213 offset:17408
	ds_read_b128 v[162:165], v213 offset:18432
	ds_read_b128 v[166:169], v213 offset:19456
	ds_read_b128 v[170:173], v213 offset:20480
	ds_read_b128 v[174:177], v213 offset:21504
	ds_read_b128 v[178:181], v213 offset:22528
	ds_read_b128 v[182:185], v213 offset:23552
	s_mov_b32 m0, s46
	s_add_u32 s98, s8, s34
	s_addc_u32 s99, s9, s35
	global_load_lds_dwordx4 v203, s[98:99]
	s_mov_b32 m0, s47
	s_add_u32 s98, s8, s18
	s_addc_u32 s99, s9, s19
	global_load_lds_dwordx4 v203, s[98:99]
	s_barrier
	s_waitcnt lgkmcnt(0)
	s_waitcnt lgkmcnt(0)
	v_mfma_f32_16x16x32_bf16 v[62:65], v[138:141], v[154:157], v[62:65]
	v_mfma_f32_16x16x32_bf16 v[58:61], v[146:149], v[154:157], v[58:61]
	v_mfma_f32_16x16x32_bf16 v[54:57], v[138:141], v[162:165], v[54:57]
	v_mfma_f32_16x16x32_bf16 v[50:53], v[146:149], v[162:165], v[50:53]
	v_mfma_f32_16x16x32_bf16 v[46:49], v[138:141], v[170:173], v[46:49]
	v_mfma_f32_16x16x32_bf16 v[42:45], v[146:149], v[170:173], v[42:45]
	v_mfma_f32_16x16x32_bf16 v[38:41], v[138:141], v[178:181], v[38:41]
	v_mfma_f32_16x16x32_bf16 v[34:37], v[146:149], v[178:181], v[34:37]
	v_mfma_f32_16x16x32_bf16 v[62:65], v[142:145], v[158:161], v[62:65]
	v_mfma_f32_16x16x32_bf16 v[58:61], v[150:153], v[158:161], v[58:61]
	v_mfma_f32_16x16x32_bf16 v[54:57], v[142:145], v[166:169], v[54:57]
	v_mfma_f32_16x16x32_bf16 v[50:53], v[150:153], v[166:169], v[50:53]
	v_mfma_f32_16x16x32_bf16 v[46:49], v[142:145], v[174:177], v[46:49]
	v_mfma_f32_16x16x32_bf16 v[42:45], v[150:153], v[174:177], v[42:45]
	v_mfma_f32_16x16x32_bf16 v[38:41], v[142:145], v[182:185], v[38:41]
	v_mfma_f32_16x16x32_bf16 v[34:37], v[150:153], v[182:185], v[34:37]
	s_barrier
	s_mov_b32 m0, s48
	s_add_u32 s98, vcc_lo, s30
	s_addc_u32 s99, vcc_hi, s31
	global_load_lds_dwordx4 v203, s[98:99]
	s_mov_b32 m0, s49
	s_add_u32 s98, vcc_lo, s40
	s_addc_u32 s99, vcc_hi, s41
	global_load_lds_dwordx4 v203, s[98:99]
	s_waitcnt vmcnt(10)
	s_barrier
; #define LDA(dst, b, h) for (int m = 0; m < 4; ++m) for (int k = 0; k < 2; ++k) \
;     dst[m][k] = *reinterpret_cast<const bf16x8*>((char*)SA(b, h) + a_thr + (m * 2 + k) * 1024)
; #define LDB(dst, b, h) for (int n = 0; n < 2; ++n) for (int k = 0; k < 2; ++k) \
;     dst[n][k] = *reinterpret_cast<const bf16x8*>((char*)SB(b, h) + b_thr + (n * 2 + k) * 1024)
; #define MMA(ai, bj, At, Btf) do { __builtin_amdgcn_s_setprio(1); \
;     for (int m = 0; m < 4; ++m) for (int n = 0; n < 2; ++n) for (int k = 0; k < 2; ++k) \
;       acc[ai][bj][m][n] = __builtin_amdgcn_mfma_f32_16x16x32_bf16(Btf[n][k], At[m][k], acc[ai][bj][m][n], 0, 0, 0); \
;     __builtin_amdgcn_s_setprio(0); } while (0)
; #define WAIT_V(n) asm volatile("s_waitcnt vmcnt(" #n ")" ::: "memory")
; #define WAIT_L(n) asm volatile("s_waitcnt lgkmcnt(" #n ")" ::: "memory")
; #define BAR __builtin_amdgcn_s_barrier()
; #define SCHED __builtin_amdgcn_sched_barrier(0)
; template <bool OVL, bool PANEL = false, class Epi>
; __device__ __forceinline__ void gemm_phase(const bf16_t* __restrict__ A, long lda, const bf16_t* __restrict__ Bt, long ldb, int nM, int nN, int K,
;                                            const Epi& epi, bf16_t* shm, int w0) {
;     ...
;       WAIT_V(6); BAR; MMA(1, 1, At, B1); BAR;
;       LDB(B0, 1, 0); SCHED; LDA(At, 1, 0); STAGE(SA(0, 1), A, lda, aoff, brow + HALF, t + 2);
;       WAIT_L(8); BAR; WAIT_L(0); MMA(0, 0, At, B0); BAR; SCHED;
;       LDB(B1, 1, 1); STAGE(SB(1, 0), Bt, ldb, boff, bcol, t + 3);
;       BAR; WAIT_L(0); MMA(0, 1, At, B1); BAR;
	v_mfma_f32_16x16x32_bf16 v[30:33], v[186:189], v[154:157], v[30:33]
	v_mfma_f32_16x16x32_bf16 v[26:29], v[194:197], v[154:157], v[26:29]
	v_mfma_f32_16x16x32_bf16 v[22:25], v[186:189], v[162:165], v[22:25]
	v_mfma_f32_16x16x32_bf16 v[18:21], v[194:197], v[162:165], v[18:21]
	v_mfma_f32_16x16x32_bf16 v[14:17], v[186:189], v[170:173], v[14:17]
	v_mfma_f32_16x16x32_bf16 v[10:13], v[194:197], v[170:173], v[10:13]
	v_mfma_f32_16x16x32_bf16 v[6:9], v[186:189], v[178:181], v[6:9]
	v_mfma_f32_16x16x32_bf16 v[2:5], v[194:197], v[178:181], v[2:5]
	v_mfma_f32_16x16x32_bf16 v[30:33], v[190:193], v[158:161], v[30:33]
	v_mfma_f32_16x16x32_bf16 v[26:29], v[198:201], v[158:161], v[26:29]
	v_mfma_f32_16x16x32_bf16 v[22:25], v[190:193], v[166:169], v[22:25]
	v_mfma_f32_16x16x32_bf16 v[18:21], v[198:201], v[166:169], v[18:21]
	v_mfma_f32_16x16x32_bf16 v[14:17], v[190:193], v[174:177], v[14:17]
	v_mfma_f32_16x16x32_bf16 v[10:13], v[198:201], v[174:177], v[10:13]
	v_mfma_f32_16x16x32_bf16 v[6:9], v[190:193], v[182:185], v[6:9]
	v_mfma_f32_16x16x32_bf16 v[2:5], v[198:201], v[182:185], v[2:5]
	s_barrier
	ds_read_b128 v[138:141], v220
	ds_read_b128 v[142:145], v220 offset:1024
	ds_read_b128 v[146:149], v220 offset:2048
	ds_read_b128 v[150:153], v220 offset:3072
	ds_read_b128 v[154:157], v213 offset:32768
	ds_read_b128 v[158:161], v213 offset:33792
	ds_read_b128 v[162:165], v213 offset:34816
	ds_read_b128 v[166:169], v213 offset:35840
	ds_read_b128 v[170:173], v213 offset:36864
	ds_read_b128 v[174:177], v213 offset:37888
	ds_read_b128 v[178:181], v213 offset:38912
	ds_read_b128 v[182:185], v213 offset:39936
	s_mov_b32 m0, s50
	s_add_u32 s98, s8, s30
	s_addc_u32 s99, s9, s31
	global_load_lds_dwordx4 v203, s[98:99]
	s_mov_b32 m0, s51
	s_add_u32 s98, s8, s40
	s_addc_u32 s99, s9, s41
	global_load_lds_dwordx4 v203, s[98:99]
	s_waitcnt lgkmcnt(8)
	s_waitcnt vmcnt(10)
	s_barrier
	s_waitcnt lgkmcnt(0)
	s_waitcnt lgkmcnt(0)
	v_mfma_f32_16x16x32_bf16 v[126:129], v[138:141], v[154:157], v[126:129]
	v_mfma_f32_16x16x32_bf16 v[122:125], v[146:149], v[154:157], v[122:125]
	v_mfma_f32_16x16x32_bf16 v[118:121], v[138:141], v[162:165], v[118:121]
	v_mfma_f32_16x16x32_bf16 v[114:117], v[146:149], v[162:165], v[114:117]
	v_mfma_f32_16x16x32_bf16 v[110:113], v[138:141], v[170:173], v[110:113]
	v_mfma_f32_16x16x32_bf16 v[106:109], v[146:149], v[170:173], v[106:109]
	v_mfma_f32_16x16x32_bf16 v[102:105], v[138:141], v[178:181], v[102:105]
	v_mfma_f32_16x16x32_bf16 v[98:101], v[146:149], v[178:181], v[98:101]
	v_mfma_f32_16x16x32_bf16 v[126:129], v[142:145], v[158:161], v[126:129]
	v_mfma_f32_16x16x32_bf16 v[122:125], v[150:153], v[158:161], v[122:125]
	v_mfma_f32_16x16x32_bf16 v[118:121], v[142:145], v[166:169], v[118:121]
	v_mfma_f32_16x16x32_bf16 v[114:117], v[150:153], v[166:169], v[114:117]
	v_mfma_f32_16x16x32_bf16 v[110:113], v[142:145], v[174:177], v[110:113]
	v_mfma_f32_16x16x32_bf16 v[106:109], v[150:153], v[174:177], v[106:109]
	v_mfma_f32_16x16x32_bf16 v[102:105], v[142:145], v[182:185], v[102:105]
	v_mfma_f32_16x16x32_bf16 v[98:101], v[150:153], v[182:185], v[98:101]
	s_barrier
	ds_read_b128 v[186:189], v221
	ds_read_b128 v[190:193], v221 offset:1024
	ds_read_b128 v[194:197], v221 offset:2048
	ds_read_b128 v[198:201], v221 offset:3072
	s_mov_b32 m0, s52
	s_add_u32 s98, vcc_lo, s94
	s_addc_u32 s99, vcc_hi, s95
	global_load_lds_dwordx4 v203, s[98:99]
	s_mov_b32 m0, s53
	s_add_u32 s98, vcc_lo, s42
	s_addc_u32 s99, vcc_hi, s43
	global_load_lds_dwordx4 v203, s[98:99]
	s_waitcnt vmcnt(10)
	s_barrier
	s_waitcnt lgkmcnt(0)
	s_waitcnt lgkmcnt(0)
	v_mfma_f32_16x16x32_bf16 v[94:97], v[186:189], v[154:157], v[94:97]
	v_mfma_f32_16x16x32_bf16 v[90:93], v[194:197], v[154:157], v[90:93]
	v_mfma_f32_16x16x32_bf16 v[86:89], v[186:189], v[162:165], v[86:89]
	v_mfma_f32_16x16x32_bf16 v[82:85], v[194:197], v[162:165], v[82:85]
	v_mfma_f32_16x16x32_bf16 v[78:81], v[186:189], v[170:173], v[78:81]
	v_mfma_f32_16x16x32_bf16 v[74:77], v[194:197], v[170:173], v[74:77]
	v_mfma_f32_16x16x32_bf16 v[70:73], v[186:189], v[178:181], v[70:73]
	v_mfma_f32_16x16x32_bf16 v[66:69], v[194:197], v[178:181], v[66:69]
	v_mfma_f32_16x16x32_bf16 v[94:97], v[190:193], v[158:161], v[94:97]
	v_mfma_f32_16x16x32_bf16 v[90:93], v[198:201], v[158:161], v[90:93]
	v_mfma_f32_16x16x32_bf16 v[86:89], v[190:193], v[166:169], v[86:89]
	v_mfma_f32_16x16x32_bf16 v[82:85], v[198:201], v[166:169], v[82:85]
	v_mfma_f32_16x16x32_bf16 v[78:81], v[190:193], v[174:177], v[78:81]
	v_mfma_f32_16x16x32_bf16 v[74:77], v[198:201], v[174:177], v[74:77]
	v_mfma_f32_16x16x32_bf16 v[70:73], v[190:193], v[182:185], v[70:73]
	v_mfma_f32_16x16x32_bf16 v[66:69], v[198:201], v[182:185], v[66:69]
	s_barrier
; #define LDA(dst, b, h) for (int m = 0; m < 4; ++m) for (int k = 0; k < 2; ++k) \
;     dst[m][k] = *reinterpret_cast<const bf16x8*>((char*)SA(b, h) + a_thr + (m * 2 + k) * 1024)
; #define LDB(dst, b, h) for (int n = 0; n < 2; ++n) for (int k = 0; k < 2; ++k) \
;     dst[n][k] = *reinterpret_cast<const bf16x8*>((char*)SB(b, h) + b_thr + (n * 2 + k) * 1024)
; #define MMA(ai, bj, At, Btf) do { __builtin_amdgcn_s_setprio(1); \
;     for (int m = 0; m < 4; ++m) for (int n = 0; n < 2; ++n) for (int k = 0; k < 2; ++k) \
;       acc[ai][bj][m][n] = __builtin_amdgcn_mfma_f32_16x16x32_bf16(Btf[n][k], At[m][k], acc[ai][bj][m][n], 0, 0, 0); \
;     __builtin_amdgcn_s_setprio(0); } while (0)
; #define WAIT_V(n) asm volatile("s_waitcnt vmcnt(" #n ")" ::: "memory")
; #define WAIT_L(n) asm volatile("s_waitcnt lgkmcnt(" #n ")" ::: "memory")
; #define BAR __builtin_amdgcn_s_barrier()
; #define SCHED __builtin_amdgcn_sched_barrier(0)
; template <bool OVL, bool PANEL = false, class Epi>
; __device__ __forceinline__ void gemm_phase(const bf16_t* __restrict__ A, long lda, const bf16_t* __restrict__ Bt, long ldb, int nM, int nN, int K,
;                                            const Epi& epi, bf16_t* shm, int w0) {
;     ...
;       LDA(At, 1, 1); STAGE(SA(1, 0), A, lda, aoff, brow, t + 3);
;       BAR; WAIT_L(0); MMA(1, 0, At, B0); BAR; SCHED;
;       STAGE(SB(1, 1), Bt, ldb, boff, bcol + HALF, t + 3);
;       WAIT_V(6); BAR; MMA(1, 1, At, B1); BAR;
;     }
;     { LDB(B0, 0, 0); LDA(At, 0, 0); STAGE(SA(1, 1), A, lda, aoff, brow + HALF, nt - 1);
	ds_read_b128 v[154:157], v213 offset:49152
	ds_read_b128 v[158:161], v213 offset:50176
	ds_read_b128 v[162:165], v213 offset:51200
	ds_read_b128 v[166:169], v213 offset:52224
	ds_read_b128 v[170:173], v213 offset:53248
	ds_read_b128 v[174:177], v213 offset:54272
	ds_read_b128 v[178:181], v213 offset:55296
	ds_read_b128 v[182:185], v213 offset:56320
	s_mov_b32 m0, s54
	s_add_u32 s98, s8, s94
	s_addc_u32 s99, s9, s95
	global_load_lds_dwordx4 v203, s[98:99]
	s_mov_b32 m0, s55
	s_add_u32 s98, s8, s42
	s_addc_u32 s99, s9, s43
	global_load_lds_dwordx4 v203, s[98:99]
	s_barrier
	s_waitcnt lgkmcnt(0)
	s_waitcnt lgkmcnt(0)
	v_mfma_f32_16x16x32_bf16 v[62:65], v[138:141], v[154:157], v[62:65]
	v_mfma_f32_16x16x32_bf16 v[58:61], v[146:149], v[154:157], v[58:61]
	v_mfma_f32_16x16x32_bf16 v[54:57], v[138:141], v[162:165], v[54:57]
	v_mfma_f32_16x16x32_bf16 v[50:53], v[146:149], v[162:165], v[50:53]
	v_mfma_f32_16x16x32_bf16 v[46:49], v[138:141], v[170:173], v[46:49]
	v_mfma_f32_16x16x32_bf16 v[42:45], v[146:149], v[170:173], v[42:45]
	v_mfma_f32_16x16x32_bf16 v[38:41], v[138:141], v[178:181], v[38:41]
	v_mfma_f32_16x16x32_bf16 v[34:37], v[146:149], v[178:181], v[34:37]
	v_mfma_f32_16x16x32_bf16 v[62:65], v[142:145], v[158:161], v[62:65]
	v_mfma_f32_16x16x32_bf16 v[58:61], v[150:153], v[158:161], v[58:61]
	v_mfma_f32_16x16x32_bf16 v[54:57], v[142:145], v[166:169], v[54:57]
	v_mfma_f32_16x16x32_bf16 v[50:53], v[150:153], v[166:169], v[50:53]
	v_mfma_f32_16x16x32_bf16 v[46:49], v[142:145], v[174:177], v[46:49]
	v_mfma_f32_16x16x32_bf16 v[42:45], v[150:153], v[174:177], v[42:45]
	v_mfma_f32_16x16x32_bf16 v[38:41], v[142:145], v[182:185], v[38:41]
	v_mfma_f32_16x16x32_bf16 v[34:37], v[150:153], v[182:185], v[34:37]
	s_barrier
	s_mov_b64 s[8:9], 0xb0180
	s_mov_b64 s[8:9], 0x108180
	s_mov_b32 m0, s60
	s_add_u32 s98, vcc_lo, 0xb0180
	s_addc_u32 s99, vcc_hi, 0
	global_load_lds_dwordx4 v203, s[98:99]
	s_mov_b32 m0, s61
	s_add_u32 s98, vcc_lo, 0x108180
	s_addc_u32 s99, vcc_hi, 0
	global_load_lds_dwordx4 v203, s[98:99]
	s_add_i32 s2, s2, 2
	s_add_u32 s6, s6, 0x100
	s_addc_u32 s7, s7, 0
	s_cmp_gt_u32 s2, 39
	s_waitcnt vmcnt(10)
	s_barrier
	v_mfma_f32_16x16x32_bf16 v[30:33], v[186:189], v[154:157], v[30:33]
	v_mfma_f32_16x16x32_bf16 v[26:29], v[194:197], v[154:157], v[26:29]
	v_mfma_f32_16x16x32_bf16 v[22:25], v[186:189], v[162:165], v[22:25]
	v_mfma_f32_16x16x32_bf16 v[18:21], v[194:197], v[162:165], v[18:21]
	v_mfma_f32_16x16x32_bf16 v[14:17], v[186:189], v[170:173], v[14:17]
	v_mfma_f32_16x16x32_bf16 v[10:13], v[194:197], v[170:173], v[10:13]
	v_mfma_f32_16x16x32_bf16 v[6:9], v[186:189], v[178:181], v[6:9]
	v_mfma_f32_16x16x32_bf16 v[2:5], v[194:197], v[178:181], v[2:5]
	v_mfma_f32_16x16x32_bf16 v[30:33], v[190:193], v[158:161], v[30:33]
	v_mfma_f32_16x16x32_bf16 v[26:29], v[198:201], v[158:161], v[26:29]
	v_mfma_f32_16x16x32_bf16 v[22:25], v[190:193], v[166:169], v[22:25]
	v_mfma_f32_16x16x32_bf16 v[18:21], v[198:201], v[166:169], v[18:21]
	v_mfma_f32_16x16x32_bf16 v[14:17], v[190:193], v[174:177], v[14:17]
	v_mfma_f32_16x16x32_bf16 v[10:13], v[198:201], v[174:177], v[10:13]
	v_mfma_f32_16x16x32_bf16 v[6:9], v[190:193], v[182:185], v[6:9]
	v_mfma_f32_16x16x32_bf16 v[2:5], v[198:201], v[182:185], v[2:5]
	s_barrier
	s_cbranch_scc0 .LBB0_125
	s_waitcnt vmcnt(6)
	s_or_b32 s0, s28, 0x80
	s_mul_hi_i32 s1, s0, 0x1600
	s_mulk_i32 s0, 0x1600
	v_readlane_b32 s2, v250, 49
	v_add_u32_e32 v227, 16, v212
	s_add_u32 s0, s2, s0
	v_readlane_b32 s2, v250, 50
	v_add_u32_e32 v0, 0x10000, v227
	s_addc_u32 s1, s2, s1
	v_readfirstlane_b32 s2, v136
	ds_read_b128 v[130:133], v0
	ds_read_b128 v[138:141], v0 offset:1024
	ds_read_b128 v[142:145], v0 offset:2048
	ds_read_b128 v[146:149], v0 offset:3072
	ds_read_b128 v[150:153], v213
	ds_read_b128 v[154:157], v213 offset:1024
	ds_read_b128 v[158:161], v213 offset:2048
	ds_read_b128 v[162:165], v213 offset:3072
	ds_read_b128 v[166:169], v213 offset:4096
	ds_read_b128 v[170:173], v213 offset:5120
	ds_read_b128 v[174:177], v213 offset:6144
	ds_read_b128 v[178:181], v213 offset:7168
	v_mov_b32_e32 v0, v203
	s_mov_b32 m0, s2
	s_nop 0
	v_lshl_add_u64 v[134:135], s[0:1], 0, v[0:1]
	global_load_lds_dwordx4 v0, s[0:1]
	v_readfirstlane_b32 s0, v137
	v_lshl_add_u64 v[134:135], v[134:135], 0, s[26:27]
	s_mov_b32 m0, s0
	s_nop 0
	global_load_lds_dwordx4 v[134:135], off
	s_barrier
	s_waitcnt lgkmcnt(0)

; #define LDA(dst, b, h) for (int m = 0; m < 4; ++m) for (int k = 0; k < 2; ++k) \
;     dst[m][k] = *reinterpret_cast<const bf16x8*>((char*)SA(b, h) + a_thr + (m * 2 + k) * 1024)
; #define LDB(dst, b, h) for (int n = 0; n < 2; ++n) for (int k = 0; k < 2; ++k) \
;     dst[n][k] = *reinterpret_cast<const bf16x8*>((char*)SB(b, h) + b_thr + (n * 2 + k) * 1024)
; #define MMA(ai, bj, At, Btf) do { __builtin_amdgcn_s_setprio(1); \
;     for (int m = 0; m < 4; ++m) for (int n = 0; n < 2; ++n) for (int k = 0; k < 2; ++k) \
;       acc[ai][bj][m][n] = __builtin_amdgcn_mfma_f32_16x16x32_bf16(Btf[n][k], At[m][k], acc[ai][bj][m][n], 0, 0, 0); \
;     __builtin_amdgcn_s_setprio(0); } while (0)
; #define WAIT_L(n) asm volatile("s_waitcnt lgkmcnt(" #n ")" ::: "memory")
; #define BAR __builtin_amdgcn_s_barrier()
; template <bool OVL, bool PANEL = false, class Epi>
; __device__ __forceinline__ void gemm_phase(const bf16_t* __restrict__ A, long lda, const bf16_t* __restrict__ Bt, long ldb, int nM, int nN, int K,
;                                            const Epi& epi, bf16_t* shm, int w0) {
;     ...
;     { LDB(B0, 0, 0); LDA(At, 0, 0); STAGE(SA(1, 1), A, lda, aoff, brow + HALF, nt - 1);
;       BAR; WAIT_L(0); MMA(0, 0, At, B0); BAR;
	s_waitcnt lgkmcnt(0)
	v_mfma_f32_16x16x32_bf16 v[126:129], v[130:133], v[150:153], v[126:129]
	v_mfma_f32_16x16x32_bf16 v[122:125], v[142:145], v[150:153], v[122:125]
	v_mfma_f32_16x16x32_bf16 v[118:121], v[130:133], v[158:161], v[118:121]
	v_mfma_f32_16x16x32_bf16 v[114:117], v[142:145], v[158:161], v[114:117]
	v_mfma_f32_16x16x32_bf16 v[110:113], v[130:133], v[166:169], v[110:113]
	v_mfma_f32_16x16x32_bf16 v[106:109], v[142:145], v[166:169], v[106:109]
	v_mfma_f32_16x16x32_bf16 v[102:105], v[130:133], v[174:177], v[102:105]
	v_mfma_f32_16x16x32_bf16 v[98:101], v[142:145], v[174:177], v[98:101]
	v_mfma_f32_16x16x32_bf16 v[126:129], v[138:141], v[154:157], v[126:129]
	v_mfma_f32_16x16x32_bf16 v[122:125], v[146:149], v[154:157], v[122:125]
	v_mfma_f32_16x16x32_bf16 v[118:121], v[138:141], v[162:165], v[118:121]
	v_mfma_f32_16x16x32_bf16 v[114:117], v[146:149], v[162:165], v[114:117]
	v_mfma_f32_16x16x32_bf16 v[110:113], v[138:141], v[170:173], v[110:113]
	v_mfma_f32_16x16x32_bf16 v[106:109], v[146:149], v[170:173], v[106:109]
	v_mfma_f32_16x16x32_bf16 v[102:105], v[138:141], v[178:181], v[102:105]
	v_mfma_f32_16x16x32_bf16 v[98:101], v[146:149], v[178:181], v[98:101]

; #define LDB(dst, b, h) for (int n = 0; n < 2; ++n) for (int k = 0; k < 2; ++k) \
;     dst[n][k] = *reinterpret_cast<const bf16x8*>((char*)SB(b, h) + b_thr + (n * 2 + k) * 1024)
; #define MMA(ai, bj, At, Btf) do { __builtin_amdgcn_s_setprio(1); \
;     for (int m = 0; m < 4; ++m) for (int n = 0; n < 2; ++n) for (int k = 0; k < 2; ++k) \
;       acc[ai][bj][m][n] = __builtin_amdgcn_mfma_f32_16x16x32_bf16(Btf[n][k], At[m][k], acc[ai][bj][m][n], 0, 0, 0); \
;     __builtin_amdgcn_s_setprio(0); } while (0)
; #define WAIT_L(n) asm volatile("s_waitcnt lgkmcnt(" #n ")" ::: "memory")
; #define BAR __builtin_amdgcn_s_barrier()
; template <bool OVL, bool PANEL = false, class Epi>
; __device__ __forceinline__ void gemm_phase(const bf16_t* __restrict__ A, long lda, const bf16_t* __restrict__ Bt, long ldb, int nM, int nN, int K,
;                                            const Epi& epi, bf16_t* shm, int w0) {
;     ...
;       LDB(B1, 0, 1); BAR; WAIT_L(0); MMA(0, 1, At, B1); BAR;
	v_add_u32_e32 v0, 0x14000, v227
	s_barrier
	ds_read_b128 v[134:137], v0
	ds_read_b128 v[182:185], v0 offset:1024
	ds_read_b128 v[186:189], v0 offset:2048
	ds_read_b128 v[190:193], v0 offset:3072
	s_barrier
	s_waitcnt lgkmcnt(0)

; #define LDB(dst, b, h) for (int n = 0; n < 2; ++n) for (int k = 0; k < 2; ++k) \
;     dst[n][k] = *reinterpret_cast<const bf16x8*>((char*)SB(b, h) + b_thr + (n * 2 + k) * 1024)
; #define MMA(ai, bj, At, Btf) do { __builtin_amdgcn_s_setprio(1); \
;     for (int m = 0; m < 4; ++m) for (int n = 0; n < 2; ++n) for (int k = 0; k < 2; ++k) \
;       acc[ai][bj][m][n] = __builtin_amdgcn_mfma_f32_16x16x32_bf16(Btf[n][k], At[m][k], acc[ai][bj][m][n], 0, 0, 0); \
;     __builtin_amdgcn_s_setprio(0); } while (0)
; #define WAIT_L(n) asm volatile("s_waitcnt lgkmcnt(" #n ")" ::: "memory")
; #define BAR __builtin_amdgcn_s_barrier()
; template <bool OVL, bool PANEL = false, class Epi>
; __device__ __forceinline__ void gemm_phase(const bf16_t* __restrict__ A, long lda, const bf16_t* __restrict__ Bt, long ldb, int nM, int nN, int K,
;                                            const Epi& epi, bf16_t* shm, int w0) {
;     ...
;       LDB(B1, 0, 1); BAR; WAIT_L(0); MMA(0, 1, At, B1); BAR;
	s_waitcnt lgkmcnt(0)
	v_mfma_f32_16x16x32_bf16 v[94:97], v[134:137], v[150:153], v[94:97]
	v_mfma_f32_16x16x32_bf16 v[90:93], v[186:189], v[150:153], v[90:93]
	v_mfma_f32_16x16x32_bf16 v[86:89], v[134:137], v[158:161], v[86:89]
	v_mfma_f32_16x16x32_bf16 v[82:85], v[186:189], v[158:161], v[82:85]
	v_mfma_f32_16x16x32_bf16 v[78:81], v[134:137], v[166:169], v[78:81]
	v_mfma_f32_16x16x32_bf16 v[66:69], v[186:189], v[174:177], v[66:69]
	v_mfma_f32_16x16x32_bf16 v[94:97], v[182:185], v[154:157], v[94:97]
	v_mfma_f32_16x16x32_bf16 v[90:93], v[190:193], v[154:157], v[90:93]
	v_mfma_f32_16x16x32_bf16 v[86:89], v[182:185], v[162:165], v[86:89]
	v_mfma_f32_16x16x32_bf16 v[82:85], v[190:193], v[162:165], v[82:85]
	v_mfma_f32_16x16x32_bf16 v[78:81], v[182:185], v[170:173], v[78:81]
	v_mfma_f32_16x16x32_bf16 v[74:77], v[186:189], v[166:169], v[74:77]
	v_mfma_f32_16x16x32_bf16 v[70:73], v[134:137], v[174:177], v[70:73]
	v_mfma_f32_16x16x32_bf16 v[66:69], v[190:193], v[178:181], v[66:69]
	v_mfma_f32_16x16x32_bf16 v[150:153], v[190:193], v[170:173], v[74:77]
	v_mfma_f32_16x16x32_bf16 v[154:157], v[182:185], v[178:181], v[70:73]

; #define LDA(dst, b, h) for (int m = 0; m < 4; ++m) for (int k = 0; k < 2; ++k) \
;     dst[m][k] = *reinterpret_cast<const bf16x8*>((char*)SA(b, h) + a_thr + (m * 2 + k) * 1024)
; #define MMA(ai, bj, At, Btf) do { __builtin_amdgcn_s_setprio(1); \
;     for (int m = 0; m < 4; ++m) for (int n = 0; n < 2; ++n) for (int k = 0; k < 2; ++k) \
;       acc[ai][bj][m][n] = __builtin_amdgcn_mfma_f32_16x16x32_bf16(Btf[n][k], At[m][k], acc[ai][bj][m][n], 0, 0, 0); \
;     __builtin_amdgcn_s_setprio(0); } while (0)
; #define WAIT_V(n) asm volatile("s_waitcnt vmcnt(" #n ")" ::: "memory")
; #define WAIT_L(n) asm volatile("s_waitcnt lgkmcnt(" #n ")" ::: "memory")
; #define BAR __builtin_amdgcn_s_barrier()
; template <bool OVL, bool PANEL = false, class Epi>
; __device__ __forceinline__ void gemm_phase(const bf16_t* __restrict__ A, long lda, const bf16_t* __restrict__ Bt, long ldb, int nM, int nN, int K,
;                                            const Epi& epi, bf16_t* shm, int w0) {
;     ...
;       LDA(At, 0, 1); WAIT_V(4); BAR; WAIT_L(0); MMA(1, 0, At, B0); MMA(1, 1, At, B1); BAR; }
	s_barrier
	s_nop 2
	ds_read_b128 v[70:73], v213 offset:16384
	ds_read_b128 v[74:77], v213 offset:17408
	ds_read_b128 v[158:161], v213 offset:18432
	ds_read_b128 v[162:165], v213 offset:19456
	ds_read_b128 v[166:169], v213 offset:20480
	ds_read_b128 v[170:173], v213 offset:21504
	ds_read_b128 v[174:177], v213 offset:22528
	ds_read_b128 v[178:181], v213 offset:23552
	s_waitcnt vmcnt(4)
	s_barrier
	s_waitcnt lgkmcnt(0)

; #define LDA(dst, b, h) for (int m = 0; m < 4; ++m) for (int k = 0; k < 2; ++k) \
;     dst[m][k] = *reinterpret_cast<const bf16x8*>((char*)SA(b, h) + a_thr + (m * 2 + k) * 1024)
; #define MMA(ai, bj, At, Btf) do { __builtin_amdgcn_s_setprio(1); \
;     for (int m = 0; m < 4; ++m) for (int n = 0; n < 2; ++n) for (int k = 0; k < 2; ++k) \
;       acc[ai][bj][m][n] = __builtin_amdgcn_mfma_f32_16x16x32_bf16(Btf[n][k], At[m][k], acc[ai][bj][m][n], 0, 0, 0); \
;     __builtin_amdgcn_s_setprio(0); } while (0)
; #define WAIT_V(n) asm volatile("s_waitcnt vmcnt(" #n ")" ::: "memory")
; #define WAIT_L(n) asm volatile("s_waitcnt lgkmcnt(" #n ")" ::: "memory")
; #define BAR __builtin_amdgcn_s_barrier()
; template <bool OVL, bool PANEL = false, class Epi>
; __device__ __forceinline__ void gemm_phase(const bf16_t* __restrict__ A, long lda, const bf16_t* __restrict__ Bt, long ldb, int nM, int nN, int K,
;                                            const Epi& epi, bf16_t* shm, int w0) {
;     ...
;       LDA(At, 0, 1); WAIT_V(4); BAR; WAIT_L(0); MMA(1, 0, At, B0); MMA(1, 1, At, B1); BAR; }
	s_waitcnt lgkmcnt(0)
	v_mfma_f32_16x16x32_bf16 v[58:61], v[142:145], v[70:73], v[58:61]
	v_mfma_f32_16x16x32_bf16 v[54:57], v[130:133], v[158:161], v[54:57]
	v_mfma_f32_16x16x32_bf16 v[62:65], v[130:133], v[70:73], v[62:65]
	v_mfma_f32_16x16x32_bf16 v[58:61], v[146:149], v[74:77], v[58:61]
	v_mfma_f32_16x16x32_bf16 v[54:57], v[138:141], v[162:165], v[54:57]
	v_mfma_f32_16x16x32_bf16 v[50:53], v[142:145], v[158:161], v[50:53]
	v_mfma_f32_16x16x32_bf16 v[46:49], v[130:133], v[166:169], v[46:49]
	v_mfma_f32_16x16x32_bf16 v[42:45], v[142:145], v[166:169], v[42:45]
	v_mfma_f32_16x16x32_bf16 v[38:41], v[130:133], v[174:177], v[38:41]
	v_mfma_f32_16x16x32_bf16 v[34:37], v[142:145], v[174:177], v[34:37]
	v_mfma_f32_16x16x32_bf16 v[194:197], v[138:141], v[74:77], v[62:65]
	v_mfma_f32_16x16x32_bf16 v[198:201], v[146:149], v[162:165], v[50:53]
	v_mfma_f32_16x16x32_bf16 v[214:217], v[138:141], v[170:173], v[46:49]
	v_mfma_f32_16x16x32_bf16 v[218:221], v[146:149], v[170:173], v[42:45]
	v_mfma_f32_16x16x32_bf16 v[130:133], v[138:141], v[178:181], v[38:41]
	v_mfma_f32_16x16x32_bf16 v[138:141], v[146:149], v[178:181], v[34:37]


; #define LDA(dst, b, h) for (int m = 0; m < 4; ++m) for (int k = 0; k < 2; ++k) \
;     dst[m][k] = *reinterpret_cast<const bf16x8*>((char*)SA(b, h) + a_thr + (m * 2 + k) * 1024)
; #define MMA(ai, bj, At, Btf) do { __builtin_amdgcn_s_setprio(1); \
;     for (int m = 0; m < 4; ++m) for (int n = 0; n < 2; ++n) for (int k = 0; k < 2; ++k) \
;       acc[ai][bj][m][n] = __builtin_amdgcn_mfma_f32_16x16x32_bf16(Btf[n][k], At[m][k], acc[ai][bj][m][n], 0, 0, 0); \
;     __builtin_amdgcn_s_setprio(0); } while (0)
; #define WAIT_V(n) asm volatile("s_waitcnt vmcnt(" #n ")" ::: "memory")
; #define WAIT_L(n) asm volatile("s_waitcnt lgkmcnt(" #n ")" ::: "memory")
; #define BAR __builtin_amdgcn_s_barrier()
; template <bool OVL, bool PANEL = false, class Epi>
; __device__ __forceinline__ void gemm_phase(const bf16_t* __restrict__ A, long lda, const bf16_t* __restrict__ Bt, long ldb, int nM, int nN, int K,
;                                            const Epi& epi, bf16_t* shm, int w0) {
;     ...
;       LDA(At, 0, 1); WAIT_V(4); BAR; WAIT_L(0); MMA(1, 0, At, B0); MMA(1, 1, At, B1); BAR; }
	v_mfma_f32_16x16x32_bf16 v[30:33], v[134:137], v[70:73], v[30:33]
	v_mfma_f32_16x16x32_bf16 v[26:29], v[186:189], v[70:73], v[26:29]
	v_mfma_f32_16x16x32_bf16 v[22:25], v[134:137], v[158:161], v[22:25]
	v_mfma_f32_16x16x32_bf16 v[18:21], v[186:189], v[158:161], v[18:21]
	v_mfma_f32_16x16x32_bf16 v[14:17], v[134:137], v[166:169], v[14:17]
	v_mfma_f32_16x16x32_bf16 v[10:13], v[186:189], v[166:169], v[10:13]
	v_mfma_f32_16x16x32_bf16 v[6:9], v[134:137], v[174:177], v[6:9]
	v_mfma_f32_16x16x32_bf16 v[2:5], v[186:189], v[174:177], v[2:5]
	v_mfma_f32_16x16x32_bf16 v[142:145], v[182:185], v[74:77], v[30:33]
	v_mfma_f32_16x16x32_bf16 v[146:149], v[190:193], v[74:77], v[26:29]
	v_mfma_f32_16x16x32_bf16 v[222:225], v[182:185], v[162:165], v[22:25]
	v_mfma_f32_16x16x32_bf16 v[158:161], v[190:193], v[162:165], v[18:21]
	v_mfma_f32_16x16x32_bf16 v[162:165], v[182:185], v[170:173], v[14:17]
	v_mfma_f32_16x16x32_bf16 v[166:169], v[190:193], v[170:173], v[10:13]
	v_mfma_f32_16x16x32_bf16 v[134:137], v[182:185], v[178:181], v[6:9]
	v_mfma_f32_16x16x32_bf16 v[170:173], v[190:193], v[178:181], v[2:5]

; #define LDA(dst, b, h) for (int m = 0; m < 4; ++m) for (int k = 0; k < 2; ++k) \
;     dst[m][k] = *reinterpret_cast<const bf16x8*>((char*)SA(b, h) + a_thr + (m * 2 + k) * 1024)
; #define LDB(dst, b, h) for (int n = 0; n < 2; ++n) for (int k = 0; k < 2; ++k) \
;     dst[n][k] = *reinterpret_cast<const bf16x8*>((char*)SB(b, h) + b_thr + (n * 2 + k) * 1024)
; #define MMA(ai, bj, At, Btf) do { __builtin_amdgcn_s_setprio(1); \
;     for (int m = 0; m < 4; ++m) for (int n = 0; n < 2; ++n) for (int k = 0; k < 2; ++k) \
;       acc[ai][bj][m][n] = __builtin_amdgcn_mfma_f32_16x16x32_bf16(Btf[n][k], At[m][k], acc[ai][bj][m][n], 0, 0, 0); \
;     __builtin_amdgcn_s_setprio(0); } while (0)
; #define WAIT_V(n) asm volatile("s_waitcnt vmcnt(" #n ")" ::: "memory")
; #define WAIT_L(n) asm volatile("s_waitcnt lgkmcnt(" #n ")" ::: "memory")
; #define BAR __builtin_amdgcn_s_barrier()
; template <bool OVL, bool PANEL = false, class Epi>
; __device__ __forceinline__ void gemm_phase(const bf16_t* __restrict__ A, long lda, const bf16_t* __restrict__ Bt, long ldb, int nM, int nN, int K,
;                                            const Epi& epi, bf16_t* shm, int w0) {
;     ...
;     { LDB(B0, 1, 0); LDA(At, 1, 0); WAIT_V(2); BAR; WAIT_L(0); MMA(0, 0, At, B0); BAR;
	v_add_u32_e32 v0, 0x18000, v227
	s_barrier
	ds_read_b128 v[34:37], v0
	ds_read_b128 v[174:177], v0 offset:1024
	ds_read_b128 v[178:181], v0 offset:2048
	ds_read_b128 v[182:185], v0 offset:3072
	ds_read_b128 v[18:21], v213 offset:32768
	ds_read_b128 v[22:25], v213 offset:33792
	ds_read_b128 v[26:29], v213 offset:34816
	ds_read_b128 v[50:53], v213 offset:35840
	ds_read_b128 v[186:189], v213 offset:36864
	ds_read_b128 v[190:193], v213 offset:37888
	ds_read_b128 v[228:231], v213 offset:38912
	ds_read_b128 v[232:235], v213 offset:39936
	s_waitcnt vmcnt(2)
	s_barrier
	s_waitcnt lgkmcnt(0)

; #define LDA(dst, b, h) for (int m = 0; m < 4; ++m) for (int k = 0; k < 2; ++k) \
;     dst[m][k] = *reinterpret_cast<const bf16x8*>((char*)SA(b, h) + a_thr + (m * 2 + k) * 1024)
; #define LDB(dst, b, h) for (int n = 0; n < 2; ++n) for (int k = 0; k < 2; ++k) \
;     dst[n][k] = *reinterpret_cast<const bf16x8*>((char*)SB(b, h) + b_thr + (n * 2 + k) * 1024)
; #define MMA(ai, bj, At, Btf) do { __builtin_amdgcn_s_setprio(1); \
;     for (int m = 0; m < 4; ++m) for (int n = 0; n < 2; ++n) for (int k = 0; k < 2; ++k) \
;       acc[ai][bj][m][n] = __builtin_amdgcn_mfma_f32_16x16x32_bf16(Btf[n][k], At[m][k], acc[ai][bj][m][n], 0, 0, 0); \
;     __builtin_amdgcn_s_setprio(0); } while (0)
; #define WAIT_V(n) asm volatile("s_waitcnt vmcnt(" #n ")" ::: "memory")
; #define WAIT_L(n) asm volatile("s_waitcnt lgkmcnt(" #n ")" ::: "memory")
; #define BAR __builtin_amdgcn_s_barrier()
; template <bool OVL, bool PANEL = false, class Epi>
; __device__ __forceinline__ void gemm_phase(const bf16_t* __restrict__ A, long lda, const bf16_t* __restrict__ Bt, long ldb, int nM, int nN, int K,
;                                            const Epi& epi, bf16_t* shm, int w0) {
;     ...
;     { LDB(B0, 1, 0); LDA(At, 1, 0); WAIT_V(2); BAR; WAIT_L(0); MMA(0, 0, At, B0); BAR;
	s_waitcnt lgkmcnt(0)
	v_mfma_f32_16x16x32_bf16 v[6:9], v[178:181], v[18:21], v[122:125]
	v_mfma_f32_16x16x32_bf16 v[10:13], v[178:181], v[26:29], v[114:117]
	v_mfma_f32_16x16x32_bf16 v[14:17], v[178:181], v[186:189], v[106:109]
	v_mfma_f32_16x16x32_bf16 v[2:5], v[34:37], v[18:21], v[126:129]
	v_mfma_f32_16x16x32_bf16 v[30:33], v[182:185], v[22:25], v[6:9]
	v_mfma_f32_16x16x32_bf16 v[6:9], v[34:37], v[26:29], v[118:121]
	v_mfma_f32_16x16x32_bf16 v[38:41], v[182:185], v[50:53], v[10:13]
	v_mfma_f32_16x16x32_bf16 v[10:13], v[34:37], v[186:189], v[110:113]
	v_mfma_f32_16x16x32_bf16 v[42:45], v[182:185], v[190:193], v[14:17]
	v_mfma_f32_16x16x32_bf16 v[14:17], v[34:37], v[228:231], v[102:105]
	v_mfma_f32_16x16x32_bf16 v[46:49], v[178:181], v[228:231], v[98:101]
	v_mfma_f32_16x16x32_bf16 v[2:5], v[174:177], v[22:25], v[2:5]
	v_mfma_f32_16x16x32_bf16 v[6:9], v[174:177], v[50:53], v[6:9]
	v_mfma_f32_16x16x32_bf16 v[10:13], v[174:177], v[190:193], v[10:13]
	v_mfma_f32_16x16x32_bf16 v[14:17], v[174:177], v[232:235], v[14:17]
	v_mfma_f32_16x16x32_bf16 v[46:49], v[182:185], v[232:235], v[46:49]

; #define LDB(dst, b, h) for (int n = 0; n < 2; ++n) for (int k = 0; k < 2; ++k) \
;     dst[n][k] = *reinterpret_cast<const bf16x8*>((char*)SB(b, h) + b_thr + (n * 2 + k) * 1024)
; #define MMA(ai, bj, At, Btf) do { __builtin_amdgcn_s_setprio(1); \
;     for (int m = 0; m < 4; ++m) for (int n = 0; n < 2; ++n) for (int k = 0; k < 2; ++k) \
;       acc[ai][bj][m][n] = __builtin_amdgcn_mfma_f32_16x16x32_bf16(Btf[n][k], At[m][k], acc[ai][bj][m][n], 0, 0, 0); \
;     __builtin_amdgcn_s_setprio(0); } while (0)
; #define WAIT_V(n) asm volatile("s_waitcnt vmcnt(" #n ")" ::: "memory")
; #define WAIT_L(n) asm volatile("s_waitcnt lgkmcnt(" #n ")" ::: "memory")
; #define BAR __builtin_amdgcn_s_barrier()
; template <bool OVL, bool PANEL = false, class Epi>
; __device__ __forceinline__ void gemm_phase(const bf16_t* __restrict__ A, long lda, const bf16_t* __restrict__ Bt, long ldb, int nM, int nN, int K,
;                                            const Epi& epi, bf16_t* shm, int w0) {
;     ...
;       LDB(B1, 1, 1); WAIT_V(0); BAR; WAIT_L(0); MMA(0, 1, At, B1); BAR;
	v_add_u32_e32 v0, 0x1c000, v227
	s_barrier
	ds_read_b128 v[102:105], v0
	ds_read_b128 v[236:239], v0 offset:1024
	ds_read_b128 v[240:243], v0 offset:2048
	ds_read_b128 v[244:247], v0 offset:3072
	s_waitcnt vmcnt(0)
	s_barrier
	s_waitcnt lgkmcnt(0)

; #define LDB(dst, b, h) for (int n = 0; n < 2; ++n) for (int k = 0; k < 2; ++k) \
;     dst[n][k] = *reinterpret_cast<const bf16x8*>((char*)SB(b, h) + b_thr + (n * 2 + k) * 1024)
; #define MMA(ai, bj, At, Btf) do { __builtin_amdgcn_s_setprio(1); \
;     for (int m = 0; m < 4; ++m) for (int n = 0; n < 2; ++n) for (int k = 0; k < 2; ++k) \
;       acc[ai][bj][m][n] = __builtin_amdgcn_mfma_f32_16x16x32_bf16(Btf[n][k], At[m][k], acc[ai][bj][m][n], 0, 0, 0); \
;     __builtin_amdgcn_s_setprio(0); } while (0)
; #define WAIT_V(n) asm volatile("s_waitcnt vmcnt(" #n ")" ::: "memory")
; #define WAIT_L(n) asm volatile("s_waitcnt lgkmcnt(" #n ")" ::: "memory")
; #define BAR __builtin_amdgcn_s_barrier()
; template <bool OVL, bool PANEL = false, class Epi>
; __device__ __forceinline__ void gemm_phase(const bf16_t* __restrict__ A, long lda, const bf16_t* __restrict__ Bt, long ldb, int nM, int nN, int K,
;                                            const Epi& epi, bf16_t* shm, int w0) {
;     ...
;       LDB(B1, 1, 1); WAIT_V(0); BAR; WAIT_L(0); MMA(0, 1, At, B1); BAR;
	s_waitcnt lgkmcnt(0)
	v_mfma_f32_16x16x32_bf16 v[62:65], v[102:105], v[18:21], v[94:97]
	v_mfma_f32_16x16x32_bf16 v[18:21], v[240:243], v[18:21], v[90:93]
	v_mfma_f32_16x16x32_bf16 v[98:101], v[244:247], v[22:25], v[18:21]
	v_mfma_f32_16x16x32_bf16 v[18:21], v[102:105], v[26:29], v[86:89]
	v_mfma_f32_16x16x32_bf16 v[70:73], v[236:239], v[50:53], v[18:21]
	v_mfma_f32_16x16x32_bf16 v[18:21], v[240:243], v[26:29], v[82:85]
	v_mfma_f32_16x16x32_bf16 v[106:109], v[244:247], v[50:53], v[18:21]
	v_mfma_f32_16x16x32_bf16 v[18:21], v[102:105], v[186:189], v[78:81]
	v_mfma_f32_16x16x32_bf16 v[74:77], v[236:239], v[190:193], v[18:21]
	v_mfma_f32_16x16x32_bf16 v[18:21], v[240:243], v[186:189], v[150:153]
	v_mfma_f32_16x16x32_bf16 v[110:113], v[244:247], v[190:193], v[18:21]
	v_mfma_f32_16x16x32_bf16 v[18:21], v[102:105], v[228:231], v[154:157]
	v_mfma_f32_16x16x32_bf16 v[78:81], v[236:239], v[232:235], v[18:21]
	v_mfma_f32_16x16x32_bf16 v[18:21], v[240:243], v[228:231], v[66:69]
	v_mfma_f32_16x16x32_bf16 v[62:65], v[236:239], v[22:25], v[62:65]
	v_mfma_f32_16x16x32_bf16 v[114:117], v[244:247], v[232:235], v[18:21]

; #define LDA(dst, b, h) for (int m = 0; m < 4; ++m) for (int k = 0; k < 2; ++k) \
;     dst[m][k] = *reinterpret_cast<const bf16x8*>((char*)SA(b, h) + a_thr + (m * 2 + k) * 1024)
; #define MMA(ai, bj, At, Btf) do { __builtin_amdgcn_s_setprio(1); \
;     for (int m = 0; m < 4; ++m) for (int n = 0; n < 2; ++n) for (int k = 0; k < 2; ++k) \
;       acc[ai][bj][m][n] = __builtin_amdgcn_mfma_f32_16x16x32_bf16(Btf[n][k], At[m][k], acc[ai][bj][m][n], 0, 0, 0); \
;     __builtin_amdgcn_s_setprio(0); } while (0)
; #define WAIT_L(n) asm volatile("s_waitcnt lgkmcnt(" #n ")" ::: "memory")
; #define BAR __builtin_amdgcn_s_barrier()
; template <bool OVL, bool PANEL = false, class Epi>
; __device__ __forceinline__ void gemm_phase(const bf16_t* __restrict__ A, long lda, const bf16_t* __restrict__ Bt, long ldb, int nM, int nN, int K,
;                                            const Epi& epi, bf16_t* shm, int w0) {
;     ...
;       LDA(At, 1, 1); BAR; WAIT_L(0); MMA(1, 0, At, B0); MMA(1, 1, At, B1); BAR; }
	s_barrier
	ds_read_b128 v[86:89], v213 offset:49152
	ds_read_b128 v[90:93], v213 offset:50176
	ds_read_b128 v[94:97], v213 offset:51200
	ds_read_b128 v[118:121], v213 offset:52224
	ds_read_b128 v[150:153], v213 offset:53248
	ds_read_b128 v[154:157], v213 offset:54272
	ds_read_b128 v[186:189], v213 offset:55296
	ds_read_b128 v[190:193], v213 offset:56320
	s_barrier
	s_waitcnt lgkmcnt(0)

; #define LDA(dst, b, h) for (int m = 0; m < 4; ++m) for (int k = 0; k < 2; ++k) \
;     dst[m][k] = *reinterpret_cast<const bf16x8*>((char*)SA(b, h) + a_thr + (m * 2 + k) * 1024)
; #define MMA(ai, bj, At, Btf) do { __builtin_amdgcn_s_setprio(1); \
;     for (int m = 0; m < 4; ++m) for (int n = 0; n < 2; ++n) for (int k = 0; k < 2; ++k) \
;       acc[ai][bj][m][n] = __builtin_amdgcn_mfma_f32_16x16x32_bf16(Btf[n][k], At[m][k], acc[ai][bj][m][n], 0, 0, 0); \
;     __builtin_amdgcn_s_setprio(0); } while (0)
; #define WAIT_L(n) asm volatile("s_waitcnt lgkmcnt(" #n ")" ::: "memory")
; #define BAR __builtin_amdgcn_s_barrier()
; template <bool OVL, bool PANEL = false, class Epi>
; __device__ __forceinline__ void gemm_phase(const bf16_t* __restrict__ A, long lda, const bf16_t* __restrict__ Bt, long ldb, int nM, int nN, int K,
;                                            const Epi& epi, bf16_t* shm, int w0) {
;     ...
;       LDA(At, 1, 1); BAR; WAIT_L(0); MMA(1, 0, At, B0); MMA(1, 1, At, B1); BAR; }
	s_waitcnt lgkmcnt(0)
	v_mfma_f32_16x16x32_bf16 v[22:25], v[178:181], v[86:89], v[58:61]
	v_mfma_f32_16x16x32_bf16 v[26:29], v[178:181], v[94:97], v[198:201]
	v_mfma_f32_16x16x32_bf16 v[18:21], v[34:37], v[86:89], v[194:197]
	v_mfma_f32_16x16x32_bf16 v[50:53], v[182:185], v[90:93], v[22:25]
	v_mfma_f32_16x16x32_bf16 v[22:25], v[34:37], v[94:97], v[54:57]
	v_mfma_f32_16x16x32_bf16 v[54:57], v[182:185], v[118:121], v[26:29]
	v_mfma_f32_16x16x32_bf16 v[26:29], v[34:37], v[150:153], v[214:217]
	v_mfma_f32_16x16x32_bf16 v[58:61], v[178:181], v[150:153], v[218:221]
	v_mfma_f32_16x16x32_bf16 v[34:37], v[34:37], v[186:189], v[130:133]
	v_mfma_f32_16x16x32_bf16 v[66:69], v[178:181], v[186:189], v[138:141]
	v_mfma_f32_16x16x32_bf16 v[18:21], v[174:177], v[90:93], v[18:21]
	v_mfma_f32_16x16x32_bf16 v[22:25], v[174:177], v[118:121], v[22:25]
	v_mfma_f32_16x16x32_bf16 v[26:29], v[174:177], v[154:157], v[26:29]
	v_mfma_f32_16x16x32_bf16 v[58:61], v[182:185], v[154:157], v[58:61]
	v_mfma_f32_16x16x32_bf16 v[34:37], v[174:177], v[190:193], v[34:37]
	v_mfma_f32_16x16x32_bf16 v[66:69], v[182:185], v[190:193], v[66:69]


; #define LDA(dst, b, h) for (int m = 0; m < 4; ++m) for (int k = 0; k < 2; ++k) \
;     dst[m][k] = *reinterpret_cast<const bf16x8*>((char*)SA(b, h) + a_thr + (m * 2 + k) * 1024)
; #define MMA(ai, bj, At, Btf) do { __builtin_amdgcn_s_setprio(1); \
;     for (int m = 0; m < 4; ++m) for (int n = 0; n < 2; ++n) for (int k = 0; k < 2; ++k) \
;       acc[ai][bj][m][n] = __builtin_amdgcn_mfma_f32_16x16x32_bf16(Btf[n][k], At[m][k], acc[ai][bj][m][n], 0, 0, 0); \
;     __builtin_amdgcn_s_setprio(0); } while (0)
; #define WAIT_L(n) asm volatile("s_waitcnt lgkmcnt(" #n ")" ::: "memory")
; #define BAR __builtin_amdgcn_s_barrier()
; template <bool OVL, bool PANEL = false, class Epi>
; __device__ __forceinline__ void gemm_phase(const bf16_t* __restrict__ A, long lda, const bf16_t* __restrict__ Bt, long ldb, int nM, int nN, int K,
;                                            const Epi& epi, bf16_t* shm, int w0) {
;     ...
;       LDA(At, 1, 1); BAR; WAIT_L(0); MMA(1, 0, At, B0); MMA(1, 1, At, B1); BAR; }
	v_mfma_f32_16x16x32_bf16 v[82:85], v[102:105], v[86:89], v[142:145]
	v_mfma_f32_16x16x32_bf16 v[86:89], v[240:243], v[86:89], v[146:149]
	v_mfma_f32_16x16x32_bf16 v[82:85], v[236:239], v[90:93], v[82:85]
	v_mfma_f32_16x16x32_bf16 v[122:125], v[244:247], v[90:93], v[86:89]
	v_mfma_f32_16x16x32_bf16 v[86:89], v[102:105], v[94:97], v[222:225]
	v_mfma_f32_16x16x32_bf16 v[90:93], v[240:243], v[94:97], v[158:161]
	v_mfma_f32_16x16x32_bf16 v[94:97], v[240:243], v[150:153], v[166:169]
	v_mfma_f32_16x16x32_bf16 v[86:89], v[236:239], v[118:121], v[86:89]
	v_mfma_f32_16x16x32_bf16 v[126:129], v[244:247], v[118:121], v[90:93]
	v_mfma_f32_16x16x32_bf16 v[118:121], v[244:247], v[154:157], v[94:97]
	v_mfma_f32_16x16x32_bf16 v[94:97], v[102:105], v[186:189], v[134:137]
	v_mfma_f32_16x16x32_bf16 v[90:93], v[102:105], v[150:153], v[162:165]
	v_mfma_f32_16x16x32_bf16 v[102:105], v[236:239], v[190:193], v[94:97]
	v_mfma_f32_16x16x32_bf16 v[94:97], v[240:243], v[186:189], v[170:173]
	v_mfma_f32_16x16x32_bf16 v[90:93], v[236:239], v[154:157], v[90:93]
	v_mfma_f32_16x16x32_bf16 v[94:97], v[244:247], v[190:193], v[94:97]

; #define LDA(dst, b, h) for (int m = 0; m < 4; ++m) for (int k = 0; k < 2; ++k) \
;     dst[m][k] = *reinterpret_cast<const bf16x8*>((char*)SA(b, h) + a_thr + (m * 2 + k) * 1024)
; #define MMA(ai, bj, At, Btf) do { __builtin_amdgcn_s_setprio(1); \
;     for (int m = 0; m < 4; ++m) for (int n = 0; n < 2; ++n) for (int k = 0; k < 2; ++k) \
;       acc[ai][bj][m][n] = __builtin_amdgcn_mfma_f32_16x16x32_bf16(Btf[n][k], At[m][k], acc[ai][bj][m][n], 0, 0, 0); \
;     __builtin_amdgcn_s_setprio(0); } while (0)
; #define WAIT_L(n) asm volatile("s_waitcnt lgkmcnt(" #n ")" ::: "memory")
; #define BAR __builtin_amdgcn_s_barrier()
; template <bool OVL, bool PANEL = false, class Epi>
; __device__ __forceinline__ void gemm_phase(const bf16_t* __restrict__ A, long lda, const bf16_t* __restrict__ Bt, long ldb, int nM, int nN, int K,
;                                            const Epi& epi, bf16_t* shm, int w0) {
;     ...
;       LDA(At, 1, 1); BAR; WAIT_L(0); MMA(1, 0, At, B0); MMA(1, 1, At, B1); BAR; }
;     if (wr == 0) BAR;
	s_barrier
	s_and_saveexec_b64 s[0:1], s[58:59]
	s_cbranch_execz .LBB0_128
	s_barrier

; #define LDA(dst, b, h) for (int m = 0; m < 4; ++m) for (int k = 0; k < 2; ++k) \
;     dst[m][k] = *reinterpret_cast<const bf16x8*>((char*)SA(b, h) + a_thr + (m * 2 + k) * 1024)
; #define LDB(dst, b, h) for (int n = 0; n < 2; ++n) for (int k = 0; k < 2; ++k) \
;     dst[n][k] = *reinterpret_cast<const bf16x8*>((char*)SB(b, h) + b_thr + (n * 2 + k) * 1024)
; #define MMA(ai, bj, At, Btf) do { __builtin_amdgcn_s_setprio(1); \
;     for (int m = 0; m < 4; ++m) for (int n = 0; n < 2; ++n) for (int k = 0; k < 2; ++k) \
;       acc[ai][bj][m][n] = __builtin_amdgcn_mfma_f32_16x16x32_bf16(Btf[n][k], At[m][k], acc[ai][bj][m][n], 0, 0, 0); \
;     __builtin_amdgcn_s_setprio(0); } while (0)
; #define WAIT_V(n) asm volatile("s_waitcnt vmcnt(" #n ")" ::: "memory")
; #define WAIT_L(n) asm volatile("s_waitcnt lgkmcnt(" #n ")" ::: "memory")
; #define BAR __builtin_amdgcn_s_barrier()
; #define SCHED __builtin_amdgcn_sched_barrier(0)
; template <bool OVL, bool PANEL = false, class Epi>
; __device__ __forceinline__ void gemm_phase(const bf16_t* __restrict__ A, long lda, const bf16_t* __restrict__ Bt, long ldb, int nM, int nN, int K,
;                                            const Epi& epi, bf16_t* shm, int w0) {
;     ...
;       LDB(B0, 0, 0); SCHED; LDA(At, 0, 0); STAGE(SA(1, 1), A, lda, aoff, brow + HALF, t + 1);
;       WAIT_L(8); BAR; WAIT_L(0); MMA(0, 0, At, B0); BAR; SCHED;
;       LDB(B1, 0, 1); STAGE(SB(0, 0), Bt, ldb, boff, bcol, t + 2);
;       BAR; WAIT_L(0); MMA(0, 1, At, B1); BAR;
;       LDA(At, 0, 1); STAGE(SA(0, 0), A, lda, aoff, brow, t + 2);
;       BAR; WAIT_L(0); MMA(1, 0, At, B0); BAR; SCHED;
;       STAGE(SB(0, 1), Bt, ldb, boff, bcol + HALF, t + 2);
;       WAIT_V(6); BAR; MMA(1, 1, At, B1); BAR;
.LBB0_386:
	ds_read_b128 v[150:153], v218
	ds_read_b128 v[154:157], v218 offset:1024
	ds_read_b128 v[158:161], v218 offset:2048
	ds_read_b128 v[162:165], v218 offset:3072
	s_add_u32 s42, s10, vcc_lo
	s_addc_u32 s43, s11, vcc_hi
	ds_read_b128 v[166:169], v141
	ds_read_b128 v[170:173], v141 offset:1024
	ds_read_b128 v[174:177], v141 offset:2048
	ds_read_b128 v[178:181], v141 offset:3072
	ds_read_b128 v[182:185], v141 offset:4096
	ds_read_b128 v[186:189], v141 offset:5120
	ds_read_b128 v[190:193], v141 offset:6144
	ds_read_b128 v[194:197], v141 offset:7168
	s_mov_b32 m0, s16
	s_add_u32 s98, s42, s28
	s_addc_u32 s99, s43, s29
	global_load_lds_dwordx4 v131, s[98:99]
	s_mov_b32 m0, s32
	s_add_u32 s98, s42, s36
	s_addc_u32 s99, s43, s37
	global_load_lds_dwordx4 v131, s[98:99]
	s_waitcnt lgkmcnt(8)
	s_waitcnt vmcnt(10)
	s_barrier
	s_waitcnt lgkmcnt(0)
	s_waitcnt lgkmcnt(0)
	v_mfma_f32_16x16x32_bf16 v[126:129], v[150:153], v[166:169], v[126:129]
	v_mfma_f32_16x16x32_bf16 v[122:125], v[158:161], v[166:169], v[122:125]
	v_mfma_f32_16x16x32_bf16 v[118:121], v[150:153], v[174:177], v[118:121]
	v_mfma_f32_16x16x32_bf16 v[114:117], v[158:161], v[174:177], v[114:117]
	v_mfma_f32_16x16x32_bf16 v[110:113], v[150:153], v[182:185], v[110:113]
	v_mfma_f32_16x16x32_bf16 v[106:109], v[158:161], v[182:185], v[106:109]
	v_mfma_f32_16x16x32_bf16 v[102:105], v[150:153], v[190:193], v[102:105]
	v_mfma_f32_16x16x32_bf16 v[98:101], v[158:161], v[190:193], v[98:101]
	v_mfma_f32_16x16x32_bf16 v[126:129], v[154:157], v[170:173], v[126:129]
	v_mfma_f32_16x16x32_bf16 v[122:125], v[162:165], v[170:173], v[122:125]
	v_mfma_f32_16x16x32_bf16 v[118:121], v[154:157], v[178:181], v[118:121]
	v_mfma_f32_16x16x32_bf16 v[114:117], v[162:165], v[178:181], v[114:117]
	v_mfma_f32_16x16x32_bf16 v[110:113], v[154:157], v[186:189], v[110:113]
	v_mfma_f32_16x16x32_bf16 v[106:109], v[162:165], v[186:189], v[106:109]
	v_mfma_f32_16x16x32_bf16 v[102:105], v[154:157], v[194:197], v[102:105]
	v_mfma_f32_16x16x32_bf16 v[98:101], v[162:165], v[194:197], v[98:101]
	s_barrier
	s_add_u32 s66, s8, vcc_lo
	ds_read_b128 v[198:201], v219
	ds_read_b128 v[202:205], v219 offset:1024
	ds_read_b128 v[206:209], v219 offset:2048
	ds_read_b128 v[210:213], v219 offset:3072
	s_addc_u32 s67, s9, vcc_hi
	s_mov_b32 m0, s46
	s_add_u32 s98, s66, s34
	s_addc_u32 s99, s67, s35
	global_load_lds_dwordx4 v131, s[98:99]
	s_mov_b32 m0, s47
	s_add_u32 s98, s66, s64
	s_addc_u32 s99, s67, s65
	global_load_lds_dwordx4 v131, s[98:99]
	s_waitcnt vmcnt(10)
	s_barrier
	s_waitcnt lgkmcnt(0)
	s_waitcnt lgkmcnt(0)
	v_mfma_f32_16x16x32_bf16 v[94:97], v[198:201], v[166:169], v[94:97]
	v_mfma_f32_16x16x32_bf16 v[90:93], v[206:209], v[166:169], v[90:93]
	v_mfma_f32_16x16x32_bf16 v[86:89], v[198:201], v[174:177], v[86:89]
	v_mfma_f32_16x16x32_bf16 v[82:85], v[206:209], v[174:177], v[82:85]
	v_mfma_f32_16x16x32_bf16 v[78:81], v[198:201], v[182:185], v[78:81]
	v_mfma_f32_16x16x32_bf16 v[74:77], v[206:209], v[182:185], v[74:77]
	v_mfma_f32_16x16x32_bf16 v[70:73], v[198:201], v[190:193], v[70:73]
	v_mfma_f32_16x16x32_bf16 v[66:69], v[206:209], v[190:193], v[66:69]
	v_mfma_f32_16x16x32_bf16 v[94:97], v[202:205], v[170:173], v[94:97]
	v_mfma_f32_16x16x32_bf16 v[90:93], v[210:213], v[170:173], v[90:93]
	v_mfma_f32_16x16x32_bf16 v[86:89], v[202:205], v[178:181], v[86:89]
	v_mfma_f32_16x16x32_bf16 v[82:85], v[210:213], v[178:181], v[82:85]
	v_mfma_f32_16x16x32_bf16 v[78:81], v[202:205], v[186:189], v[78:81]
	v_mfma_f32_16x16x32_bf16 v[74:77], v[210:213], v[186:189], v[74:77]
	v_mfma_f32_16x16x32_bf16 v[70:73], v[202:205], v[194:197], v[70:73]
	v_mfma_f32_16x16x32_bf16 v[66:69], v[210:213], v[194:197], v[66:69]
	s_barrier
	ds_read_b128 v[166:169], v141 offset:16384
	ds_read_b128 v[170:173], v141 offset:17408
	ds_read_b128 v[174:177], v141 offset:18432
	ds_read_b128 v[178:181], v141 offset:19456
	ds_read_b128 v[182:185], v141 offset:20480
	ds_read_b128 v[186:189], v141 offset:21504
	ds_read_b128 v[190:193], v141 offset:22528
	ds_read_b128 v[194:197], v141 offset:23552
	s_mov_b32 m0, s48
	s_add_u32 s98, s42, s34
	s_addc_u32 s99, s43, s35
	global_load_lds_dwordx4 v131, s[98:99]
	s_mov_b32 m0, s49
	s_add_u32 s98, s42, s64
	s_addc_u32 s99, s43, s65
	global_load_lds_dwordx4 v131, s[98:99]
	s_barrier
	s_waitcnt lgkmcnt(0)
	s_waitcnt lgkmcnt(0)
	v_mfma_f32_16x16x32_bf16 v[62:65], v[150:153], v[166:169], v[62:65]
	v_mfma_f32_16x16x32_bf16 v[58:61], v[158:161], v[166:169], v[58:61]
	v_mfma_f32_16x16x32_bf16 v[54:57], v[150:153], v[174:177], v[54:57]
	v_mfma_f32_16x16x32_bf16 v[50:53], v[158:161], v[174:177], v[50:53]
	v_mfma_f32_16x16x32_bf16 v[46:49], v[150:153], v[182:185], v[46:49]
	v_mfma_f32_16x16x32_bf16 v[42:45], v[158:161], v[182:185], v[42:45]
	v_mfma_f32_16x16x32_bf16 v[38:41], v[150:153], v[190:193], v[38:41]
	v_mfma_f32_16x16x32_bf16 v[34:37], v[158:161], v[190:193], v[34:37]
	v_mfma_f32_16x16x32_bf16 v[62:65], v[154:157], v[170:173], v[62:65]
	v_mfma_f32_16x16x32_bf16 v[58:61], v[162:165], v[170:173], v[58:61]
	v_mfma_f32_16x16x32_bf16 v[54:57], v[154:157], v[178:181], v[54:57]
	v_mfma_f32_16x16x32_bf16 v[50:53], v[162:165], v[178:181], v[50:53]
	v_mfma_f32_16x16x32_bf16 v[46:49], v[154:157], v[186:189], v[46:49]
	v_mfma_f32_16x16x32_bf16 v[42:45], v[162:165], v[186:189], v[42:45]
	v_mfma_f32_16x16x32_bf16 v[38:41], v[154:157], v[194:197], v[38:41]
	v_mfma_f32_16x16x32_bf16 v[34:37], v[162:165], v[194:197], v[34:37]
	s_barrier
	s_mov_b32 m0, s50
	s_add_u32 s98, s66, s68
	s_addc_u32 s99, s67, s69
	global_load_lds_dwordx4 v131, s[98:99]
	s_mov_b32 m0, s51
	s_add_u32 s98, s66, s70
	s_addc_u32 s99, s67, s71
	global_load_lds_dwordx4 v131, s[98:99]
	s_waitcnt vmcnt(10)
	s_barrier
; #define LDA(dst, b, h) for (int m = 0; m < 4; ++m) for (int k = 0; k < 2; ++k) \
;     dst[m][k] = *reinterpret_cast<const bf16x8*>((char*)SA(b, h) + a_thr + (m * 2 + k) * 1024)
; #define LDB(dst, b, h) for (int n = 0; n < 2; ++n) for (int k = 0; k < 2; ++k) \
;     dst[n][k] = *reinterpret_cast<const bf16x8*>((char*)SB(b, h) + b_thr + (n * 2 + k) * 1024)
; #define MMA(ai, bj, At, Btf) do { __builtin_amdgcn_s_setprio(1); \
;     for (int m = 0; m < 4; ++m) for (int n = 0; n < 2; ++n) for (int k = 0; k < 2; ++k) \
;       acc[ai][bj][m][n] = __builtin_amdgcn_mfma_f32_16x16x32_bf16(Btf[n][k], At[m][k], acc[ai][bj][m][n], 0, 0, 0); \
;     __builtin_amdgcn_s_setprio(0); } while (0)
; #define WAIT_V(n) asm volatile("s_waitcnt vmcnt(" #n ")" ::: "memory")
; #define WAIT_L(n) asm volatile("s_waitcnt lgkmcnt(" #n ")" ::: "memory")
; #define BAR __builtin_amdgcn_s_barrier()
; #define SCHED __builtin_amdgcn_sched_barrier(0)
; template <bool OVL, bool PANEL = false, class Epi>
; __device__ __forceinline__ void gemm_phase(const bf16_t* __restrict__ A, long lda, const bf16_t* __restrict__ Bt, long ldb, int nM, int nN, int K,
;                                            const Epi& epi, bf16_t* shm, int w0) {
;     ...
;       WAIT_V(6); BAR; MMA(1, 1, At, B1); BAR;
;       LDB(B0, 1, 0); SCHED; LDA(At, 1, 0); STAGE(SA(0, 1), A, lda, aoff, brow + HALF, t + 2);
;       WAIT_L(8); BAR; WAIT_L(0); MMA(0, 0, At, B0); BAR; SCHED;
;       LDB(B1, 1, 1); STAGE(SB(1, 0), Bt, ldb, boff, bcol, t + 3);
;       BAR; WAIT_L(0); MMA(0, 1, At, B1); BAR;
	v_mfma_f32_16x16x32_bf16 v[30:33], v[198:201], v[166:169], v[30:33]
	v_mfma_f32_16x16x32_bf16 v[26:29], v[206:209], v[166:169], v[26:29]
	v_mfma_f32_16x16x32_bf16 v[22:25], v[198:201], v[174:177], v[22:25]
	v_mfma_f32_16x16x32_bf16 v[18:21], v[206:209], v[174:177], v[18:21]
	v_mfma_f32_16x16x32_bf16 v[14:17], v[198:201], v[182:185], v[14:17]
	v_mfma_f32_16x16x32_bf16 v[10:13], v[206:209], v[182:185], v[10:13]
	v_mfma_f32_16x16x32_bf16 v[6:9], v[198:201], v[190:193], v[6:9]
	v_mfma_f32_16x16x32_bf16 v[2:5], v[206:209], v[190:193], v[2:5]
	v_mfma_f32_16x16x32_bf16 v[30:33], v[202:205], v[170:173], v[30:33]
	v_mfma_f32_16x16x32_bf16 v[26:29], v[210:213], v[170:173], v[26:29]
	v_mfma_f32_16x16x32_bf16 v[22:25], v[202:205], v[178:181], v[22:25]
	v_mfma_f32_16x16x32_bf16 v[18:21], v[210:213], v[178:181], v[18:21]
	v_mfma_f32_16x16x32_bf16 v[14:17], v[202:205], v[186:189], v[14:17]
	v_mfma_f32_16x16x32_bf16 v[10:13], v[210:213], v[186:189], v[10:13]
	v_mfma_f32_16x16x32_bf16 v[6:9], v[202:205], v[194:197], v[6:9]
	v_mfma_f32_16x16x32_bf16 v[2:5], v[210:213], v[194:197], v[2:5]
	s_barrier
	ds_read_b128 v[150:153], v220
	ds_read_b128 v[154:157], v220 offset:1024
	ds_read_b128 v[158:161], v220 offset:2048
	ds_read_b128 v[162:165], v220 offset:3072
	ds_read_b128 v[166:169], v141 offset:32768
	ds_read_b128 v[170:173], v141 offset:33792
	ds_read_b128 v[174:177], v141 offset:34816
	ds_read_b128 v[178:181], v141 offset:35840
	ds_read_b128 v[182:185], v141 offset:36864
	ds_read_b128 v[186:189], v141 offset:37888
	ds_read_b128 v[190:193], v141 offset:38912
	ds_read_b128 v[194:197], v141 offset:39936
	s_mov_b32 m0, s52
	s_add_u32 s98, s42, s68
	s_addc_u32 s99, s43, s69
	global_load_lds_dwordx4 v131, s[98:99]
	s_mov_b32 m0, s53
	s_add_u32 s98, s42, s70
	s_addc_u32 s99, s43, s71
	global_load_lds_dwordx4 v131, s[98:99]
	s_waitcnt lgkmcnt(8)
	s_waitcnt vmcnt(10)
	s_barrier
	s_waitcnt lgkmcnt(0)
	s_waitcnt lgkmcnt(0)
	v_mfma_f32_16x16x32_bf16 v[126:129], v[150:153], v[166:169], v[126:129]
	v_mfma_f32_16x16x32_bf16 v[122:125], v[158:161], v[166:169], v[122:125]
	v_mfma_f32_16x16x32_bf16 v[118:121], v[150:153], v[174:177], v[118:121]
	v_mfma_f32_16x16x32_bf16 v[114:117], v[158:161], v[174:177], v[114:117]
	v_mfma_f32_16x16x32_bf16 v[110:113], v[150:153], v[182:185], v[110:113]
	v_mfma_f32_16x16x32_bf16 v[106:109], v[158:161], v[182:185], v[106:109]
	v_mfma_f32_16x16x32_bf16 v[102:105], v[150:153], v[190:193], v[102:105]
	v_mfma_f32_16x16x32_bf16 v[98:101], v[158:161], v[190:193], v[98:101]
	v_mfma_f32_16x16x32_bf16 v[126:129], v[154:157], v[170:173], v[126:129]
	v_mfma_f32_16x16x32_bf16 v[122:125], v[162:165], v[170:173], v[122:125]
	v_mfma_f32_16x16x32_bf16 v[118:121], v[154:157], v[178:181], v[118:121]
	v_mfma_f32_16x16x32_bf16 v[114:117], v[162:165], v[178:181], v[114:117]
	v_mfma_f32_16x16x32_bf16 v[110:113], v[154:157], v[186:189], v[110:113]
	v_mfma_f32_16x16x32_bf16 v[106:109], v[162:165], v[186:189], v[106:109]
	v_mfma_f32_16x16x32_bf16 v[102:105], v[154:157], v[194:197], v[102:105]
	v_mfma_f32_16x16x32_bf16 v[98:101], v[162:165], v[194:197], v[98:101]
	s_barrier
	ds_read_b128 v[198:201], v221
	ds_read_b128 v[202:205], v221 offset:1024
	ds_read_b128 v[206:209], v221 offset:2048
	ds_read_b128 v[210:213], v221 offset:3072
	s_mov_b32 m0, s54
	s_add_u32 s98, s66, s94
	s_addc_u32 s99, s67, s95
	global_load_lds_dwordx4 v131, s[98:99]
	s_mov_b32 m0, s55
	s_add_u32 s98, s66, s72
	s_addc_u32 s99, s67, s73
	global_load_lds_dwordx4 v131, s[98:99]
	s_waitcnt vmcnt(10)
	s_barrier
	s_waitcnt lgkmcnt(0)
	s_waitcnt lgkmcnt(0)
	v_mfma_f32_16x16x32_bf16 v[94:97], v[198:201], v[166:169], v[94:97]
	v_mfma_f32_16x16x32_bf16 v[90:93], v[206:209], v[166:169], v[90:93]
	v_mfma_f32_16x16x32_bf16 v[86:89], v[198:201], v[174:177], v[86:89]
	v_mfma_f32_16x16x32_bf16 v[82:85], v[206:209], v[174:177], v[82:85]
	v_mfma_f32_16x16x32_bf16 v[78:81], v[198:201], v[182:185], v[78:81]
	v_mfma_f32_16x16x32_bf16 v[74:77], v[206:209], v[182:185], v[74:77]
	v_mfma_f32_16x16x32_bf16 v[70:73], v[198:201], v[190:193], v[70:73]
	v_mfma_f32_16x16x32_bf16 v[66:69], v[206:209], v[190:193], v[66:69]
	v_mfma_f32_16x16x32_bf16 v[94:97], v[202:205], v[170:173], v[94:97]
	v_mfma_f32_16x16x32_bf16 v[90:93], v[210:213], v[170:173], v[90:93]
	v_mfma_f32_16x16x32_bf16 v[86:89], v[202:205], v[178:181], v[86:89]
	v_mfma_f32_16x16x32_bf16 v[82:85], v[210:213], v[178:181], v[82:85]
	v_mfma_f32_16x16x32_bf16 v[78:81], v[202:205], v[186:189], v[78:81]
	v_mfma_f32_16x16x32_bf16 v[74:77], v[210:213], v[186:189], v[74:77]
	v_mfma_f32_16x16x32_bf16 v[70:73], v[202:205], v[194:197], v[70:73]
	v_mfma_f32_16x16x32_bf16 v[66:69], v[210:213], v[194:197], v[66:69]
	s_barrier
; #define LDA(dst, b, h) for (int m = 0; m < 4; ++m) for (int k = 0; k < 2; ++k) \
;     dst[m][k] = *reinterpret_cast<const bf16x8*>((char*)SA(b, h) + a_thr + (m * 2 + k) * 1024)
; #define LDB(dst, b, h) for (int n = 0; n < 2; ++n) for (int k = 0; k < 2; ++k) \
;     dst[n][k] = *reinterpret_cast<const bf16x8*>((char*)SB(b, h) + b_thr + (n * 2 + k) * 1024)
; #define MMA(ai, bj, At, Btf) do { __builtin_amdgcn_s_setprio(1); \
;     for (int m = 0; m < 4; ++m) for (int n = 0; n < 2; ++n) for (int k = 0; k < 2; ++k) \
;       acc[ai][bj][m][n] = __builtin_amdgcn_mfma_f32_16x16x32_bf16(Btf[n][k], At[m][k], acc[ai][bj][m][n], 0, 0, 0); \
;     __builtin_amdgcn_s_setprio(0); } while (0)
; #define WAIT_V(n) asm volatile("s_waitcnt vmcnt(" #n ")" ::: "memory")
; #define WAIT_L(n) asm volatile("s_waitcnt lgkmcnt(" #n ")" ::: "memory")
; #define BAR __builtin_amdgcn_s_barrier()
; #define SCHED __builtin_amdgcn_sched_barrier(0)
; template <bool OVL, bool PANEL = false, class Epi>
; __device__ __forceinline__ void gemm_phase(const bf16_t* __restrict__ A, long lda, const bf16_t* __restrict__ Bt, long ldb, int nM, int nN, int K,
;                                            const Epi& epi, bf16_t* shm, int w0) {
;     ...
;       LDA(At, 1, 1); STAGE(SA(1, 0), A, lda, aoff, brow, t + 3);
;       BAR; WAIT_L(0); MMA(1, 0, At, B0); BAR; SCHED;
;       STAGE(SB(1, 1), Bt, ldb, boff, bcol + HALF, t + 3);
;       WAIT_V(6); BAR; MMA(1, 1, At, B1); BAR;
;     }
;     { LDB(B0, 0, 0); LDA(At, 0, 0); STAGE(SA(1, 1), A, lda, aoff, brow + HALF, nt - 1);
	ds_read_b128 v[166:169], v141 offset:49152
	ds_read_b128 v[170:173], v141 offset:50176
	ds_read_b128 v[174:177], v141 offset:51200
	ds_read_b128 v[178:181], v141 offset:52224
	ds_read_b128 v[182:185], v141 offset:53248
	ds_read_b128 v[186:189], v141 offset:54272
	ds_read_b128 v[190:193], v141 offset:55296
	ds_read_b128 v[194:197], v141 offset:56320
	s_mov_b32 m0, s56
	s_add_u32 s98, s42, s94
	s_addc_u32 s99, s43, s95
	global_load_lds_dwordx4 v131, s[98:99]
	s_mov_b32 m0, s57
	s_add_u32 s98, s42, s72
	s_addc_u32 s99, s43, s73
	global_load_lds_dwordx4 v131, s[98:99]
	s_barrier
	s_waitcnt lgkmcnt(0)
	s_waitcnt lgkmcnt(0)
	v_mfma_f32_16x16x32_bf16 v[62:65], v[150:153], v[166:169], v[62:65]
	v_mfma_f32_16x16x32_bf16 v[58:61], v[158:161], v[166:169], v[58:61]
	v_mfma_f32_16x16x32_bf16 v[54:57], v[150:153], v[174:177], v[54:57]
	v_mfma_f32_16x16x32_bf16 v[50:53], v[158:161], v[174:177], v[50:53]
	v_mfma_f32_16x16x32_bf16 v[46:49], v[150:153], v[182:185], v[46:49]
	v_mfma_f32_16x16x32_bf16 v[42:45], v[158:161], v[182:185], v[42:45]
	v_mfma_f32_16x16x32_bf16 v[38:41], v[150:153], v[190:193], v[38:41]
	v_mfma_f32_16x16x32_bf16 v[34:37], v[158:161], v[190:193], v[34:37]
	v_mfma_f32_16x16x32_bf16 v[62:65], v[154:157], v[170:173], v[62:65]
	v_mfma_f32_16x16x32_bf16 v[58:61], v[162:165], v[170:173], v[58:61]
	v_mfma_f32_16x16x32_bf16 v[54:57], v[154:157], v[178:181], v[54:57]
	v_mfma_f32_16x16x32_bf16 v[50:53], v[162:165], v[178:181], v[50:53]
	v_mfma_f32_16x16x32_bf16 v[46:49], v[154:157], v[186:189], v[46:49]
	v_mfma_f32_16x16x32_bf16 v[42:45], v[162:165], v[186:189], v[42:45]
	v_mfma_f32_16x16x32_bf16 v[38:41], v[154:157], v[194:197], v[38:41]
	v_mfma_f32_16x16x32_bf16 v[34:37], v[162:165], v[194:197], v[34:37]
	s_barrier
	s_mov_b32 m0, s58
	s_add_u32 s98, s66, s30
	s_addc_u32 s99, s67, s31
	global_load_lds_dwordx4 v131, s[98:99]
	s_mov_b32 m0, s59
	s_add_u32 s98, s66, s44
	s_addc_u32 s99, s67, s45
	global_load_lds_dwordx4 v131, s[98:99]
	s_add_i32 s18, s18, 2
	s_add_u32 vcc_lo, vcc_lo, 0x100
	s_addc_u32 vcc_hi, vcc_hi, 0
	s_cmp_lt_u32 s18, 12
	s_waitcnt vmcnt(10)
	s_barrier
	v_mfma_f32_16x16x32_bf16 v[30:33], v[198:201], v[166:169], v[30:33]
	v_mfma_f32_16x16x32_bf16 v[26:29], v[206:209], v[166:169], v[26:29]
	v_mfma_f32_16x16x32_bf16 v[22:25], v[198:201], v[174:177], v[22:25]
	v_mfma_f32_16x16x32_bf16 v[18:21], v[206:209], v[174:177], v[18:21]
	v_mfma_f32_16x16x32_bf16 v[14:17], v[198:201], v[182:185], v[14:17]
	v_mfma_f32_16x16x32_bf16 v[10:13], v[206:209], v[182:185], v[10:13]
	v_mfma_f32_16x16x32_bf16 v[6:9], v[198:201], v[190:193], v[6:9]
	v_mfma_f32_16x16x32_bf16 v[2:5], v[206:209], v[190:193], v[2:5]
	v_mfma_f32_16x16x32_bf16 v[30:33], v[202:205], v[170:173], v[30:33]
	v_mfma_f32_16x16x32_bf16 v[26:29], v[210:213], v[170:173], v[26:29]
	v_mfma_f32_16x16x32_bf16 v[22:25], v[202:205], v[178:181], v[22:25]
	v_mfma_f32_16x16x32_bf16 v[18:21], v[210:213], v[178:181], v[18:21]
	v_mfma_f32_16x16x32_bf16 v[14:17], v[202:205], v[186:189], v[14:17]
	v_mfma_f32_16x16x32_bf16 v[10:13], v[210:213], v[186:189], v[10:13]
	v_mfma_f32_16x16x32_bf16 v[6:9], v[202:205], v[194:197], v[6:9]
	v_mfma_f32_16x16x32_bf16 v[2:5], v[210:213], v[194:197], v[2:5]
	s_barrier
	s_cbranch_scc1 .LBB0_386
	s_waitcnt vmcnt(6)
	s_or_b32 s8, s2, 0x80
	s_mov_b32 s9, s3
	v_readlane_b32 s44, v252, 20
	s_lshl_b64 s[8:9], s[8:9], 11
	v_readlane_b32 s50, v252, 26
	v_add_u32_e32 v214, 16, v140
	v_readlane_b32 s51, v252, 27
	s_add_u32 s8, s50, s8
	v_add_u32_e32 v0, 0x10000, v214
	s_addc_u32 s9, s51, s9
	ds_read_b128 v[142:145], v0
	ds_read_b128 v[150:153], v0 offset:1024
	ds_read_b128 v[154:157], v0 offset:2048
	ds_read_b128 v[158:161], v0 offset:3072
	ds_read_b128 v[162:165], v141
	ds_read_b128 v[166:169], v141 offset:1024
	ds_read_b128 v[170:173], v141 offset:2048
	ds_read_b128 v[174:177], v141 offset:3072
	ds_read_b128 v[178:181], v141 offset:4096
	ds_read_b128 v[182:185], v141 offset:5120
	ds_read_b128 v[186:189], v141 offset:6144
	ds_read_b128 v[190:193], v141 offset:7168
	v_mov_b32_e32 v0, v131
	v_readlane_b32 s45, v252, 21
	v_lshl_add_u64 v[146:147], s[8:9], 0, v[0:1]
	s_mov_b64 s[8:9], 0x780
	v_lshl_add_u64 v[194:195], v[146:147], 0, s[8:9]
	v_readfirstlane_b32 s8, v148
	s_mov_b32 m0, s8
	s_mov_b64 s[8:9], 0x20780
	v_lshl_add_u64 v[146:147], v[146:147], 0, s[8:9]
	v_readfirstlane_b32 s8, v149
	global_load_lds_dwordx4 v[194:195], off
	s_mov_b32 m0, s8
	v_readlane_b32 s46, v252, 22
	global_load_lds_dwordx4 v[146:147], off
	s_barrier
	s_waitcnt lgkmcnt(0)
	v_readlane_b32 s47, v252, 23
	v_readlane_b32 s48, v252, 24
	v_readlane_b32 s49, v252, 25
	v_readlane_b32 s52, v252, 28
	v_readlane_b32 s53, v252, 29
	v_readlane_b32 s54, v252, 30
	v_readlane_b32 s55, v252, 31
	v_readlane_b32 s56, v252, 32
	v_readlane_b32 s57, v252, 33
	v_readlane_b32 s58, v252, 34
	v_readlane_b32 s59, v252, 35

; #define LDA(dst, b, h) for (int m = 0; m < 4; ++m) for (int k = 0; k < 2; ++k) \
;     dst[m][k] = *reinterpret_cast<const bf16x8*>((char*)SA(b, h) + a_thr + (m * 2 + k) * 1024)
; #define LDB(dst, b, h) for (int n = 0; n < 2; ++n) for (int k = 0; k < 2; ++k) \
;     dst[n][k] = *reinterpret_cast<const bf16x8*>((char*)SB(b, h) + b_thr + (n * 2 + k) * 1024)
; #define MMA(ai, bj, At, Btf) do { __builtin_amdgcn_s_setprio(1); \
;     for (int m = 0; m < 4; ++m) for (int n = 0; n < 2; ++n) for (int k = 0; k < 2; ++k) \
;       acc[ai][bj][m][n] = __builtin_amdgcn_mfma_f32_16x16x32_bf16(Btf[n][k], At[m][k], acc[ai][bj][m][n], 0, 0, 0); \
;     __builtin_amdgcn_s_setprio(0); } while (0)
; #define WAIT_L(n) asm volatile("s_waitcnt lgkmcnt(" #n ")" ::: "memory")
; #define BAR __builtin_amdgcn_s_barrier()
; template <bool OVL, bool PANEL = false, class Epi>
; __device__ __forceinline__ void gemm_phase(const bf16_t* __restrict__ A, long lda, const bf16_t* __restrict__ Bt, long ldb, int nM, int nN, int K,
;                                            const Epi& epi, bf16_t* shm, int w0) {
;     ...
;     { LDB(B0, 0, 0); LDA(At, 0, 0); STAGE(SA(1, 1), A, lda, aoff, brow + HALF, nt - 1);
;       BAR; WAIT_L(0); MMA(0, 0, At, B0); BAR;
	s_waitcnt lgkmcnt(0)
	v_mfma_f32_16x16x32_bf16 v[126:129], v[142:145], v[162:165], v[126:129]
	v_mfma_f32_16x16x32_bf16 v[122:125], v[154:157], v[162:165], v[122:125]
	v_mfma_f32_16x16x32_bf16 v[118:121], v[142:145], v[170:173], v[118:121]
	v_mfma_f32_16x16x32_bf16 v[114:117], v[154:157], v[170:173], v[114:117]
	v_mfma_f32_16x16x32_bf16 v[110:113], v[142:145], v[178:181], v[110:113]
	v_mfma_f32_16x16x32_bf16 v[106:109], v[154:157], v[178:181], v[106:109]
	v_mfma_f32_16x16x32_bf16 v[98:101], v[154:157], v[186:189], v[98:101]
	v_mfma_f32_16x16x32_bf16 v[126:129], v[150:153], v[166:169], v[126:129]
	v_mfma_f32_16x16x32_bf16 v[122:125], v[158:161], v[166:169], v[122:125]
	v_mfma_f32_16x16x32_bf16 v[118:121], v[150:153], v[174:177], v[118:121]
	v_mfma_f32_16x16x32_bf16 v[114:117], v[158:161], v[174:177], v[114:117]
	v_mfma_f32_16x16x32_bf16 v[110:113], v[150:153], v[182:185], v[110:113]
	v_mfma_f32_16x16x32_bf16 v[106:109], v[158:161], v[182:185], v[106:109]
	v_mfma_f32_16x16x32_bf16 v[102:105], v[142:145], v[186:189], v[102:105]
	v_mfma_f32_16x16x32_bf16 v[98:101], v[158:161], v[190:193], v[98:101]
	v_mfma_f32_16x16x32_bf16 v[146:149], v[150:153], v[190:193], v[102:105]

; #define LDB(dst, b, h) for (int n = 0; n < 2; ++n) for (int k = 0; k < 2; ++k) \
;     dst[n][k] = *reinterpret_cast<const bf16x8*>((char*)SB(b, h) + b_thr + (n * 2 + k) * 1024)
; #define MMA(ai, bj, At, Btf) do { __builtin_amdgcn_s_setprio(1); \
;     for (int m = 0; m < 4; ++m) for (int n = 0; n < 2; ++n) for (int k = 0; k < 2; ++k) \
;       acc[ai][bj][m][n] = __builtin_amdgcn_mfma_f32_16x16x32_bf16(Btf[n][k], At[m][k], acc[ai][bj][m][n], 0, 0, 0); \
;     __builtin_amdgcn_s_setprio(0); } while (0)
; #define WAIT_L(n) asm volatile("s_waitcnt lgkmcnt(" #n ")" ::: "memory")
; #define BAR __builtin_amdgcn_s_barrier()
; template <bool OVL, bool PANEL = false, class Epi>
; __device__ __forceinline__ void gemm_phase(const bf16_t* __restrict__ A, long lda, const bf16_t* __restrict__ Bt, long ldb, int nM, int nN, int K,
;                                            const Epi& epi, bf16_t* shm, int w0) {
;     ...
;       LDB(B1, 0, 1); BAR; WAIT_L(0); MMA(0, 1, At, B1); BAR;
	v_add_u32_e32 v0, 0x14000, v214
	s_barrier
	s_nop 2
	ds_read_b128 v[102:105], v0
	ds_read_b128 v[194:197], v0 offset:1024
	ds_read_b128 v[198:201], v0 offset:2048
	ds_read_b128 v[202:205], v0 offset:3072
	s_barrier
	s_waitcnt lgkmcnt(0)

; #define LDB(dst, b, h) for (int n = 0; n < 2; ++n) for (int k = 0; k < 2; ++k) \
;     dst[n][k] = *reinterpret_cast<const bf16x8*>((char*)SB(b, h) + b_thr + (n * 2 + k) * 1024)
; #define MMA(ai, bj, At, Btf) do { __builtin_amdgcn_s_setprio(1); \
;     for (int m = 0; m < 4; ++m) for (int n = 0; n < 2; ++n) for (int k = 0; k < 2; ++k) \
;       acc[ai][bj][m][n] = __builtin_amdgcn_mfma_f32_16x16x32_bf16(Btf[n][k], At[m][k], acc[ai][bj][m][n], 0, 0, 0); \
;     __builtin_amdgcn_s_setprio(0); } while (0)
; #define WAIT_L(n) asm volatile("s_waitcnt lgkmcnt(" #n ")" ::: "memory")
; #define BAR __builtin_amdgcn_s_barrier()
; template <bool OVL, bool PANEL = false, class Epi>
; __device__ __forceinline__ void gemm_phase(const bf16_t* __restrict__ A, long lda, const bf16_t* __restrict__ Bt, long ldb, int nM, int nN, int K,
;                                            const Epi& epi, bf16_t* shm, int w0) {
;     ...
;       LDB(B1, 0, 1); BAR; WAIT_L(0); MMA(0, 1, At, B1); BAR;
	s_waitcnt lgkmcnt(0)
	v_mfma_f32_16x16x32_bf16 v[94:97], v[102:105], v[162:165], v[94:97]
	v_mfma_f32_16x16x32_bf16 v[86:89], v[102:105], v[170:173], v[86:89]
	v_mfma_f32_16x16x32_bf16 v[78:81], v[102:105], v[178:181], v[78:81]
	v_mfma_f32_16x16x32_bf16 v[74:77], v[198:201], v[178:181], v[74:77]
	v_mfma_f32_16x16x32_bf16 v[94:97], v[194:197], v[166:169], v[94:97]
	v_mfma_f32_16x16x32_bf16 v[90:93], v[198:201], v[162:165], v[90:93]
	v_mfma_f32_16x16x32_bf16 v[86:89], v[194:197], v[174:177], v[86:89]
	v_mfma_f32_16x16x32_bf16 v[82:85], v[198:201], v[170:173], v[82:85]
	v_mfma_f32_16x16x32_bf16 v[78:81], v[194:197], v[182:185], v[78:81]
	v_mfma_f32_16x16x32_bf16 v[74:77], v[202:205], v[182:185], v[74:77]
	v_mfma_f32_16x16x32_bf16 v[70:73], v[102:105], v[186:189], v[70:73]
	v_mfma_f32_16x16x32_bf16 v[66:69], v[198:201], v[186:189], v[66:69]
	v_mfma_f32_16x16x32_bf16 v[162:165], v[202:205], v[166:169], v[90:93]
	v_mfma_f32_16x16x32_bf16 v[166:169], v[202:205], v[174:177], v[82:85]
	v_mfma_f32_16x16x32_bf16 v[170:173], v[194:197], v[190:193], v[70:73]
	v_mfma_f32_16x16x32_bf16 v[174:177], v[202:205], v[190:193], v[66:69]

; #define LDA(dst, b, h) for (int m = 0; m < 4; ++m) for (int k = 0; k < 2; ++k) \
;     dst[m][k] = *reinterpret_cast<const bf16x8*>((char*)SA(b, h) + a_thr + (m * 2 + k) * 1024)
; #define MMA(ai, bj, At, Btf) do { __builtin_amdgcn_s_setprio(1); \
;     for (int m = 0; m < 4; ++m) for (int n = 0; n < 2; ++n) for (int k = 0; k < 2; ++k) \
;       acc[ai][bj][m][n] = __builtin_amdgcn_mfma_f32_16x16x32_bf16(Btf[n][k], At[m][k], acc[ai][bj][m][n], 0, 0, 0); \
;     __builtin_amdgcn_s_setprio(0); } while (0)
; #define WAIT_V(n) asm volatile("s_waitcnt vmcnt(" #n ")" ::: "memory")
; #define WAIT_L(n) asm volatile("s_waitcnt lgkmcnt(" #n ")" ::: "memory")
; #define BAR __builtin_amdgcn_s_barrier()
; template <bool OVL, bool PANEL = false, class Epi>
; __device__ __forceinline__ void gemm_phase(const bf16_t* __restrict__ A, long lda, const bf16_t* __restrict__ Bt, long ldb, int nM, int nN, int K,
;                                            const Epi& epi, bf16_t* shm, int w0) {
;     ...
;       LDA(At, 0, 1); WAIT_V(4); BAR; WAIT_L(0); MMA(1, 0, At, B0); MMA(1, 1, At, B1); BAR; }
	s_barrier
	s_nop 1
	ds_read_b128 v[66:69], v141 offset:16384
	ds_read_b128 v[70:73], v141 offset:17408
	ds_read_b128 v[82:85], v141 offset:18432
	ds_read_b128 v[90:93], v141 offset:19456
	ds_read_b128 v[178:181], v141 offset:20480
	ds_read_b128 v[182:185], v141 offset:21504
	ds_read_b128 v[186:189], v141 offset:22528
	ds_read_b128 v[190:193], v141 offset:23552
	s_waitcnt vmcnt(4)
	s_barrier
	s_waitcnt lgkmcnt(0)

; #define LDA(dst, b, h) for (int m = 0; m < 4; ++m) for (int k = 0; k < 2; ++k) \
;     dst[m][k] = *reinterpret_cast<const bf16x8*>((char*)SA(b, h) + a_thr + (m * 2 + k) * 1024)
; #define MMA(ai, bj, At, Btf) do { __builtin_amdgcn_s_setprio(1); \
;     for (int m = 0; m < 4; ++m) for (int n = 0; n < 2; ++n) for (int k = 0; k < 2; ++k) \
;       acc[ai][bj][m][n] = __builtin_amdgcn_mfma_f32_16x16x32_bf16(Btf[n][k], At[m][k], acc[ai][bj][m][n], 0, 0, 0); \
;     __builtin_amdgcn_s_setprio(0); } while (0)
; #define WAIT_V(n) asm volatile("s_waitcnt vmcnt(" #n ")" ::: "memory")
; #define WAIT_L(n) asm volatile("s_waitcnt lgkmcnt(" #n ")" ::: "memory")
; #define BAR __builtin_amdgcn_s_barrier()
; template <bool OVL, bool PANEL = false, class Epi>
; __device__ __forceinline__ void gemm_phase(const bf16_t* __restrict__ A, long lda, const bf16_t* __restrict__ Bt, long ldb, int nM, int nN, int K,
;                                            const Epi& epi, bf16_t* shm, int w0) {
;     ...
;       LDA(At, 0, 1); WAIT_V(4); BAR; WAIT_L(0); MMA(1, 0, At, B0); MMA(1, 1, At, B1); BAR; }
	s_waitcnt lgkmcnt(0)
	v_mfma_f32_16x16x32_bf16 v[62:65], v[142:145], v[66:69], v[62:65]
	v_mfma_f32_16x16x32_bf16 v[54:57], v[142:145], v[82:85], v[54:57]
	v_mfma_f32_16x16x32_bf16 v[46:49], v[142:145], v[178:181], v[46:49]
	v_mfma_f32_16x16x32_bf16 v[42:45], v[154:157], v[178:181], v[42:45]
	v_mfma_f32_16x16x32_bf16 v[38:41], v[142:145], v[186:189], v[38:41]
	v_mfma_f32_16x16x32_bf16 v[34:37], v[154:157], v[186:189], v[34:37]
	v_mfma_f32_16x16x32_bf16 v[62:65], v[150:153], v[70:73], v[62:65]
	v_mfma_f32_16x16x32_bf16 v[58:61], v[154:157], v[66:69], v[58:61]
	v_mfma_f32_16x16x32_bf16 v[54:57], v[150:153], v[90:93], v[54:57]
	v_mfma_f32_16x16x32_bf16 v[50:53], v[154:157], v[82:85], v[50:53]
	v_mfma_f32_16x16x32_bf16 v[46:49], v[150:153], v[182:185], v[46:49]
	v_mfma_f32_16x16x32_bf16 v[42:45], v[158:161], v[182:185], v[42:45]
	v_mfma_f32_16x16x32_bf16 v[38:41], v[150:153], v[190:193], v[38:41]
	v_mfma_f32_16x16x32_bf16 v[34:37], v[158:161], v[190:193], v[34:37]
	v_mfma_f32_16x16x32_bf16 v[206:209], v[158:161], v[70:73], v[58:61]
	v_mfma_f32_16x16x32_bf16 v[210:213], v[158:161], v[90:93], v[50:53]


; #define LDA(dst, b, h) for (int m = 0; m < 4; ++m) for (int k = 0; k < 2; ++k) \
;     dst[m][k] = *reinterpret_cast<const bf16x8*>((char*)SA(b, h) + a_thr + (m * 2 + k) * 1024)
; #define MMA(ai, bj, At, Btf) do { __builtin_amdgcn_s_setprio(1); \
;     for (int m = 0; m < 4; ++m) for (int n = 0; n < 2; ++n) for (int k = 0; k < 2; ++k) \
;       acc[ai][bj][m][n] = __builtin_amdgcn_mfma_f32_16x16x32_bf16(Btf[n][k], At[m][k], acc[ai][bj][m][n], 0, 0, 0); \
;     __builtin_amdgcn_s_setprio(0); } while (0)
; #define WAIT_V(n) asm volatile("s_waitcnt vmcnt(" #n ")" ::: "memory")
; #define WAIT_L(n) asm volatile("s_waitcnt lgkmcnt(" #n ")" ::: "memory")
; #define BAR __builtin_amdgcn_s_barrier()
; template <bool OVL, bool PANEL = false, class Epi>
; __device__ __forceinline__ void gemm_phase(const bf16_t* __restrict__ A, long lda, const bf16_t* __restrict__ Bt, long ldb, int nM, int nN, int K,
;                                            const Epi& epi, bf16_t* shm, int w0) {
;     ...
;       LDA(At, 0, 1); WAIT_V(4); BAR; WAIT_L(0); MMA(1, 0, At, B0); MMA(1, 1, At, B1); BAR; }
	v_mfma_f32_16x16x32_bf16 v[30:33], v[102:105], v[66:69], v[30:33]
	v_mfma_f32_16x16x32_bf16 v[26:29], v[198:201], v[66:69], v[26:29]
	v_mfma_f32_16x16x32_bf16 v[22:25], v[102:105], v[82:85], v[22:25]
	v_mfma_f32_16x16x32_bf16 v[18:21], v[198:201], v[82:85], v[18:21]
	v_mfma_f32_16x16x32_bf16 v[14:17], v[102:105], v[178:181], v[14:17]
	v_mfma_f32_16x16x32_bf16 v[10:13], v[198:201], v[178:181], v[10:13]
	v_mfma_f32_16x16x32_bf16 v[6:9], v[102:105], v[186:189], v[6:9]
	v_mfma_f32_16x16x32_bf16 v[2:5], v[198:201], v[186:189], v[2:5]
	v_mfma_f32_16x16x32_bf16 v[30:33], v[194:197], v[70:73], v[30:33]
	v_mfma_f32_16x16x32_bf16 v[26:29], v[202:205], v[70:73], v[26:29]
	v_mfma_f32_16x16x32_bf16 v[22:25], v[194:197], v[90:93], v[22:25]
	v_mfma_f32_16x16x32_bf16 v[18:21], v[202:205], v[90:93], v[18:21]
	v_mfma_f32_16x16x32_bf16 v[14:17], v[194:197], v[182:185], v[14:17]
	v_mfma_f32_16x16x32_bf16 v[10:13], v[202:205], v[182:185], v[10:13]
	v_mfma_f32_16x16x32_bf16 v[6:9], v[194:197], v[190:193], v[6:9]
	v_mfma_f32_16x16x32_bf16 v[2:5], v[202:205], v[190:193], v[2:5]

; #define LDA(dst, b, h) for (int m = 0; m < 4; ++m) for (int k = 0; k < 2; ++k) \
;     dst[m][k] = *reinterpret_cast<const bf16x8*>((char*)SA(b, h) + a_thr + (m * 2 + k) * 1024)
; #define LDB(dst, b, h) for (int n = 0; n < 2; ++n) for (int k = 0; k < 2; ++k) \
;     dst[n][k] = *reinterpret_cast<const bf16x8*>((char*)SB(b, h) + b_thr + (n * 2 + k) * 1024)
; #define MMA(ai, bj, At, Btf) do { __builtin_amdgcn_s_setprio(1); \
;     for (int m = 0; m < 4; ++m) for (int n = 0; n < 2; ++n) for (int k = 0; k < 2; ++k) \
;       acc[ai][bj][m][n] = __builtin_amdgcn_mfma_f32_16x16x32_bf16(Btf[n][k], At[m][k], acc[ai][bj][m][n], 0, 0, 0); \
;     __builtin_amdgcn_s_setprio(0); } while (0)
; #define WAIT_V(n) asm volatile("s_waitcnt vmcnt(" #n ")" ::: "memory")
; #define WAIT_L(n) asm volatile("s_waitcnt lgkmcnt(" #n ")" ::: "memory")
; #define BAR __builtin_amdgcn_s_barrier()
; template <bool OVL, bool PANEL = false, class Epi>
; __device__ __forceinline__ void gemm_phase(const bf16_t* __restrict__ A, long lda, const bf16_t* __restrict__ Bt, long ldb, int nM, int nN, int K,
;                                            const Epi& epi, bf16_t* shm, int w0) {
;     ...
;     { LDB(B0, 1, 0); LDA(At, 1, 0); WAIT_V(2); BAR; WAIT_L(0); MMA(0, 0, At, B0); BAR;
	v_add_u32_e32 v0, 0x18000, v214
	s_barrier
	ds_read_b128 v[142:145], v0
	ds_read_b128 v[150:153], v0 offset:1024
	ds_read_b128 v[154:157], v0 offset:2048
	ds_read_b128 v[158:161], v0 offset:3072
	ds_read_b128 v[50:53], v141 offset:32768
	ds_read_b128 v[58:61], v141 offset:33792
	ds_read_b128 v[66:69], v141 offset:34816
	ds_read_b128 v[70:73], v141 offset:35840
	ds_read_b128 v[178:181], v141 offset:36864
	ds_read_b128 v[182:185], v141 offset:37888
	ds_read_b128 v[186:189], v141 offset:38912
	ds_read_b128 v[190:193], v141 offset:39936
	s_waitcnt vmcnt(2)
	s_barrier
	s_waitcnt lgkmcnt(0)

; #define LDA(dst, b, h) for (int m = 0; m < 4; ++m) for (int k = 0; k < 2; ++k) \
;     dst[m][k] = *reinterpret_cast<const bf16x8*>((char*)SA(b, h) + a_thr + (m * 2 + k) * 1024)
; #define LDB(dst, b, h) for (int n = 0; n < 2; ++n) for (int k = 0; k < 2; ++k) \
;     dst[n][k] = *reinterpret_cast<const bf16x8*>((char*)SB(b, h) + b_thr + (n * 2 + k) * 1024)
; #define MMA(ai, bj, At, Btf) do { __builtin_amdgcn_s_setprio(1); \
;     for (int m = 0; m < 4; ++m) for (int n = 0; n < 2; ++n) for (int k = 0; k < 2; ++k) \
;       acc[ai][bj][m][n] = __builtin_amdgcn_mfma_f32_16x16x32_bf16(Btf[n][k], At[m][k], acc[ai][bj][m][n], 0, 0, 0); \
;     __builtin_amdgcn_s_setprio(0); } while (0)
; #define WAIT_V(n) asm volatile("s_waitcnt vmcnt(" #n ")" ::: "memory")
; #define WAIT_L(n) asm volatile("s_waitcnt lgkmcnt(" #n ")" ::: "memory")
; #define BAR __builtin_amdgcn_s_barrier()
; template <bool OVL, bool PANEL = false, class Epi>
; __device__ __forceinline__ void gemm_phase(const bf16_t* __restrict__ A, long lda, const bf16_t* __restrict__ Bt, long ldb, int nM, int nN, int K,
;                                            const Epi& epi, bf16_t* shm, int w0) {
;     ...
;     { LDB(B0, 1, 0); LDA(At, 1, 0); WAIT_V(2); BAR; WAIT_L(0); MMA(0, 0, At, B0); BAR;
	s_waitcnt lgkmcnt(0)
	v_mfma_f32_16x16x32_bf16 v[82:85], v[142:145], v[50:53], v[126:129]
	v_mfma_f32_16x16x32_bf16 v[126:129], v[150:153], v[58:61], v[82:85]
	v_mfma_f32_16x16x32_bf16 v[82:85], v[154:157], v[50:53], v[122:125]
	v_mfma_f32_16x16x32_bf16 v[122:125], v[158:161], v[58:61], v[82:85]
	v_mfma_f32_16x16x32_bf16 v[82:85], v[142:145], v[66:69], v[118:121]
	v_mfma_f32_16x16x32_bf16 v[118:121], v[150:153], v[70:73], v[82:85]
	v_mfma_f32_16x16x32_bf16 v[82:85], v[154:157], v[66:69], v[114:117]
	v_mfma_f32_16x16x32_bf16 v[114:117], v[158:161], v[70:73], v[82:85]
	v_mfma_f32_16x16x32_bf16 v[82:85], v[142:145], v[178:181], v[110:113]
	v_mfma_f32_16x16x32_bf16 v[110:113], v[150:153], v[182:185], v[82:85]
	v_mfma_f32_16x16x32_bf16 v[82:85], v[154:157], v[178:181], v[106:109]
	v_mfma_f32_16x16x32_bf16 v[102:105], v[158:161], v[182:185], v[82:85]
	v_mfma_f32_16x16x32_bf16 v[82:85], v[142:145], v[186:189], v[146:149]
	v_mfma_f32_16x16x32_bf16 v[90:93], v[150:153], v[190:193], v[82:85]
	v_mfma_f32_16x16x32_bf16 v[82:85], v[154:157], v[186:189], v[98:101]
	v_mfma_f32_16x16x32_bf16 v[82:85], v[158:161], v[190:193], v[82:85]

; #define LDB(dst, b, h) for (int n = 0; n < 2; ++n) for (int k = 0; k < 2; ++k) \
;     dst[n][k] = *reinterpret_cast<const bf16x8*>((char*)SB(b, h) + b_thr + (n * 2 + k) * 1024)
; #define MMA(ai, bj, At, Btf) do { __builtin_amdgcn_s_setprio(1); \
;     for (int m = 0; m < 4; ++m) for (int n = 0; n < 2; ++n) for (int k = 0; k < 2; ++k) \
;       acc[ai][bj][m][n] = __builtin_amdgcn_mfma_f32_16x16x32_bf16(Btf[n][k], At[m][k], acc[ai][bj][m][n], 0, 0, 0); \
;     __builtin_amdgcn_s_setprio(0); } while (0)
; #define WAIT_V(n) asm volatile("s_waitcnt vmcnt(" #n ")" ::: "memory")
; #define WAIT_L(n) asm volatile("s_waitcnt lgkmcnt(" #n ")" ::: "memory")
; #define BAR __builtin_amdgcn_s_barrier()
; template <bool OVL, bool PANEL = false, class Epi>
; __device__ __forceinline__ void gemm_phase(const bf16_t* __restrict__ A, long lda, const bf16_t* __restrict__ Bt, long ldb, int nM, int nN, int K,
;                                            const Epi& epi, bf16_t* shm, int w0) {
;     ...
;       LDB(B1, 1, 1); WAIT_V(0); BAR; WAIT_L(0); MMA(0, 1, At, B1); BAR;
	v_add_u32_e32 v0, 0x1c000, v214
	s_barrier
	ds_read_b128 v[146:149], v0
	ds_read_b128 v[194:197], v0 offset:1024
	ds_read_b128 v[198:201], v0 offset:2048
	ds_read_b128 v[202:205], v0 offset:3072
	s_waitcnt vmcnt(0)
	s_barrier
	s_waitcnt lgkmcnt(0)

; #define LDB(dst, b, h) for (int n = 0; n < 2; ++n) for (int k = 0; k < 2; ++k) \
;     dst[n][k] = *reinterpret_cast<const bf16x8*>((char*)SB(b, h) + b_thr + (n * 2 + k) * 1024)
; #define MMA(ai, bj, At, Btf) do { __builtin_amdgcn_s_setprio(1); \
;     for (int m = 0; m < 4; ++m) for (int n = 0; n < 2; ++n) for (int k = 0; k < 2; ++k) \
;       acc[ai][bj][m][n] = __builtin_amdgcn_mfma_f32_16x16x32_bf16(Btf[n][k], At[m][k], acc[ai][bj][m][n], 0, 0, 0); \
;     __builtin_amdgcn_s_setprio(0); } while (0)
; #define WAIT_V(n) asm volatile("s_waitcnt vmcnt(" #n ")" ::: "memory")
; #define WAIT_L(n) asm volatile("s_waitcnt lgkmcnt(" #n ")" ::: "memory")
; #define BAR __builtin_amdgcn_s_barrier()
; template <bool OVL, bool PANEL = false, class Epi>
; __device__ __forceinline__ void gemm_phase(const bf16_t* __restrict__ A, long lda, const bf16_t* __restrict__ Bt, long ldb, int nM, int nN, int K,
;                                            const Epi& epi, bf16_t* shm, int w0) {
;     ...
;       LDB(B1, 1, 1); WAIT_V(0); BAR; WAIT_L(0); MMA(0, 1, At, B1); BAR;
	s_waitcnt lgkmcnt(0)
	v_mfma_f32_16x16x32_bf16 v[94:97], v[146:149], v[50:53], v[94:97]
	v_mfma_f32_16x16x32_bf16 v[50:53], v[198:201], v[50:53], v[162:165]
	v_mfma_f32_16x16x32_bf16 v[98:101], v[202:205], v[58:61], v[50:53]
	v_mfma_f32_16x16x32_bf16 v[50:53], v[146:149], v[66:69], v[86:89]
	v_mfma_f32_16x16x32_bf16 v[106:109], v[194:197], v[58:61], v[94:97]
	v_mfma_f32_16x16x32_bf16 v[94:97], v[194:197], v[70:73], v[50:53]
	v_mfma_f32_16x16x32_bf16 v[50:53], v[198:201], v[66:69], v[166:169]
	v_mfma_f32_16x16x32_bf16 v[86:89], v[202:205], v[70:73], v[50:53]
	v_mfma_f32_16x16x32_bf16 v[50:53], v[146:149], v[178:181], v[78:81]
	v_mfma_f32_16x16x32_bf16 v[70:73], v[194:197], v[182:185], v[50:53]
	v_mfma_f32_16x16x32_bf16 v[50:53], v[198:201], v[178:181], v[74:77]
	v_mfma_f32_16x16x32_bf16 v[66:69], v[202:205], v[182:185], v[50:53]
	v_mfma_f32_16x16x32_bf16 v[50:53], v[146:149], v[186:189], v[170:173]
	v_mfma_f32_16x16x32_bf16 v[58:61], v[194:197], v[190:193], v[50:53]
	v_mfma_f32_16x16x32_bf16 v[50:53], v[198:201], v[186:189], v[174:177]
	v_mfma_f32_16x16x32_bf16 v[50:53], v[202:205], v[190:193], v[50:53]

; #define LDA(dst, b, h) for (int m = 0; m < 4; ++m) for (int k = 0; k < 2; ++k) \
;     dst[m][k] = *reinterpret_cast<const bf16x8*>((char*)SA(b, h) + a_thr + (m * 2 + k) * 1024)
; #define MMA(ai, bj, At, Btf) do { __builtin_amdgcn_s_setprio(1); \
;     for (int m = 0; m < 4; ++m) for (int n = 0; n < 2; ++n) for (int k = 0; k < 2; ++k) \
;       acc[ai][bj][m][n] = __builtin_amdgcn_mfma_f32_16x16x32_bf16(Btf[n][k], At[m][k], acc[ai][bj][m][n], 0, 0, 0); \
;     __builtin_amdgcn_s_setprio(0); } while (0)
; #define WAIT_L(n) asm volatile("s_waitcnt lgkmcnt(" #n ")" ::: "memory")
; #define BAR __builtin_amdgcn_s_barrier()
; template <bool OVL, bool PANEL = false, class Epi>
; __device__ __forceinline__ void gemm_phase(const bf16_t* __restrict__ A, long lda, const bf16_t* __restrict__ Bt, long ldb, int nM, int nN, int K,
;                                            const Epi& epi, bf16_t* shm, int w0) {
;     ...
;       LDA(At, 1, 1); BAR; WAIT_L(0); MMA(1, 0, At, B0); MMA(1, 1, At, B1); BAR; }
	s_barrier
	ds_read_b128 v[162:165], v141 offset:49152
	ds_read_b128 v[166:169], v141 offset:50176
	ds_read_b128 v[170:173], v141 offset:51200
	ds_read_b128 v[174:177], v141 offset:52224
	ds_read_b128 v[178:181], v141 offset:53248
	ds_read_b128 v[182:185], v141 offset:54272
	ds_read_b128 v[186:189], v141 offset:55296
	ds_read_b128 v[190:193], v141 offset:56320
	s_barrier
	s_waitcnt lgkmcnt(0)

; #define LDA(dst, b, h) for (int m = 0; m < 4; ++m) for (int k = 0; k < 2; ++k) \
;     dst[m][k] = *reinterpret_cast<const bf16x8*>((char*)SA(b, h) + a_thr + (m * 2 + k) * 1024)
; #define MMA(ai, bj, At, Btf) do { __builtin_amdgcn_s_setprio(1); \
;     for (int m = 0; m < 4; ++m) for (int n = 0; n < 2; ++n) for (int k = 0; k < 2; ++k) \
;       acc[ai][bj][m][n] = __builtin_amdgcn_mfma_f32_16x16x32_bf16(Btf[n][k], At[m][k], acc[ai][bj][m][n], 0, 0, 0); \
;     __builtin_amdgcn_s_setprio(0); } while (0)
; #define WAIT_L(n) asm volatile("s_waitcnt lgkmcnt(" #n ")" ::: "memory")
; #define BAR __builtin_amdgcn_s_barrier()
; template <bool OVL, bool PANEL = false, class Epi>
; __device__ __forceinline__ void gemm_phase(const bf16_t* __restrict__ A, long lda, const bf16_t* __restrict__ Bt, long ldb, int nM, int nN, int K,
;                                            const Epi& epi, bf16_t* shm, int w0) {
;     ...
;       LDA(At, 1, 1); BAR; WAIT_L(0); MMA(1, 0, At, B0); MMA(1, 1, At, B1); BAR; }
	s_waitcnt lgkmcnt(0)
	v_mfma_f32_16x16x32_bf16 v[62:65], v[142:145], v[162:165], v[62:65]
	v_mfma_f32_16x16x32_bf16 v[78:81], v[150:153], v[166:169], v[62:65]
	v_mfma_f32_16x16x32_bf16 v[62:65], v[154:157], v[162:165], v[206:209]
	v_mfma_f32_16x16x32_bf16 v[54:57], v[142:145], v[170:173], v[54:57]
	v_mfma_f32_16x16x32_bf16 v[74:77], v[158:161], v[166:169], v[62:65]
	v_mfma_f32_16x16x32_bf16 v[62:65], v[150:153], v[174:177], v[54:57]
	v_mfma_f32_16x16x32_bf16 v[54:57], v[154:157], v[170:173], v[210:213]
	v_mfma_f32_16x16x32_bf16 v[46:49], v[142:145], v[178:181], v[46:49]
	v_mfma_f32_16x16x32_bf16 v[42:45], v[154:157], v[178:181], v[42:45]
	v_mfma_f32_16x16x32_bf16 v[38:41], v[142:145], v[186:189], v[38:41]
	v_mfma_f32_16x16x32_bf16 v[34:37], v[154:157], v[186:189], v[34:37]
	v_mfma_f32_16x16x32_bf16 v[54:57], v[158:161], v[174:177], v[54:57]
	v_mfma_f32_16x16x32_bf16 v[46:49], v[150:153], v[182:185], v[46:49]
	v_mfma_f32_16x16x32_bf16 v[42:45], v[158:161], v[182:185], v[42:45]
	v_mfma_f32_16x16x32_bf16 v[38:41], v[150:153], v[190:193], v[38:41]
	v_mfma_f32_16x16x32_bf16 v[34:37], v[158:161], v[190:193], v[34:37]


; #define LDA(dst, b, h) for (int m = 0; m < 4; ++m) for (int k = 0; k < 2; ++k) \
;     dst[m][k] = *reinterpret_cast<const bf16x8*>((char*)SA(b, h) + a_thr + (m * 2 + k) * 1024)
; #define MMA(ai, bj, At, Btf) do { __builtin_amdgcn_s_setprio(1); \
;     for (int m = 0; m < 4; ++m) for (int n = 0; n < 2; ++n) for (int k = 0; k < 2; ++k) \
;       acc[ai][bj][m][n] = __builtin_amdgcn_mfma_f32_16x16x32_bf16(Btf[n][k], At[m][k], acc[ai][bj][m][n], 0, 0, 0); \
;     __builtin_amdgcn_s_setprio(0); } while (0)
; #define WAIT_L(n) asm volatile("s_waitcnt lgkmcnt(" #n ")" ::: "memory")
; #define BAR __builtin_amdgcn_s_barrier()
; template <bool OVL, bool PANEL = false, class Epi>
; __device__ __forceinline__ void gemm_phase(const bf16_t* __restrict__ A, long lda, const bf16_t* __restrict__ Bt, long ldb, int nM, int nN, int K,
;                                            const Epi& epi, bf16_t* shm, int w0) {
;     ...
;       LDA(At, 1, 1); BAR; WAIT_L(0); MMA(1, 0, At, B0); MMA(1, 1, At, B1); BAR; }
	v_mfma_f32_16x16x32_bf16 v[30:33], v[146:149], v[162:165], v[30:33]
	v_mfma_f32_16x16x32_bf16 v[26:29], v[198:201], v[162:165], v[26:29]
	v_mfma_f32_16x16x32_bf16 v[22:25], v[146:149], v[170:173], v[22:25]
	v_mfma_f32_16x16x32_bf16 v[18:21], v[198:201], v[170:173], v[18:21]
	v_mfma_f32_16x16x32_bf16 v[14:17], v[146:149], v[178:181], v[14:17]
	v_mfma_f32_16x16x32_bf16 v[10:13], v[198:201], v[178:181], v[10:13]
	v_mfma_f32_16x16x32_bf16 v[6:9], v[146:149], v[186:189], v[6:9]
	v_mfma_f32_16x16x32_bf16 v[2:5], v[198:201], v[186:189], v[2:5]
	v_mfma_f32_16x16x32_bf16 v[30:33], v[194:197], v[166:169], v[30:33]
	v_mfma_f32_16x16x32_bf16 v[26:29], v[202:205], v[166:169], v[26:29]
	v_mfma_f32_16x16x32_bf16 v[22:25], v[194:197], v[174:177], v[22:25]
	v_mfma_f32_16x16x32_bf16 v[18:21], v[202:205], v[174:177], v[18:21]
	v_mfma_f32_16x16x32_bf16 v[14:17], v[194:197], v[182:185], v[14:17]
	v_mfma_f32_16x16x32_bf16 v[10:13], v[202:205], v[182:185], v[10:13]
	v_mfma_f32_16x16x32_bf16 v[6:9], v[194:197], v[190:193], v[6:9]
	v_mfma_f32_16x16x32_bf16 v[2:5], v[202:205], v[190:193], v[2:5]

; #define LDA(dst, b, h) for (int m = 0; m < 4; ++m) for (int k = 0; k < 2; ++k) \
;     dst[m][k] = *reinterpret_cast<const bf16x8*>((char*)SA(b, h) + a_thr + (m * 2 + k) * 1024)
; #define MMA(ai, bj, At, Btf) do { __builtin_amdgcn_s_setprio(1); \
;     for (int m = 0; m < 4; ++m) for (int n = 0; n < 2; ++n) for (int k = 0; k < 2; ++k) \
;       acc[ai][bj][m][n] = __builtin_amdgcn_mfma_f32_16x16x32_bf16(Btf[n][k], At[m][k], acc[ai][bj][m][n], 0, 0, 0); \
;     __builtin_amdgcn_s_setprio(0); } while (0)
; #define WAIT_L(n) asm volatile("s_waitcnt lgkmcnt(" #n ")" ::: "memory")
; #define BAR __builtin_amdgcn_s_barrier()
; template <bool OVL, bool PANEL = false, class Epi>
; __device__ __forceinline__ void gemm_phase(const bf16_t* __restrict__ A, long lda, const bf16_t* __restrict__ Bt, long ldb, int nM, int nN, int K,
;                                            const Epi& epi, bf16_t* shm, int w0) {
;     ...
;       LDA(At, 1, 1); BAR; WAIT_L(0); MMA(1, 0, At, B0); MMA(1, 1, At, B1); BAR; }
;     if (wr == 0) BAR;
	s_barrier
	s_and_saveexec_b64 s[8:9], s[78:79]
	s_cbranch_execz .LBB0_389
	s_barrier

; #define LDA(dst, b, h) for (int m = 0; m < 4; ++m) for (int k = 0; k < 2; ++k) \
;     dst[m][k] = *reinterpret_cast<const bf16x8*>((char*)SA(b, h) + a_thr + (m * 2 + k) * 1024)
; #define LDB(dst, b, h) for (int n = 0; n < 2; ++n) for (int k = 0; k < 2; ++k) \
;     dst[n][k] = *reinterpret_cast<const bf16x8*>((char*)SB(b, h) + b_thr + (n * 2 + k) * 1024)
; #define MMA(ai, bj, At, Btf) do { __builtin_amdgcn_s_setprio(1); \
;     for (int m = 0; m < 4; ++m) for (int n = 0; n < 2; ++n) for (int k = 0; k < 2; ++k) \
;       acc[ai][bj][m][n] = __builtin_amdgcn_mfma_f32_16x16x32_bf16(Btf[n][k], At[m][k], acc[ai][bj][m][n], 0, 0, 0); \
;     __builtin_amdgcn_s_setprio(0); } while (0)
; #define WAIT_V(n) asm volatile("s_waitcnt vmcnt(" #n ")" ::: "memory")
; #define WAIT_L(n) asm volatile("s_waitcnt lgkmcnt(" #n ")" ::: "memory")
; #define BAR __builtin_amdgcn_s_barrier()
; #define SCHED __builtin_amdgcn_sched_barrier(0)
; template <bool OVL, bool PANEL = false, class Epi>
; __device__ __forceinline__ void gemm_phase(const bf16_t* __restrict__ A, long lda, const bf16_t* __restrict__ Bt, long ldb, int nM, int nN, int K,
;                                            const Epi& epi, bf16_t* shm, int w0) {
;     ...
;       LDB(B0, 0, 0); SCHED; LDA(At, 0, 0); STAGE(SA(1, 1), A, lda, aoff, brow + HALF, t + 1);
;       WAIT_L(8); BAR; WAIT_L(0); MMA(0, 0, At, B0); BAR; SCHED;
;       LDB(B1, 0, 1); STAGE(SB(0, 0), Bt, ldb, boff, bcol, t + 2);
;       BAR; WAIT_L(0); MMA(0, 1, At, B1); BAR;
;       LDA(At, 0, 1); STAGE(SA(0, 0), A, lda, aoff, brow, t + 2);
;       BAR; WAIT_L(0); MMA(1, 0, At, B0); BAR; SCHED;
;       STAGE(SB(0, 1), Bt, ldb, boff, bcol + HALF, t + 2);
;       WAIT_V(6); BAR; MMA(1, 1, At, B1); BAR;
.LBB0_410:
	ds_read_b128 v[152:155], v220
	ds_read_b128 v[156:159], v220 offset:1024
	ds_read_b128 v[160:163], v220 offset:2048
	ds_read_b128 v[164:167], v220 offset:3072
	s_add_u32 s12, s8, s10
	s_addc_u32 s13, s9, s11
	ds_read_b128 v[168:171], v143
	ds_read_b128 v[172:175], v143 offset:1024
	ds_read_b128 v[176:179], v143 offset:2048
	ds_read_b128 v[180:183], v143 offset:3072
	ds_read_b128 v[184:187], v143 offset:4096
	ds_read_b128 v[188:191], v143 offset:5120
	ds_read_b128 v[192:195], v143 offset:6144
	ds_read_b128 v[196:199], v143 offset:7168
	s_mov_b32 m0, s16
	s_add_u32 s98, s12, s24
	s_addc_u32 s99, s13, s25
	global_load_lds_dwordx4 v131, s[98:99]
	s_mov_b32 m0, s23
	s_add_u32 s98, s12, s36
	s_addc_u32 s99, s13, s37
	global_load_lds_dwordx4 v131, s[98:99]
	s_waitcnt lgkmcnt(8)
	s_waitcnt vmcnt(10)
	s_barrier
	s_waitcnt lgkmcnt(0)
	s_waitcnt lgkmcnt(0)
	v_mfma_f32_16x16x32_bf16 v[126:129], v[152:155], v[168:171], v[126:129]
	v_mfma_f32_16x16x32_bf16 v[122:125], v[160:163], v[168:171], v[122:125]
	v_mfma_f32_16x16x32_bf16 v[118:121], v[152:155], v[176:179], v[118:121]
	v_mfma_f32_16x16x32_bf16 v[114:117], v[160:163], v[176:179], v[114:117]
	v_mfma_f32_16x16x32_bf16 v[110:113], v[152:155], v[184:187], v[110:113]
	v_mfma_f32_16x16x32_bf16 v[106:109], v[160:163], v[184:187], v[106:109]
	v_mfma_f32_16x16x32_bf16 v[102:105], v[152:155], v[192:195], v[102:105]
	v_mfma_f32_16x16x32_bf16 v[98:101], v[160:163], v[192:195], v[98:101]
	v_mfma_f32_16x16x32_bf16 v[126:129], v[156:159], v[172:175], v[126:129]
	v_mfma_f32_16x16x32_bf16 v[122:125], v[164:167], v[172:175], v[122:125]
	v_mfma_f32_16x16x32_bf16 v[118:121], v[156:159], v[180:183], v[118:121]
	v_mfma_f32_16x16x32_bf16 v[114:117], v[164:167], v[180:183], v[114:117]
	v_mfma_f32_16x16x32_bf16 v[110:113], v[156:159], v[188:191], v[110:113]
	v_mfma_f32_16x16x32_bf16 v[106:109], v[164:167], v[188:191], v[106:109]
	v_mfma_f32_16x16x32_bf16 v[102:105], v[156:159], v[196:199], v[102:105]
	v_mfma_f32_16x16x32_bf16 v[98:101], v[164:167], v[196:199], v[98:101]
	s_barrier
	s_add_u32 s14, s0, s10
	ds_read_b128 v[200:203], v221
	ds_read_b128 v[204:207], v221 offset:1024
	ds_read_b128 v[208:211], v221 offset:2048
	ds_read_b128 v[212:215], v221 offset:3072
	s_addc_u32 s15, s1, s11
	s_mov_b32 m0, s30
	s_add_u32 s98, s14, s34
	s_addc_u32 s99, s15, s35
	global_load_lds_dwordx4 v131, s[98:99]
	s_mov_b32 m0, s31
	s_add_u32 s98, s14, s64
	s_addc_u32 s99, s15, s65
	global_load_lds_dwordx4 v131, s[98:99]
	s_waitcnt vmcnt(10)
	s_barrier
	s_waitcnt lgkmcnt(0)
	s_waitcnt lgkmcnt(0)
	v_mfma_f32_16x16x32_bf16 v[94:97], v[200:203], v[168:171], v[94:97]
	v_mfma_f32_16x16x32_bf16 v[90:93], v[208:211], v[168:171], v[90:93]
	v_mfma_f32_16x16x32_bf16 v[86:89], v[200:203], v[176:179], v[86:89]
	v_mfma_f32_16x16x32_bf16 v[82:85], v[208:211], v[176:179], v[82:85]
	v_mfma_f32_16x16x32_bf16 v[78:81], v[200:203], v[184:187], v[78:81]
	v_mfma_f32_16x16x32_bf16 v[74:77], v[208:211], v[184:187], v[74:77]
	v_mfma_f32_16x16x32_bf16 v[70:73], v[200:203], v[192:195], v[70:73]
	v_mfma_f32_16x16x32_bf16 v[66:69], v[208:211], v[192:195], v[66:69]
	v_mfma_f32_16x16x32_bf16 v[94:97], v[204:207], v[172:175], v[94:97]
	v_mfma_f32_16x16x32_bf16 v[90:93], v[212:215], v[172:175], v[90:93]
	v_mfma_f32_16x16x32_bf16 v[86:89], v[204:207], v[180:183], v[86:89]
	v_mfma_f32_16x16x32_bf16 v[82:85], v[212:215], v[180:183], v[82:85]
	v_mfma_f32_16x16x32_bf16 v[78:81], v[204:207], v[188:191], v[78:81]
	v_mfma_f32_16x16x32_bf16 v[74:77], v[212:215], v[188:191], v[74:77]
	v_mfma_f32_16x16x32_bf16 v[70:73], v[204:207], v[196:199], v[70:73]
	v_mfma_f32_16x16x32_bf16 v[66:69], v[212:215], v[196:199], v[66:69]
	s_barrier
	ds_read_b128 v[168:171], v143 offset:16384
	ds_read_b128 v[172:175], v143 offset:17408
	ds_read_b128 v[176:179], v143 offset:18432
	ds_read_b128 v[180:183], v143 offset:19456
	ds_read_b128 v[184:187], v143 offset:20480
	ds_read_b128 v[188:191], v143 offset:21504
	ds_read_b128 v[192:195], v143 offset:22528
	ds_read_b128 v[196:199], v143 offset:23552
	s_mov_b32 m0, s32
	s_add_u32 s98, s12, s34
	s_addc_u32 s99, s13, s35
	global_load_lds_dwordx4 v131, s[98:99]
	s_mov_b32 m0, s40
	s_add_u32 s98, s12, s64
	s_addc_u32 s99, s13, s65
	global_load_lds_dwordx4 v131, s[98:99]
	s_barrier
	s_waitcnt lgkmcnt(0)
	s_waitcnt lgkmcnt(0)
	v_mfma_f32_16x16x32_bf16 v[62:65], v[152:155], v[168:171], v[62:65]
	v_mfma_f32_16x16x32_bf16 v[58:61], v[160:163], v[168:171], v[58:61]
	v_mfma_f32_16x16x32_bf16 v[54:57], v[152:155], v[176:179], v[54:57]
	v_mfma_f32_16x16x32_bf16 v[50:53], v[160:163], v[176:179], v[50:53]
	v_mfma_f32_16x16x32_bf16 v[46:49], v[152:155], v[184:187], v[46:49]
	v_mfma_f32_16x16x32_bf16 v[42:45], v[160:163], v[184:187], v[42:45]
	v_mfma_f32_16x16x32_bf16 v[38:41], v[152:155], v[192:195], v[38:41]
	v_mfma_f32_16x16x32_bf16 v[34:37], v[160:163], v[192:195], v[34:37]
	v_mfma_f32_16x16x32_bf16 v[62:65], v[156:159], v[172:175], v[62:65]
	v_mfma_f32_16x16x32_bf16 v[58:61], v[164:167], v[172:175], v[58:61]
	v_mfma_f32_16x16x32_bf16 v[54:57], v[156:159], v[180:183], v[54:57]
	v_mfma_f32_16x16x32_bf16 v[50:53], v[164:167], v[180:183], v[50:53]
	v_mfma_f32_16x16x32_bf16 v[46:49], v[156:159], v[188:191], v[46:49]
	v_mfma_f32_16x16x32_bf16 v[42:45], v[164:167], v[188:191], v[42:45]
	v_mfma_f32_16x16x32_bf16 v[38:41], v[156:159], v[196:199], v[38:41]
	v_mfma_f32_16x16x32_bf16 v[34:37], v[164:167], v[196:199], v[34:37]
	s_barrier
	s_mov_b32 m0, s41
	s_add_u32 s98, s14, s68
	s_addc_u32 s99, s15, s69
	global_load_lds_dwordx4 v131, s[98:99]
	s_mov_b32 m0, s42
	s_add_u32 s98, s14, s70
	s_addc_u32 s99, s15, s71
	global_load_lds_dwordx4 v131, s[98:99]
	s_waitcnt vmcnt(10)
	s_barrier
; #define LDA(dst, b, h) for (int m = 0; m < 4; ++m) for (int k = 0; k < 2; ++k) \
;     dst[m][k] = *reinterpret_cast<const bf16x8*>((char*)SA(b, h) + a_thr + (m * 2 + k) * 1024)
; #define LDB(dst, b, h) for (int n = 0; n < 2; ++n) for (int k = 0; k < 2; ++k) \
;     dst[n][k] = *reinterpret_cast<const bf16x8*>((char*)SB(b, h) + b_thr + (n * 2 + k) * 1024)
; #define MMA(ai, bj, At, Btf) do { __builtin_amdgcn_s_setprio(1); \
;     for (int m = 0; m < 4; ++m) for (int n = 0; n < 2; ++n) for (int k = 0; k < 2; ++k) \
;       acc[ai][bj][m][n] = __builtin_amdgcn_mfma_f32_16x16x32_bf16(Btf[n][k], At[m][k], acc[ai][bj][m][n], 0, 0, 0); \
;     __builtin_amdgcn_s_setprio(0); } while (0)
; #define WAIT_V(n) asm volatile("s_waitcnt vmcnt(" #n ")" ::: "memory")
; #define WAIT_L(n) asm volatile("s_waitcnt lgkmcnt(" #n ")" ::: "memory")
; #define BAR __builtin_amdgcn_s_barrier()
; #define SCHED __builtin_amdgcn_sched_barrier(0)
; template <bool OVL, bool PANEL = false, class Epi>
; __device__ __forceinline__ void gemm_phase(const bf16_t* __restrict__ A, long lda, const bf16_t* __restrict__ Bt, long ldb, int nM, int nN, int K,
;                                            const Epi& epi, bf16_t* shm, int w0) {
;     ...
;       WAIT_V(6); BAR; MMA(1, 1, At, B1); BAR;
;       LDB(B0, 1, 0); SCHED; LDA(At, 1, 0); STAGE(SA(0, 1), A, lda, aoff, brow + HALF, t + 2);
;       WAIT_L(8); BAR; WAIT_L(0); MMA(0, 0, At, B0); BAR; SCHED;
;       LDB(B1, 1, 1); STAGE(SB(1, 0), Bt, ldb, boff, bcol, t + 3);
;       BAR; WAIT_L(0); MMA(0, 1, At, B1); BAR;
	v_mfma_f32_16x16x32_bf16 v[30:33], v[200:203], v[168:171], v[30:33]
	v_mfma_f32_16x16x32_bf16 v[26:29], v[208:211], v[168:171], v[26:29]
	v_mfma_f32_16x16x32_bf16 v[22:25], v[200:203], v[176:179], v[22:25]
	v_mfma_f32_16x16x32_bf16 v[18:21], v[208:211], v[176:179], v[18:21]
	v_mfma_f32_16x16x32_bf16 v[14:17], v[200:203], v[184:187], v[14:17]
	v_mfma_f32_16x16x32_bf16 v[10:13], v[208:211], v[184:187], v[10:13]
	v_mfma_f32_16x16x32_bf16 v[6:9], v[200:203], v[192:195], v[6:9]
	v_mfma_f32_16x16x32_bf16 v[2:5], v[208:211], v[192:195], v[2:5]
	v_mfma_f32_16x16x32_bf16 v[30:33], v[204:207], v[172:175], v[30:33]
	v_mfma_f32_16x16x32_bf16 v[26:29], v[212:215], v[172:175], v[26:29]
	v_mfma_f32_16x16x32_bf16 v[22:25], v[204:207], v[180:183], v[22:25]
	v_mfma_f32_16x16x32_bf16 v[18:21], v[212:215], v[180:183], v[18:21]
	v_mfma_f32_16x16x32_bf16 v[14:17], v[204:207], v[188:191], v[14:17]
	v_mfma_f32_16x16x32_bf16 v[10:13], v[212:215], v[188:191], v[10:13]
	v_mfma_f32_16x16x32_bf16 v[6:9], v[204:207], v[196:199], v[6:9]
	v_mfma_f32_16x16x32_bf16 v[2:5], v[212:215], v[196:199], v[2:5]
	s_barrier
	ds_read_b128 v[152:155], v222
	ds_read_b128 v[156:159], v222 offset:1024
	ds_read_b128 v[160:163], v222 offset:2048
	ds_read_b128 v[164:167], v222 offset:3072
	ds_read_b128 v[168:171], v143 offset:32768
	ds_read_b128 v[172:175], v143 offset:33792
	ds_read_b128 v[176:179], v143 offset:34816
	ds_read_b128 v[180:183], v143 offset:35840
	ds_read_b128 v[184:187], v143 offset:36864
	ds_read_b128 v[188:191], v143 offset:37888
	ds_read_b128 v[192:195], v143 offset:38912
	ds_read_b128 v[196:199], v143 offset:39936
	s_mov_b32 m0, s43
	s_add_u32 s98, s12, s68
	s_addc_u32 s99, s13, s69
	global_load_lds_dwordx4 v131, s[98:99]
	s_mov_b32 m0, s44
	s_add_u32 s98, s12, s70
	s_addc_u32 s99, s13, s71
	global_load_lds_dwordx4 v131, s[98:99]
	s_waitcnt lgkmcnt(8)
	s_waitcnt vmcnt(10)
	s_barrier
	s_waitcnt lgkmcnt(0)
	s_waitcnt lgkmcnt(0)
	v_mfma_f32_16x16x32_bf16 v[126:129], v[152:155], v[168:171], v[126:129]
	v_mfma_f32_16x16x32_bf16 v[122:125], v[160:163], v[168:171], v[122:125]
	v_mfma_f32_16x16x32_bf16 v[118:121], v[152:155], v[176:179], v[118:121]
	v_mfma_f32_16x16x32_bf16 v[114:117], v[160:163], v[176:179], v[114:117]
	v_mfma_f32_16x16x32_bf16 v[110:113], v[152:155], v[184:187], v[110:113]
	v_mfma_f32_16x16x32_bf16 v[106:109], v[160:163], v[184:187], v[106:109]
	v_mfma_f32_16x16x32_bf16 v[102:105], v[152:155], v[192:195], v[102:105]
	v_mfma_f32_16x16x32_bf16 v[98:101], v[160:163], v[192:195], v[98:101]
	v_mfma_f32_16x16x32_bf16 v[126:129], v[156:159], v[172:175], v[126:129]
	v_mfma_f32_16x16x32_bf16 v[122:125], v[164:167], v[172:175], v[122:125]
	v_mfma_f32_16x16x32_bf16 v[118:121], v[156:159], v[180:183], v[118:121]
	v_mfma_f32_16x16x32_bf16 v[114:117], v[164:167], v[180:183], v[114:117]
	v_mfma_f32_16x16x32_bf16 v[110:113], v[156:159], v[188:191], v[110:113]
	v_mfma_f32_16x16x32_bf16 v[106:109], v[164:167], v[188:191], v[106:109]
	v_mfma_f32_16x16x32_bf16 v[102:105], v[156:159], v[196:199], v[102:105]
	v_mfma_f32_16x16x32_bf16 v[98:101], v[164:167], v[196:199], v[98:101]
	s_barrier
	ds_read_b128 v[200:203], v223
	ds_read_b128 v[204:207], v223 offset:1024
	ds_read_b128 v[208:211], v223 offset:2048
	ds_read_b128 v[212:215], v223 offset:3072
	s_mov_b32 m0, s45
	s_add_u32 s98, s14, s94
	s_addc_u32 s99, s15, s95
	global_load_lds_dwordx4 v131, s[98:99]
	s_mov_b32 m0, s46
	s_add_u32 s98, s14, s72
	s_addc_u32 s99, s15, s73
	global_load_lds_dwordx4 v131, s[98:99]
	s_waitcnt vmcnt(10)
	s_barrier
	s_waitcnt lgkmcnt(0)
	s_waitcnt lgkmcnt(0)
	v_mfma_f32_16x16x32_bf16 v[94:97], v[200:203], v[168:171], v[94:97]
	v_mfma_f32_16x16x32_bf16 v[90:93], v[208:211], v[168:171], v[90:93]
	v_mfma_f32_16x16x32_bf16 v[86:89], v[200:203], v[176:179], v[86:89]
	v_mfma_f32_16x16x32_bf16 v[82:85], v[208:211], v[176:179], v[82:85]
	v_mfma_f32_16x16x32_bf16 v[78:81], v[200:203], v[184:187], v[78:81]
	v_mfma_f32_16x16x32_bf16 v[74:77], v[208:211], v[184:187], v[74:77]
	v_mfma_f32_16x16x32_bf16 v[70:73], v[200:203], v[192:195], v[70:73]
	v_mfma_f32_16x16x32_bf16 v[66:69], v[208:211], v[192:195], v[66:69]
	v_mfma_f32_16x16x32_bf16 v[94:97], v[204:207], v[172:175], v[94:97]
	v_mfma_f32_16x16x32_bf16 v[90:93], v[212:215], v[172:175], v[90:93]
	v_mfma_f32_16x16x32_bf16 v[86:89], v[204:207], v[180:183], v[86:89]
	v_mfma_f32_16x16x32_bf16 v[82:85], v[212:215], v[180:183], v[82:85]
	v_mfma_f32_16x16x32_bf16 v[78:81], v[204:207], v[188:191], v[78:81]
	v_mfma_f32_16x16x32_bf16 v[74:77], v[212:215], v[188:191], v[74:77]
	v_mfma_f32_16x16x32_bf16 v[70:73], v[204:207], v[196:199], v[70:73]
	v_mfma_f32_16x16x32_bf16 v[66:69], v[212:215], v[196:199], v[66:69]
	s_barrier
; #define LDA(dst, b, h) for (int m = 0; m < 4; ++m) for (int k = 0; k < 2; ++k) \
;     dst[m][k] = *reinterpret_cast<const bf16x8*>((char*)SA(b, h) + a_thr + (m * 2 + k) * 1024)
; #define LDB(dst, b, h) for (int n = 0; n < 2; ++n) for (int k = 0; k < 2; ++k) \
;     dst[n][k] = *reinterpret_cast<const bf16x8*>((char*)SB(b, h) + b_thr + (n * 2 + k) * 1024)
; #define MMA(ai, bj, At, Btf) do { __builtin_amdgcn_s_setprio(1); \
;     for (int m = 0; m < 4; ++m) for (int n = 0; n < 2; ++n) for (int k = 0; k < 2; ++k) \
;       acc[ai][bj][m][n] = __builtin_amdgcn_mfma_f32_16x16x32_bf16(Btf[n][k], At[m][k], acc[ai][bj][m][n], 0, 0, 0); \
;     __builtin_amdgcn_s_setprio(0); } while (0)
; #define WAIT_V(n) asm volatile("s_waitcnt vmcnt(" #n ")" ::: "memory")
; #define WAIT_L(n) asm volatile("s_waitcnt lgkmcnt(" #n ")" ::: "memory")
; #define BAR __builtin_amdgcn_s_barrier()
; #define SCHED __builtin_amdgcn_sched_barrier(0)
; template <bool OVL, bool PANEL = false, class Epi>
; __device__ __forceinline__ void gemm_phase(const bf16_t* __restrict__ A, long lda, const bf16_t* __restrict__ Bt, long ldb, int nM, int nN, int K,
;                                            const Epi& epi, bf16_t* shm, int w0) {
;     ...
;       LDA(At, 1, 1); STAGE(SA(1, 0), A, lda, aoff, brow, t + 3);
;       BAR; WAIT_L(0); MMA(1, 0, At, B0); BAR; SCHED;
;       STAGE(SB(1, 1), Bt, ldb, boff, bcol + HALF, t + 3);
;       WAIT_V(6); BAR; MMA(1, 1, At, B1); BAR;
;     }
;     { LDB(B0, 0, 0); LDA(At, 0, 0); STAGE(SA(1, 1), A, lda, aoff, brow + HALF, nt - 1);
	ds_read_b128 v[168:171], v143 offset:49152
	ds_read_b128 v[172:175], v143 offset:50176
	ds_read_b128 v[176:179], v143 offset:51200
	ds_read_b128 v[180:183], v143 offset:52224
	ds_read_b128 v[184:187], v143 offset:53248
	ds_read_b128 v[188:191], v143 offset:54272
	ds_read_b128 v[192:195], v143 offset:55296
	ds_read_b128 v[196:199], v143 offset:56320
	s_mov_b32 m0, s47
	s_add_u32 s98, s12, s94
	s_addc_u32 s99, s13, s95
	global_load_lds_dwordx4 v131, s[98:99]
	s_mov_b32 m0, s48
	s_add_u32 s98, s12, s72
	s_addc_u32 s99, s13, s73
	global_load_lds_dwordx4 v131, s[98:99]
	s_barrier
	s_waitcnt lgkmcnt(0)
	s_waitcnt lgkmcnt(0)
	v_mfma_f32_16x16x32_bf16 v[62:65], v[152:155], v[168:171], v[62:65]
	v_mfma_f32_16x16x32_bf16 v[58:61], v[160:163], v[168:171], v[58:61]
	v_mfma_f32_16x16x32_bf16 v[54:57], v[152:155], v[176:179], v[54:57]
	v_mfma_f32_16x16x32_bf16 v[50:53], v[160:163], v[176:179], v[50:53]
	v_mfma_f32_16x16x32_bf16 v[46:49], v[152:155], v[184:187], v[46:49]
	v_mfma_f32_16x16x32_bf16 v[42:45], v[160:163], v[184:187], v[42:45]
	v_mfma_f32_16x16x32_bf16 v[38:41], v[152:155], v[192:195], v[38:41]
	v_mfma_f32_16x16x32_bf16 v[34:37], v[160:163], v[192:195], v[34:37]
	v_mfma_f32_16x16x32_bf16 v[62:65], v[156:159], v[172:175], v[62:65]
	v_mfma_f32_16x16x32_bf16 v[58:61], v[164:167], v[172:175], v[58:61]
	v_mfma_f32_16x16x32_bf16 v[54:57], v[156:159], v[180:183], v[54:57]
	v_mfma_f32_16x16x32_bf16 v[50:53], v[164:167], v[180:183], v[50:53]
	v_mfma_f32_16x16x32_bf16 v[46:49], v[156:159], v[188:191], v[46:49]
	v_mfma_f32_16x16x32_bf16 v[42:45], v[164:167], v[188:191], v[42:45]
	v_mfma_f32_16x16x32_bf16 v[38:41], v[156:159], v[196:199], v[38:41]
	v_mfma_f32_16x16x32_bf16 v[34:37], v[164:167], v[196:199], v[34:37]
	s_barrier
	s_mov_b32 m0, s49
	s_add_u32 s98, s14, s26
	s_addc_u32 s99, s15, s27
	global_load_lds_dwordx4 v131, s[98:99]
	s_mov_b32 m0, s50
	s_add_u32 s98, s14, s28
	s_addc_u32 s99, s15, s29
	global_load_lds_dwordx4 v131, s[98:99]
	s_add_i32 s21, s21, 2
	s_add_u32 s10, s10, 0x100
	s_addc_u32 s11, s11, 0
	s_cmp_lt_u32 s21, 12
	s_waitcnt vmcnt(10)
	s_barrier
	v_mfma_f32_16x16x32_bf16 v[30:33], v[200:203], v[168:171], v[30:33]
	v_mfma_f32_16x16x32_bf16 v[26:29], v[208:211], v[168:171], v[26:29]
	v_mfma_f32_16x16x32_bf16 v[22:25], v[200:203], v[176:179], v[22:25]
	v_mfma_f32_16x16x32_bf16 v[18:21], v[208:211], v[176:179], v[18:21]
	v_mfma_f32_16x16x32_bf16 v[14:17], v[200:203], v[184:187], v[14:17]
	v_mfma_f32_16x16x32_bf16 v[10:13], v[208:211], v[184:187], v[10:13]
	v_mfma_f32_16x16x32_bf16 v[6:9], v[200:203], v[192:195], v[6:9]
	v_mfma_f32_16x16x32_bf16 v[2:5], v[208:211], v[192:195], v[2:5]
	v_mfma_f32_16x16x32_bf16 v[30:33], v[204:207], v[172:175], v[30:33]
	v_mfma_f32_16x16x32_bf16 v[26:29], v[212:215], v[172:175], v[26:29]
	v_mfma_f32_16x16x32_bf16 v[22:25], v[204:207], v[180:183], v[22:25]
	v_mfma_f32_16x16x32_bf16 v[18:21], v[212:215], v[180:183], v[18:21]
	v_mfma_f32_16x16x32_bf16 v[14:17], v[204:207], v[188:191], v[14:17]
	v_mfma_f32_16x16x32_bf16 v[10:13], v[212:215], v[188:191], v[10:13]
	v_mfma_f32_16x16x32_bf16 v[6:9], v[204:207], v[196:199], v[6:9]
	v_mfma_f32_16x16x32_bf16 v[2:5], v[212:215], v[196:199], v[2:5]
	s_barrier
	s_cbranch_scc1 .LBB0_410
	s_waitcnt vmcnt(6)
	v_add_u32_e32 v212, 16, v140
	v_add_u32_e32 v0, 0x10000, v212
	ds_read_b128 v[144:147], v0
	ds_read_b128 v[152:155], v0 offset:1024
	ds_read_b128 v[156:159], v0 offset:2048
	ds_read_b128 v[160:163], v0 offset:3072
	ds_read_b128 v[164:167], v143
	ds_read_b128 v[168:171], v143 offset:1024
	ds_read_b128 v[172:175], v143 offset:2048
	ds_read_b128 v[176:179], v143 offset:3072
	ds_read_b128 v[180:183], v143 offset:4096
	ds_read_b128 v[184:187], v143 offset:5120
	ds_read_b128 v[188:191], v143 offset:6144
	ds_read_b128 v[192:195], v143 offset:7168
	v_mov_b32_e32 v0, v131
	s_mov_b64 s[0:1], 0x40780
	v_lshl_add_u64 v[148:149], s[8:9], 0, v[0:1]
	v_lshl_add_u64 v[196:197], v[148:149], 0, s[0:1]
	v_readfirstlane_b32 s0, v150
	s_mov_b32 m0, s0
	s_mov_b64 s[0:1], 0x60780
	v_lshl_add_u64 v[148:149], v[148:149], 0, s[0:1]
	v_readfirstlane_b32 s0, v151
	global_load_lds_dwordx4 v[196:197], off
	s_mov_b32 m0, s0
	s_nop 0
	global_load_lds_dwordx4 v[148:149], off
	s_barrier
	s_waitcnt lgkmcnt(0)

; #define LDA(dst, b, h) for (int m = 0; m < 4; ++m) for (int k = 0; k < 2; ++k) \
;     dst[m][k] = *reinterpret_cast<const bf16x8*>((char*)SA(b, h) + a_thr + (m * 2 + k) * 1024)
; #define LDB(dst, b, h) for (int n = 0; n < 2; ++n) for (int k = 0; k < 2; ++k) \
;     dst[n][k] = *reinterpret_cast<const bf16x8*>((char*)SB(b, h) + b_thr + (n * 2 + k) * 1024)
; #define MMA(ai, bj, At, Btf) do { __builtin_amdgcn_s_setprio(1); \
;     for (int m = 0; m < 4; ++m) for (int n = 0; n < 2; ++n) for (int k = 0; k < 2; ++k) \
;       acc[ai][bj][m][n] = __builtin_amdgcn_mfma_f32_16x16x32_bf16(Btf[n][k], At[m][k], acc[ai][bj][m][n], 0, 0, 0); \
;     __builtin_amdgcn_s_setprio(0); } while (0)
; #define WAIT_L(n) asm volatile("s_waitcnt lgkmcnt(" #n ")" ::: "memory")
; #define BAR __builtin_amdgcn_s_barrier()
; template <bool OVL, bool PANEL = false, class Epi>
; __device__ __forceinline__ void gemm_phase(const bf16_t* __restrict__ A, long lda, const bf16_t* __restrict__ Bt, long ldb, int nM, int nN, int K,
;                                            const Epi& epi, bf16_t* shm, int w0) {
;     ...
;     { LDB(B0, 0, 0); LDA(At, 0, 0); STAGE(SA(1, 1), A, lda, aoff, brow + HALF, nt - 1);
;       BAR; WAIT_L(0); MMA(0, 0, At, B0); BAR;
	s_waitcnt lgkmcnt(0)
	v_mfma_f32_16x16x32_bf16 v[126:129], v[144:147], v[164:167], v[126:129]
	v_mfma_f32_16x16x32_bf16 v[122:125], v[156:159], v[164:167], v[122:125]
	v_mfma_f32_16x16x32_bf16 v[118:121], v[144:147], v[172:175], v[118:121]
	v_mfma_f32_16x16x32_bf16 v[114:117], v[156:159], v[172:175], v[114:117]
	v_mfma_f32_16x16x32_bf16 v[110:113], v[144:147], v[180:183], v[110:113]
	v_mfma_f32_16x16x32_bf16 v[106:109], v[156:159], v[180:183], v[106:109]
	v_mfma_f32_16x16x32_bf16 v[102:105], v[144:147], v[188:191], v[102:105]
	v_mfma_f32_16x16x32_bf16 v[126:129], v[152:155], v[168:171], v[126:129]
	v_mfma_f32_16x16x32_bf16 v[122:125], v[160:163], v[168:171], v[122:125]
	v_mfma_f32_16x16x32_bf16 v[118:121], v[152:155], v[176:179], v[118:121]
	v_mfma_f32_16x16x32_bf16 v[114:117], v[160:163], v[176:179], v[114:117]
	v_mfma_f32_16x16x32_bf16 v[110:113], v[152:155], v[184:187], v[110:113]
	v_mfma_f32_16x16x32_bf16 v[106:109], v[160:163], v[184:187], v[106:109]
	v_mfma_f32_16x16x32_bf16 v[102:105], v[152:155], v[192:195], v[102:105]
	v_mfma_f32_16x16x32_bf16 v[98:101], v[156:159], v[188:191], v[98:101]
	v_mfma_f32_16x16x32_bf16 v[148:151], v[160:163], v[192:195], v[98:101]

; #define LDB(dst, b, h) for (int n = 0; n < 2; ++n) for (int k = 0; k < 2; ++k) \
;     dst[n][k] = *reinterpret_cast<const bf16x8*>((char*)SB(b, h) + b_thr + (n * 2 + k) * 1024)
; #define MMA(ai, bj, At, Btf) do { __builtin_amdgcn_s_setprio(1); \
;     for (int m = 0; m < 4; ++m) for (int n = 0; n < 2; ++n) for (int k = 0; k < 2; ++k) \
;       acc[ai][bj][m][n] = __builtin_amdgcn_mfma_f32_16x16x32_bf16(Btf[n][k], At[m][k], acc[ai][bj][m][n], 0, 0, 0); \
;     __builtin_amdgcn_s_setprio(0); } while (0)
; #define WAIT_L(n) asm volatile("s_waitcnt lgkmcnt(" #n ")" ::: "memory")
; #define BAR __builtin_amdgcn_s_barrier()
; template <bool OVL, bool PANEL = false, class Epi>
; __device__ __forceinline__ void gemm_phase(const bf16_t* __restrict__ A, long lda, const bf16_t* __restrict__ Bt, long ldb, int nM, int nN, int K,
;                                            const Epi& epi, bf16_t* shm, int w0) {
;     ...
;       LDB(B1, 0, 1); BAR; WAIT_L(0); MMA(0, 1, At, B1); BAR;
	v_add_u32_e32 v0, 0x14000, v212
	s_barrier
	s_nop 3
	ds_read_b128 v[98:101], v0
	ds_read_b128 v[196:199], v0 offset:1024
	ds_read_b128 v[200:203], v0 offset:2048
	ds_read_b128 v[204:207], v0 offset:3072
	s_barrier
	s_waitcnt lgkmcnt(0)

; #define LDB(dst, b, h) for (int n = 0; n < 2; ++n) for (int k = 0; k < 2; ++k) \
;     dst[n][k] = *reinterpret_cast<const bf16x8*>((char*)SB(b, h) + b_thr + (n * 2 + k) * 1024)
; #define MMA(ai, bj, At, Btf) do { __builtin_amdgcn_s_setprio(1); \
;     for (int m = 0; m < 4; ++m) for (int n = 0; n < 2; ++n) for (int k = 0; k < 2; ++k) \
;       acc[ai][bj][m][n] = __builtin_amdgcn_mfma_f32_16x16x32_bf16(Btf[n][k], At[m][k], acc[ai][bj][m][n], 0, 0, 0); \
;     __builtin_amdgcn_s_setprio(0); } while (0)
; #define WAIT_L(n) asm volatile("s_waitcnt lgkmcnt(" #n ")" ::: "memory")
; #define BAR __builtin_amdgcn_s_barrier()
; template <bool OVL, bool PANEL = false, class Epi>
; __device__ __forceinline__ void gemm_phase(const bf16_t* __restrict__ A, long lda, const bf16_t* __restrict__ Bt, long ldb, int nM, int nN, int K,
;                                            const Epi& epi, bf16_t* shm, int w0) {
;     ...
;       LDB(B1, 0, 1); BAR; WAIT_L(0); MMA(0, 1, At, B1); BAR;
	s_waitcnt lgkmcnt(0)
	v_mfma_f32_16x16x32_bf16 v[94:97], v[98:101], v[164:167], v[94:97]
	v_mfma_f32_16x16x32_bf16 v[86:89], v[98:101], v[172:175], v[86:89]
	v_mfma_f32_16x16x32_bf16 v[82:85], v[200:203], v[172:175], v[82:85]
	v_mfma_f32_16x16x32_bf16 v[78:81], v[98:101], v[180:183], v[78:81]
	v_mfma_f32_16x16x32_bf16 v[74:77], v[200:203], v[180:183], v[74:77]
	v_mfma_f32_16x16x32_bf16 v[94:97], v[196:199], v[168:171], v[94:97]
	v_mfma_f32_16x16x32_bf16 v[90:93], v[200:203], v[164:167], v[90:93]
	v_mfma_f32_16x16x32_bf16 v[86:89], v[196:199], v[176:179], v[86:89]
	v_mfma_f32_16x16x32_bf16 v[82:85], v[204:207], v[176:179], v[82:85]
	v_mfma_f32_16x16x32_bf16 v[78:81], v[196:199], v[184:187], v[78:81]
	v_mfma_f32_16x16x32_bf16 v[74:77], v[204:207], v[184:187], v[74:77]
	v_mfma_f32_16x16x32_bf16 v[70:73], v[98:101], v[188:191], v[70:73]
	v_mfma_f32_16x16x32_bf16 v[66:69], v[200:203], v[188:191], v[66:69]
	v_mfma_f32_16x16x32_bf16 v[164:167], v[204:207], v[168:171], v[90:93]
	v_mfma_f32_16x16x32_bf16 v[168:171], v[196:199], v[192:195], v[70:73]
	v_mfma_f32_16x16x32_bf16 v[172:175], v[204:207], v[192:195], v[66:69]

; #define LDA(dst, b, h) for (int m = 0; m < 4; ++m) for (int k = 0; k < 2; ++k) \
;     dst[m][k] = *reinterpret_cast<const bf16x8*>((char*)SA(b, h) + a_thr + (m * 2 + k) * 1024)
; #define MMA(ai, bj, At, Btf) do { __builtin_amdgcn_s_setprio(1); \
;     for (int m = 0; m < 4; ++m) for (int n = 0; n < 2; ++n) for (int k = 0; k < 2; ++k) \
;       acc[ai][bj][m][n] = __builtin_amdgcn_mfma_f32_16x16x32_bf16(Btf[n][k], At[m][k], acc[ai][bj][m][n], 0, 0, 0); \
;     __builtin_amdgcn_s_setprio(0); } while (0)
; #define WAIT_V(n) asm volatile("s_waitcnt vmcnt(" #n ")" ::: "memory")
; #define WAIT_L(n) asm volatile("s_waitcnt lgkmcnt(" #n ")" ::: "memory")
; #define BAR __builtin_amdgcn_s_barrier()
; template <bool OVL, bool PANEL = false, class Epi>
; __device__ __forceinline__ void gemm_phase(const bf16_t* __restrict__ A, long lda, const bf16_t* __restrict__ Bt, long ldb, int nM, int nN, int K,
;                                            const Epi& epi, bf16_t* shm, int w0) {
;     ...
;       LDA(At, 0, 1); WAIT_V(4); BAR; WAIT_L(0); MMA(1, 0, At, B0); MMA(1, 1, At, B1); BAR; }
	s_barrier
	s_nop 2
	ds_read_b128 v[66:69], v143 offset:16384
	ds_read_b128 v[70:73], v143 offset:17408
	ds_read_b128 v[90:93], v143 offset:18432
	ds_read_b128 v[176:179], v143 offset:19456
	ds_read_b128 v[180:183], v143 offset:20480
	ds_read_b128 v[184:187], v143 offset:21504
	ds_read_b128 v[188:191], v143 offset:22528
	ds_read_b128 v[192:195], v143 offset:23552
	s_waitcnt vmcnt(4)
	s_barrier
	s_waitcnt lgkmcnt(0)

; #define LDA(dst, b, h) for (int m = 0; m < 4; ++m) for (int k = 0; k < 2; ++k) \
;     dst[m][k] = *reinterpret_cast<const bf16x8*>((char*)SA(b, h) + a_thr + (m * 2 + k) * 1024)
; #define MMA(ai, bj, At, Btf) do { __builtin_amdgcn_s_setprio(1); \
;     for (int m = 0; m < 4; ++m) for (int n = 0; n < 2; ++n) for (int k = 0; k < 2; ++k) \
;       acc[ai][bj][m][n] = __builtin_amdgcn_mfma_f32_16x16x32_bf16(Btf[n][k], At[m][k], acc[ai][bj][m][n], 0, 0, 0); \
;     __builtin_amdgcn_s_setprio(0); } while (0)
; #define WAIT_V(n) asm volatile("s_waitcnt vmcnt(" #n ")" ::: "memory")
; #define WAIT_L(n) asm volatile("s_waitcnt lgkmcnt(" #n ")" ::: "memory")
; #define BAR __builtin_amdgcn_s_barrier()
; template <bool OVL, bool PANEL = false, class Epi>
; __device__ __forceinline__ void gemm_phase(const bf16_t* __restrict__ A, long lda, const bf16_t* __restrict__ Bt, long ldb, int nM, int nN, int K,
;                                            const Epi& epi, bf16_t* shm, int w0) {
;     ...
;       LDA(At, 0, 1); WAIT_V(4); BAR; WAIT_L(0); MMA(1, 0, At, B0); MMA(1, 1, At, B1); BAR; }
	s_waitcnt lgkmcnt(0)
	v_mfma_f32_16x16x32_bf16 v[62:65], v[144:147], v[66:69], v[62:65]
	v_mfma_f32_16x16x32_bf16 v[54:57], v[144:147], v[90:93], v[54:57]
	v_mfma_f32_16x16x32_bf16 v[50:53], v[156:159], v[90:93], v[50:53]
	v_mfma_f32_16x16x32_bf16 v[46:49], v[144:147], v[180:183], v[46:49]
	v_mfma_f32_16x16x32_bf16 v[42:45], v[156:159], v[180:183], v[42:45]
	v_mfma_f32_16x16x32_bf16 v[38:41], v[144:147], v[188:191], v[38:41]
	v_mfma_f32_16x16x32_bf16 v[34:37], v[156:159], v[188:191], v[34:37]
	v_mfma_f32_16x16x32_bf16 v[62:65], v[152:155], v[70:73], v[62:65]
	v_mfma_f32_16x16x32_bf16 v[58:61], v[156:159], v[66:69], v[58:61]
	v_mfma_f32_16x16x32_bf16 v[54:57], v[152:155], v[176:179], v[54:57]
	v_mfma_f32_16x16x32_bf16 v[50:53], v[160:163], v[176:179], v[50:53]
	v_mfma_f32_16x16x32_bf16 v[46:49], v[152:155], v[184:187], v[46:49]
	v_mfma_f32_16x16x32_bf16 v[42:45], v[160:163], v[184:187], v[42:45]
	v_mfma_f32_16x16x32_bf16 v[38:41], v[152:155], v[192:195], v[38:41]
	v_mfma_f32_16x16x32_bf16 v[34:37], v[160:163], v[192:195], v[34:37]
	v_mfma_f32_16x16x32_bf16 v[208:211], v[160:163], v[70:73], v[58:61]


; #define LDA(dst, b, h) for (int m = 0; m < 4; ++m) for (int k = 0; k < 2; ++k) \
;     dst[m][k] = *reinterpret_cast<const bf16x8*>((char*)SA(b, h) + a_thr + (m * 2 + k) * 1024)
; #define MMA(ai, bj, At, Btf) do { __builtin_amdgcn_s_setprio(1); \
;     for (int m = 0; m < 4; ++m) for (int n = 0; n < 2; ++n) for (int k = 0; k < 2; ++k) \
;       acc[ai][bj][m][n] = __builtin_amdgcn_mfma_f32_16x16x32_bf16(Btf[n][k], At[m][k], acc[ai][bj][m][n], 0, 0, 0); \
;     __builtin_amdgcn_s_setprio(0); } while (0)
; #define WAIT_V(n) asm volatile("s_waitcnt vmcnt(" #n ")" ::: "memory")
; #define WAIT_L(n) asm volatile("s_waitcnt lgkmcnt(" #n ")" ::: "memory")
; #define BAR __builtin_amdgcn_s_barrier()
; template <bool OVL, bool PANEL = false, class Epi>
; __device__ __forceinline__ void gemm_phase(const bf16_t* __restrict__ A, long lda, const bf16_t* __restrict__ Bt, long ldb, int nM, int nN, int K,
;                                            const Epi& epi, bf16_t* shm, int w0) {
;     ...
;       LDA(At, 0, 1); WAIT_V(4); BAR; WAIT_L(0); MMA(1, 0, At, B0); MMA(1, 1, At, B1); BAR; }
	v_mfma_f32_16x16x32_bf16 v[30:33], v[98:101], v[66:69], v[30:33]
	v_mfma_f32_16x16x32_bf16 v[26:29], v[200:203], v[66:69], v[26:29]
	v_mfma_f32_16x16x32_bf16 v[22:25], v[98:101], v[90:93], v[22:25]
	v_mfma_f32_16x16x32_bf16 v[18:21], v[200:203], v[90:93], v[18:21]
	v_mfma_f32_16x16x32_bf16 v[14:17], v[98:101], v[180:183], v[14:17]
	v_mfma_f32_16x16x32_bf16 v[10:13], v[200:203], v[180:183], v[10:13]
	v_mfma_f32_16x16x32_bf16 v[6:9], v[98:101], v[188:191], v[6:9]
	v_mfma_f32_16x16x32_bf16 v[2:5], v[200:203], v[188:191], v[2:5]
	v_mfma_f32_16x16x32_bf16 v[30:33], v[196:199], v[70:73], v[30:33]
	v_mfma_f32_16x16x32_bf16 v[26:29], v[204:207], v[70:73], v[26:29]
	v_mfma_f32_16x16x32_bf16 v[22:25], v[196:199], v[176:179], v[22:25]
	v_mfma_f32_16x16x32_bf16 v[18:21], v[204:207], v[176:179], v[18:21]
	v_mfma_f32_16x16x32_bf16 v[14:17], v[196:199], v[184:187], v[14:17]
	v_mfma_f32_16x16x32_bf16 v[10:13], v[204:207], v[184:187], v[10:13]
	v_mfma_f32_16x16x32_bf16 v[6:9], v[196:199], v[192:195], v[6:9]
	v_mfma_f32_16x16x32_bf16 v[2:5], v[204:207], v[192:195], v[2:5]

; #define LDA(dst, b, h) for (int m = 0; m < 4; ++m) for (int k = 0; k < 2; ++k) \
;     dst[m][k] = *reinterpret_cast<const bf16x8*>((char*)SA(b, h) + a_thr + (m * 2 + k) * 1024)
; #define LDB(dst, b, h) for (int n = 0; n < 2; ++n) for (int k = 0; k < 2; ++k) \
;     dst[n][k] = *reinterpret_cast<const bf16x8*>((char*)SB(b, h) + b_thr + (n * 2 + k) * 1024)
; #define MMA(ai, bj, At, Btf) do { __builtin_amdgcn_s_setprio(1); \
;     for (int m = 0; m < 4; ++m) for (int n = 0; n < 2; ++n) for (int k = 0; k < 2; ++k) \
;       acc[ai][bj][m][n] = __builtin_amdgcn_mfma_f32_16x16x32_bf16(Btf[n][k], At[m][k], acc[ai][bj][m][n], 0, 0, 0); \
;     __builtin_amdgcn_s_setprio(0); } while (0)
; #define WAIT_V(n) asm volatile("s_waitcnt vmcnt(" #n ")" ::: "memory")
; #define WAIT_L(n) asm volatile("s_waitcnt lgkmcnt(" #n ")" ::: "memory")
; #define BAR __builtin_amdgcn_s_barrier()
; template <bool OVL, bool PANEL = false, class Epi>
; __device__ __forceinline__ void gemm_phase(const bf16_t* __restrict__ A, long lda, const bf16_t* __restrict__ Bt, long ldb, int nM, int nN, int K,
;                                            const Epi& epi, bf16_t* shm, int w0) {
;     ...
;     { LDB(B0, 1, 0); LDA(At, 1, 0); WAIT_V(2); BAR; WAIT_L(0); MMA(0, 0, At, B0); BAR;
	v_add_u32_e32 v0, 0x18000, v212
	s_barrier
	ds_read_b128 v[144:147], v0
	ds_read_b128 v[152:155], v0 offset:1024
	ds_read_b128 v[156:159], v0 offset:2048
	ds_read_b128 v[160:163], v0 offset:3072
	ds_read_b128 v[58:61], v143 offset:32768
	ds_read_b128 v[66:69], v143 offset:33792
	ds_read_b128 v[70:73], v143 offset:34816
	ds_read_b128 v[176:179], v143 offset:35840
	ds_read_b128 v[180:183], v143 offset:36864
	ds_read_b128 v[184:187], v143 offset:37888
	ds_read_b128 v[188:191], v143 offset:38912
	ds_read_b128 v[192:195], v143 offset:39936
	s_waitcnt vmcnt(2)
	s_barrier
	s_waitcnt lgkmcnt(0)

; #define LDA(dst, b, h) for (int m = 0; m < 4; ++m) for (int k = 0; k < 2; ++k) \
;     dst[m][k] = *reinterpret_cast<const bf16x8*>((char*)SA(b, h) + a_thr + (m * 2 + k) * 1024)
; #define LDB(dst, b, h) for (int n = 0; n < 2; ++n) for (int k = 0; k < 2; ++k) \
;     dst[n][k] = *reinterpret_cast<const bf16x8*>((char*)SB(b, h) + b_thr + (n * 2 + k) * 1024)
; #define MMA(ai, bj, At, Btf) do { __builtin_amdgcn_s_setprio(1); \
;     for (int m = 0; m < 4; ++m) for (int n = 0; n < 2; ++n) for (int k = 0; k < 2; ++k) \
;       acc[ai][bj][m][n] = __builtin_amdgcn_mfma_f32_16x16x32_bf16(Btf[n][k], At[m][k], acc[ai][bj][m][n], 0, 0, 0); \
;     __builtin_amdgcn_s_setprio(0); } while (0)
; #define WAIT_V(n) asm volatile("s_waitcnt vmcnt(" #n ")" ::: "memory")
; #define WAIT_L(n) asm volatile("s_waitcnt lgkmcnt(" #n ")" ::: "memory")
; #define BAR __builtin_amdgcn_s_barrier()
; template <bool OVL, bool PANEL = false, class Epi>
; __device__ __forceinline__ void gemm_phase(const bf16_t* __restrict__ A, long lda, const bf16_t* __restrict__ Bt, long ldb, int nM, int nN, int K,
;                                            const Epi& epi, bf16_t* shm, int w0) {
;     ...
;     { LDB(B0, 1, 0); LDA(At, 1, 0); WAIT_V(2); BAR; WAIT_L(0); MMA(0, 0, At, B0); BAR;
	s_waitcnt lgkmcnt(0)
	v_mfma_f32_16x16x32_bf16 v[90:93], v[144:147], v[58:61], v[126:129]
	v_mfma_f32_16x16x32_bf16 v[126:129], v[152:155], v[66:69], v[90:93]
	v_mfma_f32_16x16x32_bf16 v[90:93], v[156:159], v[58:61], v[122:125]
	v_mfma_f32_16x16x32_bf16 v[122:125], v[160:163], v[66:69], v[90:93]
	v_mfma_f32_16x16x32_bf16 v[90:93], v[144:147], v[70:73], v[118:121]
	v_mfma_f32_16x16x32_bf16 v[118:121], v[152:155], v[176:179], v[90:93]
	v_mfma_f32_16x16x32_bf16 v[90:93], v[156:159], v[70:73], v[114:117]
	v_mfma_f32_16x16x32_bf16 v[114:117], v[160:163], v[176:179], v[90:93]
	v_mfma_f32_16x16x32_bf16 v[90:93], v[144:147], v[180:183], v[110:113]
	v_mfma_f32_16x16x32_bf16 v[110:113], v[152:155], v[184:187], v[90:93]
	v_mfma_f32_16x16x32_bf16 v[90:93], v[156:159], v[180:183], v[106:109]
	v_mfma_f32_16x16x32_bf16 v[106:109], v[160:163], v[184:187], v[90:93]
	v_mfma_f32_16x16x32_bf16 v[90:93], v[144:147], v[188:191], v[102:105]
	v_mfma_f32_16x16x32_bf16 v[98:101], v[152:155], v[192:195], v[90:93]
	v_mfma_f32_16x16x32_bf16 v[90:93], v[156:159], v[188:191], v[148:151]
	v_mfma_f32_16x16x32_bf16 v[90:93], v[160:163], v[192:195], v[90:93]

; #define LDB(dst, b, h) for (int n = 0; n < 2; ++n) for (int k = 0; k < 2; ++k) \
;     dst[n][k] = *reinterpret_cast<const bf16x8*>((char*)SB(b, h) + b_thr + (n * 2 + k) * 1024)
; #define MMA(ai, bj, At, Btf) do { __builtin_amdgcn_s_setprio(1); \
;     for (int m = 0; m < 4; ++m) for (int n = 0; n < 2; ++n) for (int k = 0; k < 2; ++k) \
;       acc[ai][bj][m][n] = __builtin_amdgcn_mfma_f32_16x16x32_bf16(Btf[n][k], At[m][k], acc[ai][bj][m][n], 0, 0, 0); \
;     __builtin_amdgcn_s_setprio(0); } while (0)
; #define WAIT_V(n) asm volatile("s_waitcnt vmcnt(" #n ")" ::: "memory")
; #define WAIT_L(n) asm volatile("s_waitcnt lgkmcnt(" #n ")" ::: "memory")
; #define BAR __builtin_amdgcn_s_barrier()
; template <bool OVL, bool PANEL = false, class Epi>
; __device__ __forceinline__ void gemm_phase(const bf16_t* __restrict__ A, long lda, const bf16_t* __restrict__ Bt, long ldb, int nM, int nN, int K,
;                                            const Epi& epi, bf16_t* shm, int w0) {
;     ...
;       LDB(B1, 1, 1); WAIT_V(0); BAR; WAIT_L(0); MMA(0, 1, At, B1); BAR;
	v_add_u32_e32 v0, 0x1c000, v212
	s_barrier
	ds_read_b128 v[148:151], v0
	ds_read_b128 v[196:199], v0 offset:1024
	ds_read_b128 v[200:203], v0 offset:2048
	ds_read_b128 v[204:207], v0 offset:3072
	s_waitcnt vmcnt(0)
	s_barrier
	s_waitcnt lgkmcnt(0)

; #define LDB(dst, b, h) for (int n = 0; n < 2; ++n) for (int k = 0; k < 2; ++k) \
;     dst[n][k] = *reinterpret_cast<const bf16x8*>((char*)SB(b, h) + b_thr + (n * 2 + k) * 1024)
; #define MMA(ai, bj, At, Btf) do { __builtin_amdgcn_s_setprio(1); \
;     for (int m = 0; m < 4; ++m) for (int n = 0; n < 2; ++n) for (int k = 0; k < 2; ++k) \
;       acc[ai][bj][m][n] = __builtin_amdgcn_mfma_f32_16x16x32_bf16(Btf[n][k], At[m][k], acc[ai][bj][m][n], 0, 0, 0); \
;     __builtin_amdgcn_s_setprio(0); } while (0)
; #define WAIT_V(n) asm volatile("s_waitcnt vmcnt(" #n ")" ::: "memory")
; #define WAIT_L(n) asm volatile("s_waitcnt lgkmcnt(" #n ")" ::: "memory")
; #define BAR __builtin_amdgcn_s_barrier()
; template <bool OVL, bool PANEL = false, class Epi>
; __device__ __forceinline__ void gemm_phase(const bf16_t* __restrict__ A, long lda, const bf16_t* __restrict__ Bt, long ldb, int nM, int nN, int K,
;                                            const Epi& epi, bf16_t* shm, int w0) {
;     ...
;       LDB(B1, 1, 1); WAIT_V(0); BAR; WAIT_L(0); MMA(0, 1, At, B1); BAR;
	s_waitcnt lgkmcnt(0)
	v_mfma_f32_16x16x32_bf16 v[94:97], v[148:151], v[58:61], v[94:97]
	v_mfma_f32_16x16x32_bf16 v[58:61], v[200:203], v[58:61], v[164:167]
	v_mfma_f32_16x16x32_bf16 v[102:105], v[196:199], v[66:69], v[94:97]
	v_mfma_f32_16x16x32_bf16 v[94:97], v[204:207], v[66:69], v[58:61]
	v_mfma_f32_16x16x32_bf16 v[58:61], v[148:151], v[70:73], v[86:89]
	v_mfma_f32_16x16x32_bf16 v[86:89], v[196:199], v[176:179], v[58:61]
	v_mfma_f32_16x16x32_bf16 v[58:61], v[200:203], v[70:73], v[82:85]
	v_mfma_f32_16x16x32_bf16 v[82:85], v[204:207], v[176:179], v[58:61]
	v_mfma_f32_16x16x32_bf16 v[58:61], v[148:151], v[180:183], v[78:81]
	v_mfma_f32_16x16x32_bf16 v[78:81], v[196:199], v[184:187], v[58:61]
	v_mfma_f32_16x16x32_bf16 v[58:61], v[200:203], v[180:183], v[74:77]
	v_mfma_f32_16x16x32_bf16 v[70:73], v[204:207], v[184:187], v[58:61]
	v_mfma_f32_16x16x32_bf16 v[58:61], v[148:151], v[188:191], v[168:171]
	v_mfma_f32_16x16x32_bf16 v[66:69], v[196:199], v[192:195], v[58:61]
	v_mfma_f32_16x16x32_bf16 v[58:61], v[200:203], v[188:191], v[172:175]
	v_mfma_f32_16x16x32_bf16 v[58:61], v[204:207], v[192:195], v[58:61]

; #define LDA(dst, b, h) for (int m = 0; m < 4; ++m) for (int k = 0; k < 2; ++k) \
;     dst[m][k] = *reinterpret_cast<const bf16x8*>((char*)SA(b, h) + a_thr + (m * 2 + k) * 1024)
; #define MMA(ai, bj, At, Btf) do { __builtin_amdgcn_s_setprio(1); \
;     for (int m = 0; m < 4; ++m) for (int n = 0; n < 2; ++n) for (int k = 0; k < 2; ++k) \
;       acc[ai][bj][m][n] = __builtin_amdgcn_mfma_f32_16x16x32_bf16(Btf[n][k], At[m][k], acc[ai][bj][m][n], 0, 0, 0); \
;     __builtin_amdgcn_s_setprio(0); } while (0)
; #define WAIT_L(n) asm volatile("s_waitcnt lgkmcnt(" #n ")" ::: "memory")
; #define BAR __builtin_amdgcn_s_barrier()
; template <bool OVL, bool PANEL = false, class Epi>
; __device__ __forceinline__ void gemm_phase(const bf16_t* __restrict__ A, long lda, const bf16_t* __restrict__ Bt, long ldb, int nM, int nN, int K,
;                                            const Epi& epi, bf16_t* shm, int w0) {
;     ...
;       LDA(At, 1, 1); BAR; WAIT_L(0); MMA(1, 0, At, B0); MMA(1, 1, At, B1); BAR; }
	s_barrier
	ds_read_b128 v[164:167], v143 offset:49152
	ds_read_b128 v[168:171], v143 offset:50176
	ds_read_b128 v[172:175], v143 offset:51200
	ds_read_b128 v[176:179], v143 offset:52224
	ds_read_b128 v[180:183], v143 offset:53248
	ds_read_b128 v[184:187], v143 offset:54272
	ds_read_b128 v[188:191], v143 offset:55296
	ds_read_b128 v[192:195], v143 offset:56320
	s_barrier
	s_waitcnt lgkmcnt(0)

; #define LDA(dst, b, h) for (int m = 0; m < 4; ++m) for (int k = 0; k < 2; ++k) \
;     dst[m][k] = *reinterpret_cast<const bf16x8*>((char*)SA(b, h) + a_thr + (m * 2 + k) * 1024)
; #define MMA(ai, bj, At, Btf) do { __builtin_amdgcn_s_setprio(1); \
;     for (int m = 0; m < 4; ++m) for (int n = 0; n < 2; ++n) for (int k = 0; k < 2; ++k) \
;       acc[ai][bj][m][n] = __builtin_amdgcn_mfma_f32_16x16x32_bf16(Btf[n][k], At[m][k], acc[ai][bj][m][n], 0, 0, 0); \
;     __builtin_amdgcn_s_setprio(0); } while (0)
; #define WAIT_L(n) asm volatile("s_waitcnt lgkmcnt(" #n ")" ::: "memory")
; #define BAR __builtin_amdgcn_s_barrier()
; template <bool OVL, bool PANEL = false, class Epi>
; __device__ __forceinline__ void gemm_phase(const bf16_t* __restrict__ A, long lda, const bf16_t* __restrict__ Bt, long ldb, int nM, int nN, int K,
;                                            const Epi& epi, bf16_t* shm, int w0) {
;     ...
;       LDA(At, 1, 1); BAR; WAIT_L(0); MMA(1, 0, At, B0); MMA(1, 1, At, B1); BAR; }
	s_waitcnt lgkmcnt(0)
	v_mfma_f32_16x16x32_bf16 v[62:65], v[144:147], v[164:167], v[62:65]
	v_mfma_f32_16x16x32_bf16 v[74:77], v[152:155], v[168:171], v[62:65]
	v_mfma_f32_16x16x32_bf16 v[62:65], v[156:159], v[164:167], v[208:211]
	v_mfma_f32_16x16x32_bf16 v[54:57], v[144:147], v[172:175], v[54:57]
	v_mfma_f32_16x16x32_bf16 v[50:53], v[156:159], v[172:175], v[50:53]
	v_mfma_f32_16x16x32_bf16 v[46:49], v[144:147], v[180:183], v[46:49]
	v_mfma_f32_16x16x32_bf16 v[42:45], v[156:159], v[180:183], v[42:45]
	v_mfma_f32_16x16x32_bf16 v[38:41], v[144:147], v[188:191], v[38:41]
	v_mfma_f32_16x16x32_bf16 v[34:37], v[156:159], v[188:191], v[34:37]
	v_mfma_f32_16x16x32_bf16 v[62:65], v[160:163], v[168:171], v[62:65]
	v_mfma_f32_16x16x32_bf16 v[54:57], v[152:155], v[176:179], v[54:57]
	v_mfma_f32_16x16x32_bf16 v[50:53], v[160:163], v[176:179], v[50:53]
	v_mfma_f32_16x16x32_bf16 v[46:49], v[152:155], v[184:187], v[46:49]
	v_mfma_f32_16x16x32_bf16 v[42:45], v[160:163], v[184:187], v[42:45]
	v_mfma_f32_16x16x32_bf16 v[38:41], v[152:155], v[192:195], v[38:41]
	v_mfma_f32_16x16x32_bf16 v[34:37], v[160:163], v[192:195], v[34:37]


; #define LDA(dst, b, h) for (int m = 0; m < 4; ++m) for (int k = 0; k < 2; ++k) \
;     dst[m][k] = *reinterpret_cast<const bf16x8*>((char*)SA(b, h) + a_thr + (m * 2 + k) * 1024)
; #define MMA(ai, bj, At, Btf) do { __builtin_amdgcn_s_setprio(1); \
;     for (int m = 0; m < 4; ++m) for (int n = 0; n < 2; ++n) for (int k = 0; k < 2; ++k) \
;       acc[ai][bj][m][n] = __builtin_amdgcn_mfma_f32_16x16x32_bf16(Btf[n][k], At[m][k], acc[ai][bj][m][n], 0, 0, 0); \
;     __builtin_amdgcn_s_setprio(0); } while (0)
; #define WAIT_L(n) asm volatile("s_waitcnt lgkmcnt(" #n ")" ::: "memory")
; #define BAR __builtin_amdgcn_s_barrier()
; template <bool OVL, bool PANEL = false, class Epi>
; __device__ __forceinline__ void gemm_phase(const bf16_t* __restrict__ A, long lda, const bf16_t* __restrict__ Bt, long ldb, int nM, int nN, int K,
;                                            const Epi& epi, bf16_t* shm, int w0) {
;     ...
;       LDA(At, 1, 1); BAR; WAIT_L(0); MMA(1, 0, At, B0); MMA(1, 1, At, B1); BAR; }
	v_mfma_f32_16x16x32_bf16 v[30:33], v[148:151], v[164:167], v[30:33]
	v_mfma_f32_16x16x32_bf16 v[26:29], v[200:203], v[164:167], v[26:29]
	v_mfma_f32_16x16x32_bf16 v[22:25], v[148:151], v[172:175], v[22:25]
	v_mfma_f32_16x16x32_bf16 v[18:21], v[200:203], v[172:175], v[18:21]
	v_mfma_f32_16x16x32_bf16 v[14:17], v[148:151], v[180:183], v[14:17]
	v_mfma_f32_16x16x32_bf16 v[10:13], v[200:203], v[180:183], v[10:13]
	v_mfma_f32_16x16x32_bf16 v[6:9], v[148:151], v[188:191], v[6:9]
	v_mfma_f32_16x16x32_bf16 v[2:5], v[200:203], v[188:191], v[2:5]
	v_mfma_f32_16x16x32_bf16 v[30:33], v[196:199], v[168:171], v[30:33]
	v_mfma_f32_16x16x32_bf16 v[26:29], v[204:207], v[168:171], v[26:29]
	v_mfma_f32_16x16x32_bf16 v[22:25], v[196:199], v[176:179], v[22:25]
	v_mfma_f32_16x16x32_bf16 v[18:21], v[204:207], v[176:179], v[18:21]
	v_mfma_f32_16x16x32_bf16 v[14:17], v[196:199], v[184:187], v[14:17]
	v_mfma_f32_16x16x32_bf16 v[10:13], v[204:207], v[184:187], v[10:13]
	v_mfma_f32_16x16x32_bf16 v[6:9], v[196:199], v[192:195], v[6:9]
	v_mfma_f32_16x16x32_bf16 v[2:5], v[204:207], v[192:195], v[2:5]

; #define LDA(dst, b, h) for (int m = 0; m < 4; ++m) for (int k = 0; k < 2; ++k) \
;     dst[m][k] = *reinterpret_cast<const bf16x8*>((char*)SA(b, h) + a_thr + (m * 2 + k) * 1024)
; #define MMA(ai, bj, At, Btf) do { __builtin_amdgcn_s_setprio(1); \
;     for (int m = 0; m < 4; ++m) for (int n = 0; n < 2; ++n) for (int k = 0; k < 2; ++k) \
;       acc[ai][bj][m][n] = __builtin_amdgcn_mfma_f32_16x16x32_bf16(Btf[n][k], At[m][k], acc[ai][bj][m][n], 0, 0, 0); \
;     __builtin_amdgcn_s_setprio(0); } while (0)
; #define WAIT_L(n) asm volatile("s_waitcnt lgkmcnt(" #n ")" ::: "memory")
; #define BAR __builtin_amdgcn_s_barrier()
; template <bool OVL, bool PANEL = false, class Epi>
; __device__ __forceinline__ void gemm_phase(const bf16_t* __restrict__ A, long lda, const bf16_t* __restrict__ Bt, long ldb, int nM, int nN, int K,
;                                            const Epi& epi, bf16_t* shm, int w0) {
;     ...
;       LDA(At, 1, 1); BAR; WAIT_L(0); MMA(1, 0, At, B0); MMA(1, 1, At, B1); BAR; }
;     if (wr == 0) BAR;
	s_barrier
	s_and_saveexec_b64 s[0:1], s[6:7]
	s_cbranch_execz .LBB0_413
	s_barrier

; #define LDA(dst, b, h) for (int m = 0; m < 4; ++m) for (int k = 0; k < 2; ++k) \
;     dst[m][k] = *reinterpret_cast<const bf16x8*>((char*)SA(b, h) + a_thr + (m * 2 + k) * 1024)
; #define LDB(dst, b, h) for (int n = 0; n < 2; ++n) for (int k = 0; k < 2; ++k) \
;     dst[n][k] = *reinterpret_cast<const bf16x8*>((char*)SB(b, h) + b_thr + (n * 2 + k) * 1024)
; #define MMA(ai, bj, At, Btf) do { __builtin_amdgcn_s_setprio(1); \
;     for (int m = 0; m < 4; ++m) for (int n = 0; n < 2; ++n) for (int k = 0; k < 2; ++k) \
;       acc[ai][bj][m][n] = __builtin_amdgcn_mfma_f32_16x16x32_bf16(Btf[n][k], At[m][k], acc[ai][bj][m][n], 0, 0, 0); \
;     __builtin_amdgcn_s_setprio(0); } while (0)
; #define WAIT_V(n) asm volatile("s_waitcnt vmcnt(" #n ")" ::: "memory")
; #define WAIT_L(n) asm volatile("s_waitcnt lgkmcnt(" #n ")" ::: "memory")
; #define BAR __builtin_amdgcn_s_barrier()
; #define SCHED __builtin_amdgcn_sched_barrier(0)
; template <bool OVL, bool PANEL = false, class Epi>
; __device__ __forceinline__ void gemm_phase(const bf16_t* __restrict__ A, long lda, const bf16_t* __restrict__ Bt, long ldb, int nM, int nN, int K,
;                                            const Epi& epi, bf16_t* shm, int w0) {
;     ...
;     for (int t = 0; t < nt - 2; t += 2) {
;       LDB(B0, 0, 0); SCHED; LDA(At, 0, 0); STAGE(SA(1, 1), A, lda, aoff, brow + HALF, t + 1);
;       WAIT_L(8); BAR; WAIT_L(0); MMA(0, 0, At, B0); BAR; SCHED;
;       LDB(B1, 0, 1); STAGE(SB(0, 0), Bt, ldb, boff, bcol, t + 2);
;       BAR; WAIT_L(0); MMA(0, 1, At, B1); BAR;
;       LDA(At, 0, 1); STAGE(SA(0, 0), A, lda, aoff, brow, t + 2);
;       BAR; WAIT_L(0); MMA(1, 0, At, B0); BAR; SCHED;
;       STAGE(SB(0, 1), Bt, ldb, boff, bcol + HALF, t + 2);
;       WAIT_V(6); BAR; MMA(1, 1, At, B1); BAR;
.LBB0_472:
	ds_read_b128 v[138:141], v206
	ds_read_b128 v[142:145], v206 offset:1024
	ds_read_b128 v[146:149], v206 offset:2048
	ds_read_b128 v[150:153], v206 offset:3072
	s_add_u32 vcc_lo, s8, s80
	s_addc_u32 vcc_hi, s9, s81
	ds_read_b128 v[154:157], v241
	ds_read_b128 v[158:161], v241 offset:1024
	ds_read_b128 v[162:165], v241 offset:2048
	ds_read_b128 v[166:169], v241 offset:3072
	ds_read_b128 v[170:173], v241 offset:4096
	ds_read_b128 v[174:177], v241 offset:5120
	ds_read_b128 v[178:181], v241 offset:6144
	ds_read_b128 v[182:185], v241 offset:7168
	s_mov_b32 m0, s16
	s_add_u32 s98, vcc_lo, s12
	s_addc_u32 s99, vcc_hi, s13
	global_load_lds_dwordx4 v221, s[98:99]
	s_mov_b32 m0, s32
	s_add_u32 s98, vcc_lo, s36
	s_addc_u32 s99, vcc_hi, s37
	global_load_lds_dwordx4 v221, s[98:99]
	s_waitcnt lgkmcnt(8)
	s_waitcnt vmcnt(10)
	s_barrier
	s_waitcnt lgkmcnt(0)
	s_waitcnt lgkmcnt(0)
	v_mfma_f32_16x16x32_bf16 v[126:129], v[138:141], v[154:157], v[126:129]
	v_mfma_f32_16x16x32_bf16 v[122:125], v[146:149], v[154:157], v[122:125]
	v_mfma_f32_16x16x32_bf16 v[118:121], v[138:141], v[162:165], v[118:121]
	v_mfma_f32_16x16x32_bf16 v[114:117], v[146:149], v[162:165], v[114:117]
	v_mfma_f32_16x16x32_bf16 v[110:113], v[138:141], v[170:173], v[110:113]
	v_mfma_f32_16x16x32_bf16 v[106:109], v[146:149], v[170:173], v[106:109]
	v_mfma_f32_16x16x32_bf16 v[102:105], v[138:141], v[178:181], v[102:105]
	v_mfma_f32_16x16x32_bf16 v[98:101], v[146:149], v[178:181], v[98:101]
	v_mfma_f32_16x16x32_bf16 v[126:129], v[142:145], v[158:161], v[126:129]
	v_mfma_f32_16x16x32_bf16 v[122:125], v[150:153], v[158:161], v[122:125]
	v_mfma_f32_16x16x32_bf16 v[118:121], v[142:145], v[166:169], v[118:121]
	v_mfma_f32_16x16x32_bf16 v[114:117], v[150:153], v[166:169], v[114:117]
	v_mfma_f32_16x16x32_bf16 v[110:113], v[142:145], v[174:177], v[110:113]
	v_mfma_f32_16x16x32_bf16 v[106:109], v[150:153], v[174:177], v[106:109]
	v_mfma_f32_16x16x32_bf16 v[102:105], v[142:145], v[182:185], v[102:105]
	v_mfma_f32_16x16x32_bf16 v[98:101], v[150:153], v[182:185], v[98:101]
	s_barrier
	s_add_u32 s0, s6, s80
	ds_read_b128 v[186:189], v207
	ds_read_b128 v[190:193], v207 offset:1024
	ds_read_b128 v[194:197], v207 offset:2048
	ds_read_b128 v[198:201], v207 offset:3072
	s_addc_u32 s1, s7, s81
	s_mov_b32 m0, s44
	s_add_u32 s98, s0, s34
	s_addc_u32 s99, s1, s35
	global_load_lds_dwordx4 v221, s[98:99]
	s_mov_b32 m0, s45
	s_add_u32 s98, s0, s64
	s_addc_u32 s99, s1, s65
	global_load_lds_dwordx4 v221, s[98:99]
	s_waitcnt vmcnt(10)
	s_barrier
	s_waitcnt lgkmcnt(0)
	s_waitcnt lgkmcnt(0)
	v_mfma_f32_16x16x32_bf16 v[94:97], v[186:189], v[154:157], v[94:97]
	v_mfma_f32_16x16x32_bf16 v[90:93], v[194:197], v[154:157], v[90:93]
	v_mfma_f32_16x16x32_bf16 v[86:89], v[186:189], v[162:165], v[86:89]
	v_mfma_f32_16x16x32_bf16 v[82:85], v[194:197], v[162:165], v[82:85]
	v_mfma_f32_16x16x32_bf16 v[78:81], v[186:189], v[170:173], v[78:81]
	v_mfma_f32_16x16x32_bf16 v[74:77], v[194:197], v[170:173], v[74:77]
	v_mfma_f32_16x16x32_bf16 v[70:73], v[186:189], v[178:181], v[70:73]
	v_mfma_f32_16x16x32_bf16 v[66:69], v[194:197], v[178:181], v[66:69]
	v_mfma_f32_16x16x32_bf16 v[94:97], v[190:193], v[158:161], v[94:97]
	v_mfma_f32_16x16x32_bf16 v[90:93], v[198:201], v[158:161], v[90:93]
	v_mfma_f32_16x16x32_bf16 v[86:89], v[190:193], v[166:169], v[86:89]
	v_mfma_f32_16x16x32_bf16 v[82:85], v[198:201], v[166:169], v[82:85]
	v_mfma_f32_16x16x32_bf16 v[78:81], v[190:193], v[174:177], v[78:81]
	v_mfma_f32_16x16x32_bf16 v[74:77], v[198:201], v[174:177], v[74:77]
	v_mfma_f32_16x16x32_bf16 v[70:73], v[190:193], v[182:185], v[70:73]
	v_mfma_f32_16x16x32_bf16 v[66:69], v[198:201], v[182:185], v[66:69]
	s_barrier
	ds_read_b128 v[154:157], v241 offset:16384
	ds_read_b128 v[158:161], v241 offset:17408
	ds_read_b128 v[162:165], v241 offset:18432
	ds_read_b128 v[166:169], v241 offset:19456
	ds_read_b128 v[170:173], v241 offset:20480
	ds_read_b128 v[174:177], v241 offset:21504
	ds_read_b128 v[178:181], v241 offset:22528
	ds_read_b128 v[182:185], v241 offset:23552
	s_mov_b32 m0, s46
	s_add_u32 s98, vcc_lo, s34
	s_addc_u32 s99, vcc_hi, s35
	global_load_lds_dwordx4 v221, s[98:99]
	s_mov_b32 m0, s47
	s_add_u32 s98, vcc_lo, s64
	s_addc_u32 s99, vcc_hi, s65
	global_load_lds_dwordx4 v221, s[98:99]
	s_barrier
	s_waitcnt lgkmcnt(0)
	s_waitcnt lgkmcnt(0)
	v_mfma_f32_16x16x32_bf16 v[62:65], v[138:141], v[154:157], v[62:65]
	v_mfma_f32_16x16x32_bf16 v[58:61], v[146:149], v[154:157], v[58:61]
	v_mfma_f32_16x16x32_bf16 v[54:57], v[138:141], v[162:165], v[54:57]
	v_mfma_f32_16x16x32_bf16 v[50:53], v[146:149], v[162:165], v[50:53]
	v_mfma_f32_16x16x32_bf16 v[46:49], v[138:141], v[170:173], v[46:49]
	v_mfma_f32_16x16x32_bf16 v[42:45], v[146:149], v[170:173], v[42:45]
	v_mfma_f32_16x16x32_bf16 v[38:41], v[138:141], v[178:181], v[38:41]
	v_mfma_f32_16x16x32_bf16 v[34:37], v[146:149], v[178:181], v[34:37]
	v_mfma_f32_16x16x32_bf16 v[62:65], v[142:145], v[158:161], v[62:65]
	v_mfma_f32_16x16x32_bf16 v[58:61], v[150:153], v[158:161], v[58:61]
	v_mfma_f32_16x16x32_bf16 v[54:57], v[142:145], v[166:169], v[54:57]
	v_mfma_f32_16x16x32_bf16 v[50:53], v[150:153], v[166:169], v[50:53]
	v_mfma_f32_16x16x32_bf16 v[46:49], v[142:145], v[174:177], v[46:49]
	v_mfma_f32_16x16x32_bf16 v[42:45], v[150:153], v[174:177], v[42:45]
	v_mfma_f32_16x16x32_bf16 v[38:41], v[142:145], v[182:185], v[38:41]
	v_mfma_f32_16x16x32_bf16 v[34:37], v[150:153], v[182:185], v[34:37]
	s_barrier
	s_mov_b32 m0, s48
	s_add_u32 s98, s0, s68
	s_addc_u32 s99, s1, s69
	global_load_lds_dwordx4 v221, s[98:99]
	s_mov_b32 m0, s49
	s_add_u32 s98, s0, s70
	s_addc_u32 s99, s1, s71
	global_load_lds_dwordx4 v221, s[98:99]
	s_waitcnt vmcnt(10)
	s_barrier
; #define LDA(dst, b, h) for (int m = 0; m < 4; ++m) for (int k = 0; k < 2; ++k) \
;     dst[m][k] = *reinterpret_cast<const bf16x8*>((char*)SA(b, h) + a_thr + (m * 2 + k) * 1024)
; #define LDB(dst, b, h) for (int n = 0; n < 2; ++n) for (int k = 0; k < 2; ++k) \
;     dst[n][k] = *reinterpret_cast<const bf16x8*>((char*)SB(b, h) + b_thr + (n * 2 + k) * 1024)
; #define MMA(ai, bj, At, Btf) do { __builtin_amdgcn_s_setprio(1); \
;     for (int m = 0; m < 4; ++m) for (int n = 0; n < 2; ++n) for (int k = 0; k < 2; ++k) \
;       acc[ai][bj][m][n] = __builtin_amdgcn_mfma_f32_16x16x32_bf16(Btf[n][k], At[m][k], acc[ai][bj][m][n], 0, 0, 0); \
;     __builtin_amdgcn_s_setprio(0); } while (0)
; #define WAIT_V(n) asm volatile("s_waitcnt vmcnt(" #n ")" ::: "memory")
; #define WAIT_L(n) asm volatile("s_waitcnt lgkmcnt(" #n ")" ::: "memory")
; #define BAR __builtin_amdgcn_s_barrier()
; #define SCHED __builtin_amdgcn_sched_barrier(0)
; template <bool OVL, bool PANEL = false, class Epi>
; __device__ __forceinline__ void gemm_phase(const bf16_t* __restrict__ A, long lda, const bf16_t* __restrict__ Bt, long ldb, int nM, int nN, int K,
;                                            const Epi& epi, bf16_t* shm, int w0) {
;     ...
;       WAIT_V(6); BAR; MMA(1, 1, At, B1); BAR;
;       LDB(B0, 1, 0); SCHED; LDA(At, 1, 0); STAGE(SA(0, 1), A, lda, aoff, brow + HALF, t + 2);
;       WAIT_L(8); BAR; WAIT_L(0); MMA(0, 0, At, B0); BAR; SCHED;
;       LDB(B1, 1, 1); STAGE(SB(1, 0), Bt, ldb, boff, bcol, t + 3);
;       BAR; WAIT_L(0); MMA(0, 1, At, B1); BAR;
	v_mfma_f32_16x16x32_bf16 v[30:33], v[186:189], v[154:157], v[30:33]
	v_mfma_f32_16x16x32_bf16 v[26:29], v[194:197], v[154:157], v[26:29]
	v_mfma_f32_16x16x32_bf16 v[22:25], v[186:189], v[162:165], v[22:25]
	v_mfma_f32_16x16x32_bf16 v[18:21], v[194:197], v[162:165], v[18:21]
	v_mfma_f32_16x16x32_bf16 v[14:17], v[186:189], v[170:173], v[14:17]
	v_mfma_f32_16x16x32_bf16 v[10:13], v[194:197], v[170:173], v[10:13]
	v_mfma_f32_16x16x32_bf16 v[6:9], v[186:189], v[178:181], v[6:9]
	v_mfma_f32_16x16x32_bf16 v[2:5], v[194:197], v[178:181], v[2:5]
	v_mfma_f32_16x16x32_bf16 v[30:33], v[190:193], v[158:161], v[30:33]
	v_mfma_f32_16x16x32_bf16 v[26:29], v[198:201], v[158:161], v[26:29]
	v_mfma_f32_16x16x32_bf16 v[22:25], v[190:193], v[166:169], v[22:25]
	v_mfma_f32_16x16x32_bf16 v[18:21], v[198:201], v[166:169], v[18:21]
	v_mfma_f32_16x16x32_bf16 v[14:17], v[190:193], v[174:177], v[14:17]
	v_mfma_f32_16x16x32_bf16 v[10:13], v[198:201], v[174:177], v[10:13]
	v_mfma_f32_16x16x32_bf16 v[6:9], v[190:193], v[182:185], v[6:9]
	v_mfma_f32_16x16x32_bf16 v[2:5], v[198:201], v[182:185], v[2:5]
	s_barrier
	ds_read_b128 v[138:141], v208
	ds_read_b128 v[142:145], v208 offset:1024
	ds_read_b128 v[146:149], v208 offset:2048
	ds_read_b128 v[150:153], v208 offset:3072
	ds_read_b128 v[154:157], v241 offset:32768
	ds_read_b128 v[158:161], v241 offset:33792
	ds_read_b128 v[162:165], v241 offset:34816
	ds_read_b128 v[166:169], v241 offset:35840
	ds_read_b128 v[170:173], v241 offset:36864
	ds_read_b128 v[174:177], v241 offset:37888
	ds_read_b128 v[178:181], v241 offset:38912
	ds_read_b128 v[182:185], v241 offset:39936
	s_mov_b32 m0, s50
	s_add_u32 s98, vcc_lo, s68
	s_addc_u32 s99, vcc_hi, s69
	global_load_lds_dwordx4 v221, s[98:99]
	s_mov_b32 m0, s51
	s_add_u32 s98, vcc_lo, s70
	s_addc_u32 s99, vcc_hi, s71
	global_load_lds_dwordx4 v221, s[98:99]
	s_waitcnt lgkmcnt(8)
	s_waitcnt vmcnt(10)
	s_barrier
	s_waitcnt lgkmcnt(0)
	s_waitcnt lgkmcnt(0)
	v_mfma_f32_16x16x32_bf16 v[126:129], v[138:141], v[154:157], v[126:129]
	v_mfma_f32_16x16x32_bf16 v[122:125], v[146:149], v[154:157], v[122:125]
	v_mfma_f32_16x16x32_bf16 v[118:121], v[138:141], v[162:165], v[118:121]
	v_mfma_f32_16x16x32_bf16 v[114:117], v[146:149], v[162:165], v[114:117]
	v_mfma_f32_16x16x32_bf16 v[110:113], v[138:141], v[170:173], v[110:113]
	v_mfma_f32_16x16x32_bf16 v[106:109], v[146:149], v[170:173], v[106:109]
	v_mfma_f32_16x16x32_bf16 v[102:105], v[138:141], v[178:181], v[102:105]
	v_mfma_f32_16x16x32_bf16 v[98:101], v[146:149], v[178:181], v[98:101]
	v_mfma_f32_16x16x32_bf16 v[126:129], v[142:145], v[158:161], v[126:129]
	v_mfma_f32_16x16x32_bf16 v[122:125], v[150:153], v[158:161], v[122:125]
	v_mfma_f32_16x16x32_bf16 v[118:121], v[142:145], v[166:169], v[118:121]
	v_mfma_f32_16x16x32_bf16 v[114:117], v[150:153], v[166:169], v[114:117]
	v_mfma_f32_16x16x32_bf16 v[110:113], v[142:145], v[174:177], v[110:113]
	v_mfma_f32_16x16x32_bf16 v[106:109], v[150:153], v[174:177], v[106:109]
	v_mfma_f32_16x16x32_bf16 v[102:105], v[142:145], v[182:185], v[102:105]
	v_mfma_f32_16x16x32_bf16 v[98:101], v[150:153], v[182:185], v[98:101]
	s_barrier
	ds_read_b128 v[186:189], v209
	ds_read_b128 v[190:193], v209 offset:1024
	ds_read_b128 v[194:197], v209 offset:2048
	ds_read_b128 v[198:201], v209 offset:3072
	s_mov_b32 m0, s52
	s_add_u32 s98, s0, s94
	s_addc_u32 s99, s1, s95
	global_load_lds_dwordx4 v221, s[98:99]
	s_mov_b32 m0, s53
	s_add_u32 s98, s0, s72
	s_addc_u32 s99, s1, s73
	global_load_lds_dwordx4 v221, s[98:99]
	s_waitcnt vmcnt(10)
	s_barrier
	s_waitcnt lgkmcnt(0)
	s_waitcnt lgkmcnt(0)
	v_mfma_f32_16x16x32_bf16 v[94:97], v[186:189], v[154:157], v[94:97]
	v_mfma_f32_16x16x32_bf16 v[90:93], v[194:197], v[154:157], v[90:93]
	v_mfma_f32_16x16x32_bf16 v[86:89], v[186:189], v[162:165], v[86:89]
	v_mfma_f32_16x16x32_bf16 v[82:85], v[194:197], v[162:165], v[82:85]
	v_mfma_f32_16x16x32_bf16 v[78:81], v[186:189], v[170:173], v[78:81]
	v_mfma_f32_16x16x32_bf16 v[74:77], v[194:197], v[170:173], v[74:77]
	v_mfma_f32_16x16x32_bf16 v[70:73], v[186:189], v[178:181], v[70:73]
	v_mfma_f32_16x16x32_bf16 v[66:69], v[194:197], v[178:181], v[66:69]
	v_mfma_f32_16x16x32_bf16 v[94:97], v[190:193], v[158:161], v[94:97]
	v_mfma_f32_16x16x32_bf16 v[90:93], v[198:201], v[158:161], v[90:93]
	v_mfma_f32_16x16x32_bf16 v[86:89], v[190:193], v[166:169], v[86:89]
	v_mfma_f32_16x16x32_bf16 v[82:85], v[198:201], v[166:169], v[82:85]
	v_mfma_f32_16x16x32_bf16 v[78:81], v[190:193], v[174:177], v[78:81]
	v_mfma_f32_16x16x32_bf16 v[74:77], v[198:201], v[174:177], v[74:77]
	v_mfma_f32_16x16x32_bf16 v[70:73], v[190:193], v[182:185], v[70:73]
	v_mfma_f32_16x16x32_bf16 v[66:69], v[198:201], v[182:185], v[66:69]
	s_barrier
; #define LDA(dst, b, h) for (int m = 0; m < 4; ++m) for (int k = 0; k < 2; ++k) \
;     dst[m][k] = *reinterpret_cast<const bf16x8*>((char*)SA(b, h) + a_thr + (m * 2 + k) * 1024)
; #define LDB(dst, b, h) for (int n = 0; n < 2; ++n) for (int k = 0; k < 2; ++k) \
;     dst[n][k] = *reinterpret_cast<const bf16x8*>((char*)SB(b, h) + b_thr + (n * 2 + k) * 1024)
; #define MMA(ai, bj, At, Btf) do { __builtin_amdgcn_s_setprio(1); \
;     for (int m = 0; m < 4; ++m) for (int n = 0; n < 2; ++n) for (int k = 0; k < 2; ++k) \
;       acc[ai][bj][m][n] = __builtin_amdgcn_mfma_f32_16x16x32_bf16(Btf[n][k], At[m][k], acc[ai][bj][m][n], 0, 0, 0); \
;     __builtin_amdgcn_s_setprio(0); } while (0)
; #define WAIT_V(n) asm volatile("s_waitcnt vmcnt(" #n ")" ::: "memory")
; #define WAIT_L(n) asm volatile("s_waitcnt lgkmcnt(" #n ")" ::: "memory")
; #define BAR __builtin_amdgcn_s_barrier()
; #define SCHED __builtin_amdgcn_sched_barrier(0)
; template <bool OVL, bool PANEL = false, class Epi>
; __device__ __forceinline__ void gemm_phase(const bf16_t* __restrict__ A, long lda, const bf16_t* __restrict__ Bt, long ldb, int nM, int nN, int K,
;                                            const Epi& epi, bf16_t* shm, int w0) {
;     ...
;       LDA(At, 1, 1); STAGE(SA(1, 0), A, lda, aoff, brow, t + 3);
;       BAR; WAIT_L(0); MMA(1, 0, At, B0); BAR; SCHED;
;       STAGE(SB(1, 1), Bt, ldb, boff, bcol + HALF, t + 3);
;       WAIT_V(6); BAR; MMA(1, 1, At, B1); BAR;
;     }
;     { LDB(B0, 0, 0); LDA(At, 0, 0); STAGE(SA(1, 1), A, lda, aoff, brow + HALF, nt - 1);
;       BAR; WAIT_L(0); MMA(0, 0, At, B0); BAR;
	ds_read_b128 v[154:157], v241 offset:49152
	ds_read_b128 v[158:161], v241 offset:50176
	ds_read_b128 v[162:165], v241 offset:51200
	ds_read_b128 v[166:169], v241 offset:52224
	ds_read_b128 v[170:173], v241 offset:53248
	ds_read_b128 v[174:177], v241 offset:54272
	ds_read_b128 v[178:181], v241 offset:55296
	ds_read_b128 v[182:185], v241 offset:56320
	s_mov_b32 m0, s54
	s_add_u32 s98, vcc_lo, s94
	s_addc_u32 s99, vcc_hi, s95
	global_load_lds_dwordx4 v221, s[98:99]
	s_mov_b32 m0, s55
	s_add_u32 s98, vcc_lo, s72
	s_addc_u32 s99, vcc_hi, s73
	global_load_lds_dwordx4 v221, s[98:99]
	s_barrier
	s_waitcnt lgkmcnt(0)
	s_waitcnt lgkmcnt(0)
	v_mfma_f32_16x16x32_bf16 v[62:65], v[138:141], v[154:157], v[62:65]
	v_mfma_f32_16x16x32_bf16 v[58:61], v[146:149], v[154:157], v[58:61]
	v_mfma_f32_16x16x32_bf16 v[54:57], v[138:141], v[162:165], v[54:57]
	v_mfma_f32_16x16x32_bf16 v[50:53], v[146:149], v[162:165], v[50:53]
	v_mfma_f32_16x16x32_bf16 v[46:49], v[138:141], v[170:173], v[46:49]
	v_mfma_f32_16x16x32_bf16 v[42:45], v[146:149], v[170:173], v[42:45]
	v_mfma_f32_16x16x32_bf16 v[38:41], v[138:141], v[178:181], v[38:41]
	v_mfma_f32_16x16x32_bf16 v[34:37], v[146:149], v[178:181], v[34:37]
	v_mfma_f32_16x16x32_bf16 v[62:65], v[142:145], v[158:161], v[62:65]
	v_mfma_f32_16x16x32_bf16 v[58:61], v[150:153], v[158:161], v[58:61]
	v_mfma_f32_16x16x32_bf16 v[54:57], v[142:145], v[166:169], v[54:57]
	v_mfma_f32_16x16x32_bf16 v[50:53], v[150:153], v[166:169], v[50:53]
	v_mfma_f32_16x16x32_bf16 v[46:49], v[142:145], v[174:177], v[46:49]
	v_mfma_f32_16x16x32_bf16 v[42:45], v[150:153], v[174:177], v[42:45]
	v_mfma_f32_16x16x32_bf16 v[38:41], v[142:145], v[182:185], v[38:41]
	v_mfma_f32_16x16x32_bf16 v[34:37], v[150:153], v[182:185], v[34:37]
	s_barrier
	s_mov_b32 m0, s56
	s_add_u32 s98, s0, s14
	s_addc_u32 s99, s1, s15
	global_load_lds_dwordx4 v221, s[98:99]
	s_mov_b32 m0, s57
	s_add_u32 s98, s0, s18
	s_addc_u32 s99, s1, s19
	global_load_lds_dwordx4 v221, s[98:99]
	s_add_i32 s2, s2, 2
	s_add_u32 s80, s80, 0x100
	s_addc_u32 s81, s81, 0
	s_cmp_gt_u32 s2, 11
	s_waitcnt vmcnt(10)
	s_barrier
	v_mfma_f32_16x16x32_bf16 v[30:33], v[186:189], v[154:157], v[30:33]
	v_mfma_f32_16x16x32_bf16 v[26:29], v[194:197], v[154:157], v[26:29]
	v_mfma_f32_16x16x32_bf16 v[22:25], v[186:189], v[162:165], v[22:25]
	v_mfma_f32_16x16x32_bf16 v[18:21], v[194:197], v[162:165], v[18:21]
	v_mfma_f32_16x16x32_bf16 v[14:17], v[186:189], v[170:173], v[14:17]
	v_mfma_f32_16x16x32_bf16 v[10:13], v[194:197], v[170:173], v[10:13]
	v_mfma_f32_16x16x32_bf16 v[6:9], v[186:189], v[178:181], v[6:9]
	v_mfma_f32_16x16x32_bf16 v[2:5], v[194:197], v[178:181], v[2:5]
	v_mfma_f32_16x16x32_bf16 v[30:33], v[190:193], v[158:161], v[30:33]
	v_mfma_f32_16x16x32_bf16 v[26:29], v[198:201], v[158:161], v[26:29]
	v_mfma_f32_16x16x32_bf16 v[22:25], v[190:193], v[166:169], v[22:25]
	v_mfma_f32_16x16x32_bf16 v[18:21], v[198:201], v[166:169], v[18:21]
	v_mfma_f32_16x16x32_bf16 v[14:17], v[190:193], v[174:177], v[14:17]
	v_mfma_f32_16x16x32_bf16 v[10:13], v[198:201], v[174:177], v[10:13]
	v_mfma_f32_16x16x32_bf16 v[6:9], v[190:193], v[182:185], v[6:9]
	v_mfma_f32_16x16x32_bf16 v[2:5], v[198:201], v[182:185], v[2:5]
	s_barrier
	s_cbranch_scc0 .LBB0_472
	s_waitcnt vmcnt(6)
	s_or_b32 s0, s82, 0x80
	s_ashr_i32 s1, s0, 31
	v_readlane_b32 s44, v252, 20
	s_lshl_b64 s[0:1], s[0:1], 11
	v_readlane_b32 s50, v252, 26
	v_add_u32_e32 v206, 16, v240
	v_readlane_b32 s51, v252, 27
	s_add_u32 s0, s50, s0
	v_add_u32_e32 v0, 0x10000, v206
	s_addc_u32 s1, s51, s1
	ds_read_b128 v[130:133], v0
	ds_read_b128 v[138:141], v0 offset:1024
	ds_read_b128 v[142:145], v0 offset:2048
	ds_read_b128 v[146:149], v0 offset:3072
	ds_read_b128 v[150:153], v241
	ds_read_b128 v[154:157], v241 offset:1024
	ds_read_b128 v[158:161], v241 offset:2048
	ds_read_b128 v[162:165], v241 offset:3072
	ds_read_b128 v[166:169], v241 offset:4096
	ds_read_b128 v[170:173], v241 offset:5120
	ds_read_b128 v[174:177], v241 offset:6144
	ds_read_b128 v[178:181], v241 offset:7168
	v_mov_b32_e32 v0, v221
	v_readlane_b32 s45, v252, 21
	v_lshl_add_u64 v[134:135], s[0:1], 0, v[0:1]
	s_mov_b64 s[0:1], 0x780
	v_lshl_add_u64 v[182:183], v[134:135], 0, s[0:1]
	v_readfirstlane_b32 s0, v136
	s_mov_b32 m0, s0
	s_mov_b64 s[0:1], 0x20780
	v_lshl_add_u64 v[134:135], v[134:135], 0, s[0:1]
	v_readfirstlane_b32 s0, v137
	global_load_lds_dwordx4 v[182:183], off
	s_mov_b32 m0, s0
	v_readlane_b32 s46, v252, 22
	global_load_lds_dwordx4 v[134:135], off
	s_barrier
	s_waitcnt lgkmcnt(0)
	v_readlane_b32 s47, v252, 23
	v_readlane_b32 s48, v252, 24
	v_readlane_b32 s49, v252, 25
	v_readlane_b32 s52, v252, 28
	v_readlane_b32 s53, v252, 29
	v_readlane_b32 s54, v252, 30
	v_readlane_b32 s55, v252, 31
	v_readlane_b32 s56, v252, 32
	v_readlane_b32 s57, v252, 33
	v_readlane_b32 s58, v252, 34
	v_readlane_b32 s59, v252, 35

; #define MMA(ai, bj, At, Btf) do { __builtin_amdgcn_s_setprio(1); \
;     for (int m = 0; m < 4; ++m) for (int n = 0; n < 2; ++n) for (int k = 0; k < 2; ++k) \
;       acc[ai][bj][m][n] = __builtin_amdgcn_mfma_f32_16x16x32_bf16(Btf[n][k], At[m][k], acc[ai][bj][m][n], 0, 0, 0); \
;     __builtin_amdgcn_s_setprio(0); } while (0)
; #define WAIT_L(n) asm volatile("s_waitcnt lgkmcnt(" #n ")" ::: "memory")
; #define BAR __builtin_amdgcn_s_barrier()
; template <bool OVL, bool PANEL = false, class Epi>
; __device__ __forceinline__ void gemm_phase(const bf16_t* __restrict__ A, long lda, const bf16_t* __restrict__ Bt, long ldb, int nM, int nN, int K,
;                                            const Epi& epi, bf16_t* shm, int w0) {
;     ...
;       BAR; WAIT_L(0); MMA(0, 0, At, B0); BAR;
	s_waitcnt lgkmcnt(0)
	v_mfma_f32_16x16x32_bf16 v[126:129], v[130:133], v[150:153], v[126:129]
	v_mfma_f32_16x16x32_bf16 v[122:125], v[142:145], v[150:153], v[122:125]
	v_mfma_f32_16x16x32_bf16 v[118:121], v[130:133], v[158:161], v[118:121]
	v_mfma_f32_16x16x32_bf16 v[114:117], v[142:145], v[158:161], v[114:117]
	v_mfma_f32_16x16x32_bf16 v[106:109], v[142:145], v[166:169], v[106:109]
	v_mfma_f32_16x16x32_bf16 v[102:105], v[130:133], v[174:177], v[102:105]
	v_mfma_f32_16x16x32_bf16 v[98:101], v[142:145], v[174:177], v[98:101]
	v_mfma_f32_16x16x32_bf16 v[126:129], v[138:141], v[154:157], v[126:129]
	v_mfma_f32_16x16x32_bf16 v[122:125], v[146:149], v[154:157], v[122:125]
	v_mfma_f32_16x16x32_bf16 v[118:121], v[138:141], v[162:165], v[118:121]
	v_mfma_f32_16x16x32_bf16 v[114:117], v[146:149], v[162:165], v[114:117]
	v_mfma_f32_16x16x32_bf16 v[110:113], v[130:133], v[166:169], v[110:113]
	v_mfma_f32_16x16x32_bf16 v[106:109], v[146:149], v[170:173], v[106:109]
	v_mfma_f32_16x16x32_bf16 v[102:105], v[138:141], v[178:181], v[102:105]
	v_mfma_f32_16x16x32_bf16 v[98:101], v[146:149], v[178:181], v[98:101]
	v_mfma_f32_16x16x32_bf16 v[134:137], v[138:141], v[170:173], v[110:113]

; #define LDB(dst, b, h) for (int n = 0; n < 2; ++n) for (int k = 0; k < 2; ++k) \
;     dst[n][k] = *reinterpret_cast<const bf16x8*>((char*)SB(b, h) + b_thr + (n * 2 + k) * 1024)
; #define MMA(ai, bj, At, Btf) do { __builtin_amdgcn_s_setprio(1); \
;     for (int m = 0; m < 4; ++m) for (int n = 0; n < 2; ++n) for (int k = 0; k < 2; ++k) \
;       acc[ai][bj][m][n] = __builtin_amdgcn_mfma_f32_16x16x32_bf16(Btf[n][k], At[m][k], acc[ai][bj][m][n], 0, 0, 0); \
;     __builtin_amdgcn_s_setprio(0); } while (0)
; #define WAIT_L(n) asm volatile("s_waitcnt lgkmcnt(" #n ")" ::: "memory")
; #define BAR __builtin_amdgcn_s_barrier()
; template <bool OVL, bool PANEL = false, class Epi>
; __device__ __forceinline__ void gemm_phase(const bf16_t* __restrict__ A, long lda, const bf16_t* __restrict__ Bt, long ldb, int nM, int nN, int K,
;                                            const Epi& epi, bf16_t* shm, int w0) {
;     ...
;       LDB(B1, 0, 1); BAR; WAIT_L(0); MMA(0, 1, At, B1); BAR;
	v_add_u32_e32 v0, 0x14000, v206
	s_barrier
	s_nop 0
	ds_read_b128 v[110:113], v0
	ds_read_b128 v[182:185], v0 offset:1024
	ds_read_b128 v[186:189], v0 offset:2048
	ds_read_b128 v[190:193], v0 offset:3072
	s_barrier
	s_waitcnt lgkmcnt(0)

; #define LDB(dst, b, h) for (int n = 0; n < 2; ++n) for (int k = 0; k < 2; ++k) \
;     dst[n][k] = *reinterpret_cast<const bf16x8*>((char*)SB(b, h) + b_thr + (n * 2 + k) * 1024)
; #define MMA(ai, bj, At, Btf) do { __builtin_amdgcn_s_setprio(1); \
;     for (int m = 0; m < 4; ++m) for (int n = 0; n < 2; ++n) for (int k = 0; k < 2; ++k) \
;       acc[ai][bj][m][n] = __builtin_amdgcn_mfma_f32_16x16x32_bf16(Btf[n][k], At[m][k], acc[ai][bj][m][n], 0, 0, 0); \
;     __builtin_amdgcn_s_setprio(0); } while (0)
; #define WAIT_L(n) asm volatile("s_waitcnt lgkmcnt(" #n ")" ::: "memory")
; #define BAR __builtin_amdgcn_s_barrier()
; template <bool OVL, bool PANEL = false, class Epi>
; __device__ __forceinline__ void gemm_phase(const bf16_t* __restrict__ A, long lda, const bf16_t* __restrict__ Bt, long ldb, int nM, int nN, int K,
;                                            const Epi& epi, bf16_t* shm, int w0) {
;     ...
;       LDB(B1, 0, 1); BAR; WAIT_L(0); MMA(0, 1, At, B1); BAR;
	s_waitcnt lgkmcnt(0)
	v_mfma_f32_16x16x32_bf16 v[90:93], v[186:189], v[150:153], v[90:93]
	v_mfma_f32_16x16x32_bf16 v[74:77], v[186:189], v[166:169], v[74:77]
	v_mfma_f32_16x16x32_bf16 v[70:73], v[110:113], v[174:177], v[70:73]
	v_mfma_f32_16x16x32_bf16 v[66:69], v[186:189], v[174:177], v[66:69]
	v_mfma_f32_16x16x32_bf16 v[94:97], v[110:113], v[150:153], v[94:97]
	v_mfma_f32_16x16x32_bf16 v[90:93], v[190:193], v[154:157], v[90:93]
	v_mfma_f32_16x16x32_bf16 v[86:89], v[110:113], v[158:161], v[86:89]
	v_mfma_f32_16x16x32_bf16 v[82:85], v[186:189], v[158:161], v[82:85]
	v_mfma_f32_16x16x32_bf16 v[78:81], v[110:113], v[166:169], v[78:81]
	v_mfma_f32_16x16x32_bf16 v[74:77], v[190:193], v[170:173], v[74:77]
	v_mfma_f32_16x16x32_bf16 v[70:73], v[182:185], v[178:181], v[70:73]
	v_mfma_f32_16x16x32_bf16 v[66:69], v[190:193], v[178:181], v[66:69]
	v_mfma_f32_16x16x32_bf16 v[194:197], v[182:185], v[154:157], v[94:97]
	v_mfma_f32_16x16x32_bf16 v[150:153], v[182:185], v[162:165], v[86:89]
	v_mfma_f32_16x16x32_bf16 v[154:157], v[190:193], v[162:165], v[82:85]
	v_mfma_f32_16x16x32_bf16 v[158:161], v[182:185], v[170:173], v[78:81]

; #define LDA(dst, b, h) for (int m = 0; m < 4; ++m) for (int k = 0; k < 2; ++k) \
;     dst[m][k] = *reinterpret_cast<const bf16x8*>((char*)SA(b, h) + a_thr + (m * 2 + k) * 1024)
; #define MMA(ai, bj, At, Btf) do { __builtin_amdgcn_s_setprio(1); \
;     for (int m = 0; m < 4; ++m) for (int n = 0; n < 2; ++n) for (int k = 0; k < 2; ++k) \
;       acc[ai][bj][m][n] = __builtin_amdgcn_mfma_f32_16x16x32_bf16(Btf[n][k], At[m][k], acc[ai][bj][m][n], 0, 0, 0); \
;     __builtin_amdgcn_s_setprio(0); } while (0)
; #define WAIT_V(n) asm volatile("s_waitcnt vmcnt(" #n ")" ::: "memory")
; #define WAIT_L(n) asm volatile("s_waitcnt lgkmcnt(" #n ")" ::: "memory")
; #define BAR __builtin_amdgcn_s_barrier()
; template <bool OVL, bool PANEL = false, class Epi>
; __device__ __forceinline__ void gemm_phase(const bf16_t* __restrict__ A, long lda, const bf16_t* __restrict__ Bt, long ldb, int nM, int nN, int K,
;                                            const Epi& epi, bf16_t* shm, int w0) {
;     ...
;       LDA(At, 0, 1); WAIT_V(4); BAR; WAIT_L(0); MMA(1, 0, At, B0); MMA(1, 1, At, B1); BAR; }
	s_barrier
	s_nop 0
	ds_read_b128 v[78:81], v241 offset:16384
	ds_read_b128 v[82:85], v241 offset:17408
	ds_read_b128 v[86:89], v241 offset:18432
	ds_read_b128 v[94:97], v241 offset:19456
	ds_read_b128 v[162:165], v241 offset:20480
	ds_read_b128 v[166:169], v241 offset:21504
	ds_read_b128 v[170:173], v241 offset:22528
	ds_read_b128 v[174:177], v241 offset:23552
	s_waitcnt vmcnt(4)
	s_barrier
	s_waitcnt lgkmcnt(0)

; #define LDA(dst, b, h) for (int m = 0; m < 4; ++m) for (int k = 0; k < 2; ++k) \
;     dst[m][k] = *reinterpret_cast<const bf16x8*>((char*)SA(b, h) + a_thr + (m * 2 + k) * 1024)
; #define MMA(ai, bj, At, Btf) do { __builtin_amdgcn_s_setprio(1); \
;     for (int m = 0; m < 4; ++m) for (int n = 0; n < 2; ++n) for (int k = 0; k < 2; ++k) \
;       acc[ai][bj][m][n] = __builtin_amdgcn_mfma_f32_16x16x32_bf16(Btf[n][k], At[m][k], acc[ai][bj][m][n], 0, 0, 0); \
;     __builtin_amdgcn_s_setprio(0); } while (0)
; #define WAIT_V(n) asm volatile("s_waitcnt vmcnt(" #n ")" ::: "memory")
; #define WAIT_L(n) asm volatile("s_waitcnt lgkmcnt(" #n ")" ::: "memory")
; #define BAR __builtin_amdgcn_s_barrier()
; template <bool OVL, bool PANEL = false, class Epi>
; __device__ __forceinline__ void gemm_phase(const bf16_t* __restrict__ A, long lda, const bf16_t* __restrict__ Bt, long ldb, int nM, int nN, int K,
;                                            const Epi& epi, bf16_t* shm, int w0) {
;     ...
;       LDA(At, 0, 1); WAIT_V(4); BAR; WAIT_L(0); MMA(1, 0, At, B0); MMA(1, 1, At, B1); BAR; }
	s_waitcnt lgkmcnt(0)
	v_mfma_f32_16x16x32_bf16 v[62:65], v[130:133], v[78:81], v[62:65]
	v_mfma_f32_16x16x32_bf16 v[58:61], v[142:145], v[78:81], v[58:61]
	v_mfma_f32_16x16x32_bf16 v[54:57], v[130:133], v[86:89], v[54:57]
	v_mfma_f32_16x16x32_bf16 v[50:53], v[142:145], v[86:89], v[50:53]
	v_mfma_f32_16x16x32_bf16 v[46:49], v[130:133], v[162:165], v[46:49]
	v_mfma_f32_16x16x32_bf16 v[42:45], v[142:145], v[162:165], v[42:45]
	v_mfma_f32_16x16x32_bf16 v[34:37], v[142:145], v[170:173], v[34:37]
	v_mfma_f32_16x16x32_bf16 v[62:65], v[138:141], v[82:85], v[62:65]
	v_mfma_f32_16x16x32_bf16 v[58:61], v[146:149], v[82:85], v[58:61]
	v_mfma_f32_16x16x32_bf16 v[54:57], v[138:141], v[94:97], v[54:57]
	v_mfma_f32_16x16x32_bf16 v[50:53], v[146:149], v[94:97], v[50:53]
	v_mfma_f32_16x16x32_bf16 v[46:49], v[138:141], v[166:169], v[46:49]
	v_mfma_f32_16x16x32_bf16 v[42:45], v[146:149], v[166:169], v[42:45]
	v_mfma_f32_16x16x32_bf16 v[38:41], v[130:133], v[170:173], v[38:41]
	v_mfma_f32_16x16x32_bf16 v[34:37], v[146:149], v[174:177], v[34:37]
	v_mfma_f32_16x16x32_bf16 v[130:133], v[138:141], v[174:177], v[38:41]


; #define LDA(dst, b, h) for (int m = 0; m < 4; ++m) for (int k = 0; k < 2; ++k) \
;     dst[m][k] = *reinterpret_cast<const bf16x8*>((char*)SA(b, h) + a_thr + (m * 2 + k) * 1024)
; #define MMA(ai, bj, At, Btf) do { __builtin_amdgcn_s_setprio(1); \
;     for (int m = 0; m < 4; ++m) for (int n = 0; n < 2; ++n) for (int k = 0; k < 2; ++k) \
;       acc[ai][bj][m][n] = __builtin_amdgcn_mfma_f32_16x16x32_bf16(Btf[n][k], At[m][k], acc[ai][bj][m][n], 0, 0, 0); \
;     __builtin_amdgcn_s_setprio(0); } while (0)
; #define WAIT_V(n) asm volatile("s_waitcnt vmcnt(" #n ")" ::: "memory")
; #define WAIT_L(n) asm volatile("s_waitcnt lgkmcnt(" #n ")" ::: "memory")
; #define BAR __builtin_amdgcn_s_barrier()
; template <bool OVL, bool PANEL = false, class Epi>
; __device__ __forceinline__ void gemm_phase(const bf16_t* __restrict__ A, long lda, const bf16_t* __restrict__ Bt, long ldb, int nM, int nN, int K,
;                                            const Epi& epi, bf16_t* shm, int w0) {
;     ...
;       LDA(At, 0, 1); WAIT_V(4); BAR; WAIT_L(0); MMA(1, 0, At, B0); MMA(1, 1, At, B1); BAR; }
	v_mfma_f32_16x16x32_bf16 v[30:33], v[110:113], v[78:81], v[30:33]
	v_mfma_f32_16x16x32_bf16 v[26:29], v[186:189], v[78:81], v[26:29]
	v_mfma_f32_16x16x32_bf16 v[22:25], v[110:113], v[86:89], v[22:25]
	v_mfma_f32_16x16x32_bf16 v[18:21], v[186:189], v[86:89], v[18:21]
	v_mfma_f32_16x16x32_bf16 v[14:17], v[110:113], v[162:165], v[14:17]
	v_mfma_f32_16x16x32_bf16 v[10:13], v[186:189], v[162:165], v[10:13]
	v_mfma_f32_16x16x32_bf16 v[6:9], v[110:113], v[170:173], v[6:9]
	v_mfma_f32_16x16x32_bf16 v[2:5], v[186:189], v[170:173], v[2:5]
	v_mfma_f32_16x16x32_bf16 v[138:141], v[182:185], v[82:85], v[30:33]
	v_mfma_f32_16x16x32_bf16 v[142:145], v[190:193], v[82:85], v[26:29]
	v_mfma_f32_16x16x32_bf16 v[146:149], v[182:185], v[94:97], v[22:25]
	v_mfma_f32_16x16x32_bf16 v[178:181], v[190:193], v[94:97], v[18:21]
	v_mfma_f32_16x16x32_bf16 v[198:201], v[182:185], v[166:169], v[14:17]
	v_mfma_f32_16x16x32_bf16 v[162:165], v[190:193], v[166:169], v[10:13]
	v_mfma_f32_16x16x32_bf16 v[166:169], v[182:185], v[174:177], v[6:9]
	v_mfma_f32_16x16x32_bf16 v[170:173], v[190:193], v[174:177], v[2:5]

; #define LDA(dst, b, h) for (int m = 0; m < 4; ++m) for (int k = 0; k < 2; ++k) \
;     dst[m][k] = *reinterpret_cast<const bf16x8*>((char*)SA(b, h) + a_thr + (m * 2 + k) * 1024)
; #define LDB(dst, b, h) for (int n = 0; n < 2; ++n) for (int k = 0; k < 2; ++k) \
;     dst[n][k] = *reinterpret_cast<const bf16x8*>((char*)SB(b, h) + b_thr + (n * 2 + k) * 1024)
; #define MMA(ai, bj, At, Btf) do { __builtin_amdgcn_s_setprio(1); \
;     for (int m = 0; m < 4; ++m) for (int n = 0; n < 2; ++n) for (int k = 0; k < 2; ++k) \
;       acc[ai][bj][m][n] = __builtin_amdgcn_mfma_f32_16x16x32_bf16(Btf[n][k], At[m][k], acc[ai][bj][m][n], 0, 0, 0); \
;     __builtin_amdgcn_s_setprio(0); } while (0)
; #define WAIT_V(n) asm volatile("s_waitcnt vmcnt(" #n ")" ::: "memory")
; #define WAIT_L(n) asm volatile("s_waitcnt lgkmcnt(" #n ")" ::: "memory")
; #define BAR __builtin_amdgcn_s_barrier()
; template <bool OVL, bool PANEL = false, class Epi>
; __device__ __forceinline__ void gemm_phase(const bf16_t* __restrict__ A, long lda, const bf16_t* __restrict__ Bt, long ldb, int nM, int nN, int K,
;                                            const Epi& epi, bf16_t* shm, int w0) {
;     ...
;     { LDB(B0, 1, 0); LDA(At, 1, 0); WAIT_V(2); BAR; WAIT_L(0); MMA(0, 0, At, B0); BAR;
	v_add_u32_e32 v0, 0x18000, v206
	s_barrier
	ds_read_b128 v[174:177], v0
	ds_read_b128 v[182:185], v0 offset:1024
	ds_read_b128 v[186:189], v0 offset:2048
	ds_read_b128 v[190:193], v0 offset:3072
	ds_read_b128 v[6:9], v241 offset:32768
	ds_read_b128 v[14:17], v241 offset:33792
	ds_read_b128 v[18:21], v241 offset:34816
	ds_read_b128 v[22:25], v241 offset:35840
	ds_read_b128 v[26:29], v241 offset:36864
	ds_read_b128 v[30:33], v241 offset:37888
	ds_read_b128 v[38:41], v241 offset:38912
	ds_read_b128 v[202:205], v241 offset:39936
	s_waitcnt vmcnt(2)
	s_barrier
	s_waitcnt lgkmcnt(0)

; #define LDA(dst, b, h) for (int m = 0; m < 4; ++m) for (int k = 0; k < 2; ++k) \
;     dst[m][k] = *reinterpret_cast<const bf16x8*>((char*)SA(b, h) + a_thr + (m * 2 + k) * 1024)
; #define LDB(dst, b, h) for (int n = 0; n < 2; ++n) for (int k = 0; k < 2; ++k) \
;     dst[n][k] = *reinterpret_cast<const bf16x8*>((char*)SB(b, h) + b_thr + (n * 2 + k) * 1024)
; #define MMA(ai, bj, At, Btf) do { __builtin_amdgcn_s_setprio(1); \
;     for (int m = 0; m < 4; ++m) for (int n = 0; n < 2; ++n) for (int k = 0; k < 2; ++k) \
;       acc[ai][bj][m][n] = __builtin_amdgcn_mfma_f32_16x16x32_bf16(Btf[n][k], At[m][k], acc[ai][bj][m][n], 0, 0, 0); \
;     __builtin_amdgcn_s_setprio(0); } while (0)
; #define WAIT_V(n) asm volatile("s_waitcnt vmcnt(" #n ")" ::: "memory")
; #define WAIT_L(n) asm volatile("s_waitcnt lgkmcnt(" #n ")" ::: "memory")
; #define BAR __builtin_amdgcn_s_barrier()
; template <bool OVL, bool PANEL = false, class Epi>
; __device__ __forceinline__ void gemm_phase(const bf16_t* __restrict__ A, long lda, const bf16_t* __restrict__ Bt, long ldb, int nM, int nN, int K,
;                                            const Epi& epi, bf16_t* shm, int w0) {
;     ...
;     { LDB(B0, 1, 0); LDA(At, 1, 0); WAIT_V(2); BAR; WAIT_L(0); MMA(0, 0, At, B0); BAR;
	s_waitcnt lgkmcnt(0)
	v_mfma_f32_16x16x32_bf16 v[2:5], v[174:177], v[6:9], v[126:129]
	v_mfma_f32_16x16x32_bf16 v[126:129], v[182:185], v[14:17], v[2:5]
	v_mfma_f32_16x16x32_bf16 v[2:5], v[186:189], v[6:9], v[122:125]
	v_mfma_f32_16x16x32_bf16 v[82:85], v[190:193], v[14:17], v[2:5]
	v_mfma_f32_16x16x32_bf16 v[2:5], v[174:177], v[18:21], v[118:121]
	v_mfma_f32_16x16x32_bf16 v[110:113], v[182:185], v[22:25], v[2:5]
	v_mfma_f32_16x16x32_bf16 v[2:5], v[186:189], v[18:21], v[114:117]
	v_mfma_f32_16x16x32_bf16 v[86:89], v[190:193], v[22:25], v[2:5]
	v_mfma_f32_16x16x32_bf16 v[2:5], v[174:177], v[26:29], v[134:137]
	v_mfma_f32_16x16x32_bf16 v[94:97], v[182:185], v[30:33], v[2:5]
	v_mfma_f32_16x16x32_bf16 v[2:5], v[186:189], v[26:29], v[106:109]
	v_mfma_f32_16x16x32_bf16 v[78:81], v[190:193], v[30:33], v[2:5]
	v_mfma_f32_16x16x32_bf16 v[2:5], v[174:177], v[38:41], v[102:105]
	v_mfma_f32_16x16x32_bf16 v[10:13], v[186:189], v[38:41], v[98:101]
	v_mfma_f32_16x16x32_bf16 v[2:5], v[182:185], v[202:205], v[2:5]
	v_mfma_f32_16x16x32_bf16 v[10:13], v[190:193], v[202:205], v[10:13]

; #define LDB(dst, b, h) for (int n = 0; n < 2; ++n) for (int k = 0; k < 2; ++k) \
;     dst[n][k] = *reinterpret_cast<const bf16x8*>((char*)SB(b, h) + b_thr + (n * 2 + k) * 1024)
; #define MMA(ai, bj, At, Btf) do { __builtin_amdgcn_s_setprio(1); \
;     for (int m = 0; m < 4; ++m) for (int n = 0; n < 2; ++n) for (int k = 0; k < 2; ++k) \
;       acc[ai][bj][m][n] = __builtin_amdgcn_mfma_f32_16x16x32_bf16(Btf[n][k], At[m][k], acc[ai][bj][m][n], 0, 0, 0); \
;     __builtin_amdgcn_s_setprio(0); } while (0)
; #define WAIT_V(n) asm volatile("s_waitcnt vmcnt(" #n ")" ::: "memory")
; #define WAIT_L(n) asm volatile("s_waitcnt lgkmcnt(" #n ")" ::: "memory")
; #define BAR __builtin_amdgcn_s_barrier()
; template <bool OVL, bool PANEL = false, class Epi>
; __device__ __forceinline__ void gemm_phase(const bf16_t* __restrict__ A, long lda, const bf16_t* __restrict__ Bt, long ldb, int nM, int nN, int K,
;                                            const Epi& epi, bf16_t* shm, int w0) {
;     ...
;       LDB(B1, 1, 1); WAIT_V(0); BAR; WAIT_L(0); MMA(0, 1, At, B1); BAR;
	v_add_u32_e32 v0, 0x1c000, v206
	s_barrier
	ds_read_b128 v[122:125], v0
	ds_read_b128 v[134:137], v0 offset:1024
	ds_read_b128 v[206:209], v0 offset:2048
	ds_read_b128 v[210:213], v0 offset:3072
	s_waitcnt vmcnt(0)
	s_barrier
	s_waitcnt lgkmcnt(0)

; #define LDB(dst, b, h) for (int n = 0; n < 2; ++n) for (int k = 0; k < 2; ++k) \
;     dst[n][k] = *reinterpret_cast<const bf16x8*>((char*)SB(b, h) + b_thr + (n * 2 + k) * 1024)
; #define MMA(ai, bj, At, Btf) do { __builtin_amdgcn_s_setprio(1); \
;     for (int m = 0; m < 4; ++m) for (int n = 0; n < 2; ++n) for (int k = 0; k < 2; ++k) \
;       acc[ai][bj][m][n] = __builtin_amdgcn_mfma_f32_16x16x32_bf16(Btf[n][k], At[m][k], acc[ai][bj][m][n], 0, 0, 0); \
;     __builtin_amdgcn_s_setprio(0); } while (0)
; #define WAIT_V(n) asm volatile("s_waitcnt vmcnt(" #n ")" ::: "memory")
; #define WAIT_L(n) asm volatile("s_waitcnt lgkmcnt(" #n ")" ::: "memory")
; #define BAR __builtin_amdgcn_s_barrier()
; template <bool OVL, bool PANEL = false, class Epi>
; __device__ __forceinline__ void gemm_phase(const bf16_t* __restrict__ A, long lda, const bf16_t* __restrict__ Bt, long ldb, int nM, int nN, int K,
;                                            const Epi& epi, bf16_t* shm, int w0) {
;     ...
;       LDB(B1, 1, 1); WAIT_V(0); BAR; WAIT_L(0); MMA(0, 1, At, B1); BAR;
	s_waitcnt lgkmcnt(0)
	v_mfma_f32_16x16x32_bf16 v[98:101], v[122:125], v[6:9], v[194:197]
	v_mfma_f32_16x16x32_bf16 v[6:9], v[206:209], v[6:9], v[90:93]
	v_mfma_f32_16x16x32_bf16 v[114:117], v[210:213], v[14:17], v[6:9]
	v_mfma_f32_16x16x32_bf16 v[6:9], v[122:125], v[18:21], v[150:153]
	v_mfma_f32_16x16x32_bf16 v[102:105], v[134:137], v[22:25], v[6:9]
	v_mfma_f32_16x16x32_bf16 v[6:9], v[206:209], v[18:21], v[154:157]
	v_mfma_f32_16x16x32_bf16 v[118:121], v[210:213], v[22:25], v[6:9]
	v_mfma_f32_16x16x32_bf16 v[6:9], v[122:125], v[26:29], v[158:161]
	v_mfma_f32_16x16x32_bf16 v[90:93], v[134:137], v[30:33], v[6:9]
	v_mfma_f32_16x16x32_bf16 v[6:9], v[206:209], v[26:29], v[74:77]
	v_mfma_f32_16x16x32_bf16 v[106:109], v[210:213], v[30:33], v[6:9]
	v_mfma_f32_16x16x32_bf16 v[6:9], v[122:125], v[38:41], v[70:73]
	v_mfma_f32_16x16x32_bf16 v[22:25], v[134:137], v[202:205], v[6:9]
	v_mfma_f32_16x16x32_bf16 v[6:9], v[206:209], v[38:41], v[66:69]
	v_mfma_f32_16x16x32_bf16 v[98:101], v[134:137], v[14:17], v[98:101]
	v_mfma_f32_16x16x32_bf16 v[38:41], v[210:213], v[202:205], v[6:9]

; #define LDA(dst, b, h) for (int m = 0; m < 4; ++m) for (int k = 0; k < 2; ++k) \
;     dst[m][k] = *reinterpret_cast<const bf16x8*>((char*)SA(b, h) + a_thr + (m * 2 + k) * 1024)
; #define MMA(ai, bj, At, Btf) do { __builtin_amdgcn_s_setprio(1); \
;     for (int m = 0; m < 4; ++m) for (int n = 0; n < 2; ++n) for (int k = 0; k < 2; ++k) \
;       acc[ai][bj][m][n] = __builtin_amdgcn_mfma_f32_16x16x32_bf16(Btf[n][k], At[m][k], acc[ai][bj][m][n], 0, 0, 0); \
;     __builtin_amdgcn_s_setprio(0); } while (0)
; #define WAIT_L(n) asm volatile("s_waitcnt lgkmcnt(" #n ")" ::: "memory")
; #define BAR __builtin_amdgcn_s_barrier()
; template <bool OVL, bool PANEL = false, class Epi>
; __device__ __forceinline__ void gemm_phase(const bf16_t* __restrict__ A, long lda, const bf16_t* __restrict__ Bt, long ldb, int nM, int nN, int K,
;                                            const Epi& epi, bf16_t* shm, int w0) {
;     ...
;       LDA(At, 1, 1); BAR; WAIT_L(0); MMA(1, 0, At, B0); MMA(1, 1, At, B1); BAR; }
	s_barrier
	ds_read_b128 v[70:73], v241 offset:49152
	ds_read_b128 v[74:77], v241 offset:50176
	ds_read_b128 v[150:153], v241 offset:51200
	ds_read_b128 v[154:157], v241 offset:52224
	ds_read_b128 v[158:161], v241 offset:53248
	ds_read_b128 v[194:197], v241 offset:54272
	ds_read_b128 v[202:205], v241 offset:55296
	ds_read_b128 v[214:217], v241 offset:56320
	s_barrier
	s_waitcnt lgkmcnt(0)

; #define LDA(dst, b, h) for (int m = 0; m < 4; ++m) for (int k = 0; k < 2; ++k) \
;     dst[m][k] = *reinterpret_cast<const bf16x8*>((char*)SA(b, h) + a_thr + (m * 2 + k) * 1024)
; #define MMA(ai, bj, At, Btf) do { __builtin_amdgcn_s_setprio(1); \
;     for (int m = 0; m < 4; ++m) for (int n = 0; n < 2; ++n) for (int k = 0; k < 2; ++k) \
;       acc[ai][bj][m][n] = __builtin_amdgcn_mfma_f32_16x16x32_bf16(Btf[n][k], At[m][k], acc[ai][bj][m][n], 0, 0, 0); \
;     __builtin_amdgcn_s_setprio(0); } while (0)
; #define WAIT_L(n) asm volatile("s_waitcnt lgkmcnt(" #n ")" ::: "memory")
; #define BAR __builtin_amdgcn_s_barrier()
; template <bool OVL, bool PANEL = false, class Epi>
; __device__ __forceinline__ void gemm_phase(const bf16_t* __restrict__ A, long lda, const bf16_t* __restrict__ Bt, long ldb, int nM, int nN, int K,
;                                            const Epi& epi, bf16_t* shm, int w0) {
;     ...
;       LDA(At, 1, 1); BAR; WAIT_L(0); MMA(1, 0, At, B0); MMA(1, 1, At, B1); BAR; }
	s_waitcnt lgkmcnt(0)
	v_mfma_f32_16x16x32_bf16 v[14:17], v[186:189], v[70:73], v[58:61]
	v_mfma_f32_16x16x32_bf16 v[42:45], v[186:189], v[158:161], v[42:45]
	v_mfma_f32_16x16x32_bf16 v[6:9], v[174:177], v[70:73], v[62:65]
	v_mfma_f32_16x16x32_bf16 v[18:21], v[190:193], v[74:77], v[14:17]
	v_mfma_f32_16x16x32_bf16 v[14:17], v[174:177], v[150:153], v[54:57]
	v_mfma_f32_16x16x32_bf16 v[26:29], v[186:189], v[150:153], v[50:53]
	v_mfma_f32_16x16x32_bf16 v[30:33], v[174:177], v[158:161], v[46:49]
	v_mfma_f32_16x16x32_bf16 v[46:49], v[190:193], v[194:197], v[42:45]
	v_mfma_f32_16x16x32_bf16 v[42:45], v[174:177], v[202:205], v[130:133]
	v_mfma_f32_16x16x32_bf16 v[34:37], v[186:189], v[202:205], v[34:37]
	v_mfma_f32_16x16x32_bf16 v[6:9], v[182:185], v[74:77], v[6:9]
	v_mfma_f32_16x16x32_bf16 v[14:17], v[182:185], v[154:157], v[14:17]
	v_mfma_f32_16x16x32_bf16 v[26:29], v[190:193], v[154:157], v[26:29]
	v_mfma_f32_16x16x32_bf16 v[30:33], v[182:185], v[194:197], v[30:33]
	v_mfma_f32_16x16x32_bf16 v[54:57], v[182:185], v[214:217], v[42:45]
	v_mfma_f32_16x16x32_bf16 v[66:69], v[190:193], v[214:217], v[34:37]


; #define LDA(dst, b, h) for (int m = 0; m < 4; ++m) for (int k = 0; k < 2; ++k) \
;     dst[m][k] = *reinterpret_cast<const bf16x8*>((char*)SA(b, h) + a_thr + (m * 2 + k) * 1024)
; #define MMA(ai, bj, At, Btf) do { __builtin_amdgcn_s_setprio(1); \
;     for (int m = 0; m < 4; ++m) for (int n = 0; n < 2; ++n) for (int k = 0; k < 2; ++k) \
;       acc[ai][bj][m][n] = __builtin_amdgcn_mfma_f32_16x16x32_bf16(Btf[n][k], At[m][k], acc[ai][bj][m][n], 0, 0, 0); \
;     __builtin_amdgcn_s_setprio(0); } while (0)
; #define WAIT_L(n) asm volatile("s_waitcnt lgkmcnt(" #n ")" ::: "memory")
; #define BAR __builtin_amdgcn_s_barrier()
; template <bool OVL, bool PANEL = false, class Epi>
; __device__ __forceinline__ void gemm_phase(const bf16_t* __restrict__ A, long lda, const bf16_t* __restrict__ Bt, long ldb, int nM, int nN, int K,
;                                            const Epi& epi, bf16_t* shm, int w0) {
;     ...
;       LDA(At, 1, 1); BAR; WAIT_L(0); MMA(1, 0, At, B0); MMA(1, 1, At, B1); BAR; }
	v_mfma_f32_16x16x32_bf16 v[34:37], v[122:125], v[70:73], v[138:141]
	v_mfma_f32_16x16x32_bf16 v[42:45], v[206:209], v[70:73], v[142:145]
	v_mfma_f32_16x16x32_bf16 v[34:37], v[134:137], v[74:77], v[34:37]
	v_mfma_f32_16x16x32_bf16 v[50:53], v[210:213], v[74:77], v[42:45]
	v_mfma_f32_16x16x32_bf16 v[42:45], v[122:125], v[150:153], v[146:149]
	v_mfma_f32_16x16x32_bf16 v[58:61], v[206:209], v[150:153], v[178:181]
	v_mfma_f32_16x16x32_bf16 v[62:65], v[122:125], v[158:161], v[198:201]
	v_mfma_f32_16x16x32_bf16 v[70:73], v[206:209], v[158:161], v[162:165]
	v_mfma_f32_16x16x32_bf16 v[74:77], v[122:125], v[202:205], v[166:169]
	v_mfma_f32_16x16x32_bf16 v[122:125], v[206:209], v[202:205], v[170:173]
	v_mfma_f32_16x16x32_bf16 v[42:45], v[134:137], v[154:157], v[42:45]
	v_mfma_f32_16x16x32_bf16 v[58:61], v[210:213], v[154:157], v[58:61]
	v_mfma_f32_16x16x32_bf16 v[62:65], v[134:137], v[194:197], v[62:65]
	v_mfma_f32_16x16x32_bf16 v[70:73], v[210:213], v[194:197], v[70:73]
	v_mfma_f32_16x16x32_bf16 v[74:77], v[134:137], v[214:217], v[74:77]
	v_mfma_f32_16x16x32_bf16 v[122:125], v[210:213], v[214:217], v[122:125]

; #define LDA(dst, b, h) for (int m = 0; m < 4; ++m) for (int k = 0; k < 2; ++k) \
;     dst[m][k] = *reinterpret_cast<const bf16x8*>((char*)SA(b, h) + a_thr + (m * 2 + k) * 1024)
; #define MMA(ai, bj, At, Btf) do { __builtin_amdgcn_s_setprio(1); \
;     for (int m = 0; m < 4; ++m) for (int n = 0; n < 2; ++n) for (int k = 0; k < 2; ++k) \
;       acc[ai][bj][m][n] = __builtin_amdgcn_mfma_f32_16x16x32_bf16(Btf[n][k], At[m][k], acc[ai][bj][m][n], 0, 0, 0); \
;     __builtin_amdgcn_s_setprio(0); } while (0)
; #define WAIT_L(n) asm volatile("s_waitcnt lgkmcnt(" #n ")" ::: "memory")
; #define BAR __builtin_amdgcn_s_barrier()
; template <bool OVL, bool PANEL = false, class Epi>
; __device__ __forceinline__ void gemm_phase(const bf16_t* __restrict__ A, long lda, const bf16_t* __restrict__ Bt, long ldb, int nM, int nN, int K,
;                                            const Epi& epi, bf16_t* shm, int w0) {
;     ...
;       LDA(At, 1, 1); BAR; WAIT_L(0); MMA(1, 0, At, B0); MMA(1, 1, At, B1); BAR; }
;     if (wr == 0) BAR;
	s_barrier
	s_and_saveexec_b64 s[0:1], s[90:91]
	s_cbranch_execz .LBB0_475
	s_barrier

; #define LDA(dst, b, h) for (int m = 0; m < 4; ++m) for (int k = 0; k < 2; ++k) \
;     dst[m][k] = *reinterpret_cast<const bf16x8*>((char*)SA(b, h) + a_thr + (m * 2 + k) * 1024)
; #define LDB(dst, b, h) for (int n = 0; n < 2; ++n) for (int k = 0; k < 2; ++k) \
;     dst[n][k] = *reinterpret_cast<const bf16x8*>((char*)SB(b, h) + b_thr + (n * 2 + k) * 1024)
; #define MMA(ai, bj, At, Btf) do { __builtin_amdgcn_s_setprio(1); \
;     for (int m = 0; m < 4; ++m) for (int n = 0; n < 2; ++n) for (int k = 0; k < 2; ++k) \
;       acc[ai][bj][m][n] = __builtin_amdgcn_mfma_f32_16x16x32_bf16(Btf[n][k], At[m][k], acc[ai][bj][m][n], 0, 0, 0); \
;     __builtin_amdgcn_s_setprio(0); } while (0)
; #define WAIT_V(n) asm volatile("s_waitcnt vmcnt(" #n ")" ::: "memory")
; #define WAIT_L(n) asm volatile("s_waitcnt lgkmcnt(" #n ")" ::: "memory")
; #define BAR __builtin_amdgcn_s_barrier()
; #define SCHED __builtin_amdgcn_sched_barrier(0)
; template <bool OVL, bool PANEL = false, class Epi>
; __device__ __forceinline__ void gemm_phase(const bf16_t* __restrict__ A, long lda, const bf16_t* __restrict__ Bt, long ldb, int nM, int nN, int K,
;                                            const Epi& epi, bf16_t* shm, int w0) {
;     ...
;     for (int t = 0; t < nt - 2; t += 2) {
;       LDB(B0, 0, 0); SCHED; LDA(At, 0, 0); STAGE(SA(1, 1), A, lda, aoff, brow + HALF, t + 1);
;       WAIT_L(8); BAR; WAIT_L(0); MMA(0, 0, At, B0); BAR; SCHED;
;       LDB(B1, 0, 1); STAGE(SB(0, 0), Bt, ldb, boff, bcol, t + 2);
;       BAR; WAIT_L(0); MMA(0, 1, At, B1); BAR;
;       LDA(At, 0, 1); STAGE(SA(0, 0), A, lda, aoff, brow, t + 2);
;       BAR; WAIT_L(0); MMA(1, 0, At, B0); BAR; SCHED;
;       STAGE(SB(0, 1), Bt, ldb, boff, bcol + HALF, t + 2);
;       WAIT_V(6); BAR; MMA(1, 1, At, B1); BAR;
.LBB0_1053:
	ds_read_b128 v[152:155], v184
	ds_read_b128 v[156:159], v184 offset:1024
	ds_read_b128 v[160:163], v184 offset:2048
	ds_read_b128 v[164:167], v184 offset:3072
	s_add_u32 s40, s10, s14
	s_addc_u32 s41, s11, s15
	ds_read_b128 v[168:171], v147
	ds_read_b128 v[172:175], v147 offset:1024
	ds_read_b128 v[176:179], v147 offset:2048
	ds_read_b128 v[194:197], v147 offset:3072
	ds_read_b128 v[198:201], v147 offset:4096
	ds_read_b128 v[202:205], v147 offset:5120
	ds_read_b128 v[206:209], v147 offset:6144
	ds_read_b128 v[210:213], v147 offset:7168
	s_mov_b32 m0, s22
	s_add_u32 s98, s40, s16
	s_addc_u32 s99, s41, s17
	global_load_lds_dwordx4 v135, s[98:99]
	s_mov_b32 m0, s23
	s_add_u32 s98, s40, s36
	s_addc_u32 s99, s41, s37
	global_load_lds_dwordx4 v135, s[98:99]
	s_waitcnt lgkmcnt(8)
	s_waitcnt vmcnt(10)
	s_barrier
	s_waitcnt lgkmcnt(0)
	s_waitcnt lgkmcnt(0)
	v_mfma_f32_16x16x32_bf16 v[126:129], v[152:155], v[168:171], v[126:129]
	v_mfma_f32_16x16x32_bf16 v[122:125], v[160:163], v[168:171], v[122:125]
	v_mfma_f32_16x16x32_bf16 v[118:121], v[152:155], v[176:179], v[118:121]
	v_mfma_f32_16x16x32_bf16 v[114:117], v[160:163], v[176:179], v[114:117]
	v_mfma_f32_16x16x32_bf16 v[110:113], v[152:155], v[198:201], v[110:113]
	v_mfma_f32_16x16x32_bf16 v[106:109], v[160:163], v[198:201], v[106:109]
	v_mfma_f32_16x16x32_bf16 v[102:105], v[152:155], v[206:209], v[102:105]
	v_mfma_f32_16x16x32_bf16 v[98:101], v[160:163], v[206:209], v[98:101]
	v_mfma_f32_16x16x32_bf16 v[126:129], v[156:159], v[172:175], v[126:129]
	v_mfma_f32_16x16x32_bf16 v[122:125], v[164:167], v[172:175], v[122:125]
	v_mfma_f32_16x16x32_bf16 v[118:121], v[156:159], v[194:197], v[118:121]
	v_mfma_f32_16x16x32_bf16 v[114:117], v[164:167], v[194:197], v[114:117]
	v_mfma_f32_16x16x32_bf16 v[110:113], v[156:159], v[202:205], v[110:113]
	v_mfma_f32_16x16x32_bf16 v[106:109], v[164:167], v[202:205], v[106:109]
	v_mfma_f32_16x16x32_bf16 v[102:105], v[156:159], v[210:213], v[102:105]
	v_mfma_f32_16x16x32_bf16 v[98:101], v[164:167], v[210:213], v[98:101]
	s_barrier
	s_add_u32 s42, s8, s14
	ds_read_b128 v[214:217], v185
	ds_read_b128 v[218:221], v185 offset:1024
	ds_read_b128 v[234:237], v185 offset:2048
	ds_read_b128 v[238:241], v185 offset:3072
	s_addc_u32 s43, s9, s15
	s_mov_b32 m0, s24
	s_add_u32 s98, s42, s34
	s_addc_u32 s99, s43, s35
	global_load_lds_dwordx4 v135, s[98:99]
	s_mov_b32 m0, s25
	s_add_u32 s98, s42, s64
	s_addc_u32 s99, s43, s65
	global_load_lds_dwordx4 v135, s[98:99]
	s_waitcnt vmcnt(10)
	s_barrier
	s_waitcnt lgkmcnt(0)
	s_waitcnt lgkmcnt(0)
	v_mfma_f32_16x16x32_bf16 v[94:97], v[214:217], v[168:171], v[94:97]
	v_mfma_f32_16x16x32_bf16 v[90:93], v[234:237], v[168:171], v[90:93]
	v_mfma_f32_16x16x32_bf16 v[86:89], v[214:217], v[176:179], v[86:89]
	v_mfma_f32_16x16x32_bf16 v[82:85], v[234:237], v[176:179], v[82:85]
	v_mfma_f32_16x16x32_bf16 v[78:81], v[214:217], v[198:201], v[78:81]
	v_mfma_f32_16x16x32_bf16 v[74:77], v[234:237], v[198:201], v[74:77]
	v_mfma_f32_16x16x32_bf16 v[70:73], v[214:217], v[206:209], v[70:73]
	v_mfma_f32_16x16x32_bf16 v[66:69], v[234:237], v[206:209], v[66:69]
	v_mfma_f32_16x16x32_bf16 v[94:97], v[218:221], v[172:175], v[94:97]
	v_mfma_f32_16x16x32_bf16 v[90:93], v[238:241], v[172:175], v[90:93]
	v_mfma_f32_16x16x32_bf16 v[86:89], v[218:221], v[194:197], v[86:89]
	v_mfma_f32_16x16x32_bf16 v[82:85], v[238:241], v[194:197], v[82:85]
	v_mfma_f32_16x16x32_bf16 v[78:81], v[218:221], v[202:205], v[78:81]
	v_mfma_f32_16x16x32_bf16 v[74:77], v[238:241], v[202:205], v[74:77]
	v_mfma_f32_16x16x32_bf16 v[70:73], v[218:221], v[210:213], v[70:73]
	v_mfma_f32_16x16x32_bf16 v[66:69], v[238:241], v[210:213], v[66:69]
	s_barrier
	ds_read_b128 v[168:171], v147 offset:16384
	ds_read_b128 v[172:175], v147 offset:17408
	ds_read_b128 v[176:179], v147 offset:18432
	ds_read_b128 v[194:197], v147 offset:19456
	ds_read_b128 v[198:201], v147 offset:20480
	ds_read_b128 v[202:205], v147 offset:21504
	ds_read_b128 v[206:209], v147 offset:22528
	ds_read_b128 v[210:213], v147 offset:23552
	s_mov_b32 m0, s26
	s_add_u32 s98, s40, s34
	s_addc_u32 s99, s41, s35
	global_load_lds_dwordx4 v135, s[98:99]
	s_mov_b32 m0, s27
	s_add_u32 s98, s40, s64
	s_addc_u32 s99, s41, s65
	global_load_lds_dwordx4 v135, s[98:99]
	s_barrier
	s_waitcnt lgkmcnt(0)
	s_waitcnt lgkmcnt(0)
	v_mfma_f32_16x16x32_bf16 v[62:65], v[152:155], v[168:171], v[62:65]
	v_mfma_f32_16x16x32_bf16 v[58:61], v[160:163], v[168:171], v[58:61]
	v_mfma_f32_16x16x32_bf16 v[54:57], v[152:155], v[176:179], v[54:57]
	v_mfma_f32_16x16x32_bf16 v[50:53], v[160:163], v[176:179], v[50:53]
	v_mfma_f32_16x16x32_bf16 v[46:49], v[152:155], v[198:201], v[46:49]
	v_mfma_f32_16x16x32_bf16 v[42:45], v[160:163], v[198:201], v[42:45]
	v_mfma_f32_16x16x32_bf16 v[38:41], v[152:155], v[206:209], v[38:41]
	v_mfma_f32_16x16x32_bf16 v[34:37], v[160:163], v[206:209], v[34:37]
	v_mfma_f32_16x16x32_bf16 v[62:65], v[156:159], v[172:175], v[62:65]
	v_mfma_f32_16x16x32_bf16 v[58:61], v[164:167], v[172:175], v[58:61]
	v_mfma_f32_16x16x32_bf16 v[54:57], v[156:159], v[194:197], v[54:57]
	v_mfma_f32_16x16x32_bf16 v[50:53], v[164:167], v[194:197], v[50:53]
	v_mfma_f32_16x16x32_bf16 v[46:49], v[156:159], v[202:205], v[46:49]
	v_mfma_f32_16x16x32_bf16 v[42:45], v[164:167], v[202:205], v[42:45]
	v_mfma_f32_16x16x32_bf16 v[38:41], v[156:159], v[210:213], v[38:41]
	v_mfma_f32_16x16x32_bf16 v[34:37], v[164:167], v[210:213], v[34:37]
	s_barrier
	s_mov_b32 m0, s28
	s_add_u32 s98, s42, s68
	s_addc_u32 s99, s43, s69
	global_load_lds_dwordx4 v135, s[98:99]
	s_mov_b32 m0, s29
	s_add_u32 s98, s42, s70
	s_addc_u32 s99, s43, s71
	global_load_lds_dwordx4 v135, s[98:99]
	s_waitcnt vmcnt(10)
	s_barrier
; #define LDA(dst, b, h) for (int m = 0; m < 4; ++m) for (int k = 0; k < 2; ++k) \
;     dst[m][k] = *reinterpret_cast<const bf16x8*>((char*)SA(b, h) + a_thr + (m * 2 + k) * 1024)
; #define LDB(dst, b, h) for (int n = 0; n < 2; ++n) for (int k = 0; k < 2; ++k) \
;     dst[n][k] = *reinterpret_cast<const bf16x8*>((char*)SB(b, h) + b_thr + (n * 2 + k) * 1024)
; #define MMA(ai, bj, At, Btf) do { __builtin_amdgcn_s_setprio(1); \
;     for (int m = 0; m < 4; ++m) for (int n = 0; n < 2; ++n) for (int k = 0; k < 2; ++k) \
;       acc[ai][bj][m][n] = __builtin_amdgcn_mfma_f32_16x16x32_bf16(Btf[n][k], At[m][k], acc[ai][bj][m][n], 0, 0, 0); \
;     __builtin_amdgcn_s_setprio(0); } while (0)
; #define WAIT_V(n) asm volatile("s_waitcnt vmcnt(" #n ")" ::: "memory")
; #define WAIT_L(n) asm volatile("s_waitcnt lgkmcnt(" #n ")" ::: "memory")
; #define BAR __builtin_amdgcn_s_barrier()
; #define SCHED __builtin_amdgcn_sched_barrier(0)
; template <bool OVL, bool PANEL = false, class Epi>
; __device__ __forceinline__ void gemm_phase(const bf16_t* __restrict__ A, long lda, const bf16_t* __restrict__ Bt, long ldb, int nM, int nN, int K,
;                                            const Epi& epi, bf16_t* shm, int w0) {
;     ...
;       WAIT_V(6); BAR; MMA(1, 1, At, B1); BAR;
;       LDB(B0, 1, 0); SCHED; LDA(At, 1, 0); STAGE(SA(0, 1), A, lda, aoff, brow + HALF, t + 2);
;       WAIT_L(8); BAR; WAIT_L(0); MMA(0, 0, At, B0); BAR; SCHED;
;       LDB(B1, 1, 1); STAGE(SB(1, 0), Bt, ldb, boff, bcol, t + 3);
;       BAR; WAIT_L(0); MMA(0, 1, At, B1); BAR;
	v_mfma_f32_16x16x32_bf16 v[30:33], v[214:217], v[168:171], v[30:33]
	v_mfma_f32_16x16x32_bf16 v[26:29], v[234:237], v[168:171], v[26:29]
	v_mfma_f32_16x16x32_bf16 v[22:25], v[214:217], v[176:179], v[22:25]
	v_mfma_f32_16x16x32_bf16 v[18:21], v[234:237], v[176:179], v[18:21]
	v_mfma_f32_16x16x32_bf16 v[14:17], v[214:217], v[198:201], v[14:17]
	v_mfma_f32_16x16x32_bf16 v[10:13], v[234:237], v[198:201], v[10:13]
	v_mfma_f32_16x16x32_bf16 v[6:9], v[214:217], v[206:209], v[6:9]
	v_mfma_f32_16x16x32_bf16 v[2:5], v[234:237], v[206:209], v[2:5]
	v_mfma_f32_16x16x32_bf16 v[30:33], v[218:221], v[172:175], v[30:33]
	v_mfma_f32_16x16x32_bf16 v[26:29], v[238:241], v[172:175], v[26:29]
	v_mfma_f32_16x16x32_bf16 v[22:25], v[218:221], v[194:197], v[22:25]
	v_mfma_f32_16x16x32_bf16 v[18:21], v[238:241], v[194:197], v[18:21]
	v_mfma_f32_16x16x32_bf16 v[14:17], v[218:221], v[202:205], v[14:17]
	v_mfma_f32_16x16x32_bf16 v[10:13], v[238:241], v[202:205], v[10:13]
	v_mfma_f32_16x16x32_bf16 v[6:9], v[218:221], v[210:213], v[6:9]
	v_mfma_f32_16x16x32_bf16 v[2:5], v[238:241], v[210:213], v[2:5]
	s_barrier
	ds_read_b128 v[152:155], v186
	ds_read_b128 v[156:159], v186 offset:1024
	ds_read_b128 v[160:163], v186 offset:2048
	ds_read_b128 v[164:167], v186 offset:3072
	ds_read_b128 v[168:171], v147 offset:32768
	ds_read_b128 v[172:175], v147 offset:33792
	ds_read_b128 v[176:179], v147 offset:34816
	ds_read_b128 v[194:197], v147 offset:35840
	ds_read_b128 v[198:201], v147 offset:36864
	ds_read_b128 v[202:205], v147 offset:37888
	ds_read_b128 v[206:209], v147 offset:38912
	ds_read_b128 v[210:213], v147 offset:39936
	s_mov_b32 m0, s30
	s_add_u32 s98, s40, s68
	s_addc_u32 s99, s41, s69
	global_load_lds_dwordx4 v135, s[98:99]
	s_mov_b32 m0, s31
	s_add_u32 s98, s40, s70
	s_addc_u32 s99, s41, s71
	global_load_lds_dwordx4 v135, s[98:99]
	s_waitcnt lgkmcnt(8)
	s_waitcnt vmcnt(10)
	s_barrier
	s_waitcnt lgkmcnt(0)
	s_waitcnt lgkmcnt(0)
	v_mfma_f32_16x16x32_bf16 v[126:129], v[152:155], v[168:171], v[126:129]
	v_mfma_f32_16x16x32_bf16 v[122:125], v[160:163], v[168:171], v[122:125]
	v_mfma_f32_16x16x32_bf16 v[118:121], v[152:155], v[176:179], v[118:121]
	v_mfma_f32_16x16x32_bf16 v[114:117], v[160:163], v[176:179], v[114:117]
	v_mfma_f32_16x16x32_bf16 v[110:113], v[152:155], v[198:201], v[110:113]
	v_mfma_f32_16x16x32_bf16 v[106:109], v[160:163], v[198:201], v[106:109]
	v_mfma_f32_16x16x32_bf16 v[102:105], v[152:155], v[206:209], v[102:105]
	v_mfma_f32_16x16x32_bf16 v[98:101], v[160:163], v[206:209], v[98:101]
	v_mfma_f32_16x16x32_bf16 v[126:129], v[156:159], v[172:175], v[126:129]
	v_mfma_f32_16x16x32_bf16 v[122:125], v[164:167], v[172:175], v[122:125]
	v_mfma_f32_16x16x32_bf16 v[118:121], v[156:159], v[194:197], v[118:121]
	v_mfma_f32_16x16x32_bf16 v[114:117], v[164:167], v[194:197], v[114:117]
	v_mfma_f32_16x16x32_bf16 v[110:113], v[156:159], v[202:205], v[110:113]
	v_mfma_f32_16x16x32_bf16 v[106:109], v[164:167], v[202:205], v[106:109]
	v_mfma_f32_16x16x32_bf16 v[102:105], v[156:159], v[210:213], v[102:105]
	v_mfma_f32_16x16x32_bf16 v[98:101], v[164:167], v[210:213], v[98:101]
	s_barrier
	ds_read_b128 v[214:217], v187
	ds_read_b128 v[218:221], v187 offset:1024
	ds_read_b128 v[234:237], v187 offset:2048
	ds_read_b128 v[238:241], v187 offset:3072
	s_mov_b32 m0, s32
	s_add_u32 s98, s42, s94
	s_addc_u32 s99, s43, s95
	global_load_lds_dwordx4 v135, s[98:99]
	s_mov_b32 m0, s44
	s_add_u32 s98, s42, s72
	s_addc_u32 s99, s43, s73
	global_load_lds_dwordx4 v135, s[98:99]
	s_waitcnt vmcnt(10)
	s_barrier
	s_waitcnt lgkmcnt(0)
	s_waitcnt lgkmcnt(0)
	v_mfma_f32_16x16x32_bf16 v[94:97], v[214:217], v[168:171], v[94:97]
	v_mfma_f32_16x16x32_bf16 v[90:93], v[234:237], v[168:171], v[90:93]
	v_mfma_f32_16x16x32_bf16 v[86:89], v[214:217], v[176:179], v[86:89]
	v_mfma_f32_16x16x32_bf16 v[82:85], v[234:237], v[176:179], v[82:85]
	v_mfma_f32_16x16x32_bf16 v[78:81], v[214:217], v[198:201], v[78:81]
	v_mfma_f32_16x16x32_bf16 v[74:77], v[234:237], v[198:201], v[74:77]
	v_mfma_f32_16x16x32_bf16 v[70:73], v[214:217], v[206:209], v[70:73]
	v_mfma_f32_16x16x32_bf16 v[66:69], v[234:237], v[206:209], v[66:69]
	v_mfma_f32_16x16x32_bf16 v[94:97], v[218:221], v[172:175], v[94:97]
	v_mfma_f32_16x16x32_bf16 v[90:93], v[238:241], v[172:175], v[90:93]
	v_mfma_f32_16x16x32_bf16 v[86:89], v[218:221], v[194:197], v[86:89]
	v_mfma_f32_16x16x32_bf16 v[82:85], v[238:241], v[194:197], v[82:85]
	v_mfma_f32_16x16x32_bf16 v[78:81], v[218:221], v[202:205], v[78:81]
	v_mfma_f32_16x16x32_bf16 v[74:77], v[238:241], v[202:205], v[74:77]
	v_mfma_f32_16x16x32_bf16 v[70:73], v[218:221], v[210:213], v[70:73]
	v_mfma_f32_16x16x32_bf16 v[66:69], v[238:241], v[210:213], v[66:69]
	s_barrier
; #define LDA(dst, b, h) for (int m = 0; m < 4; ++m) for (int k = 0; k < 2; ++k) \
;     dst[m][k] = *reinterpret_cast<const bf16x8*>((char*)SA(b, h) + a_thr + (m * 2 + k) * 1024)
; #define LDB(dst, b, h) for (int n = 0; n < 2; ++n) for (int k = 0; k < 2; ++k) \
;     dst[n][k] = *reinterpret_cast<const bf16x8*>((char*)SB(b, h) + b_thr + (n * 2 + k) * 1024)
; #define MMA(ai, bj, At, Btf) do { __builtin_amdgcn_s_setprio(1); \
;     for (int m = 0; m < 4; ++m) for (int n = 0; n < 2; ++n) for (int k = 0; k < 2; ++k) \
;       acc[ai][bj][m][n] = __builtin_amdgcn_mfma_f32_16x16x32_bf16(Btf[n][k], At[m][k], acc[ai][bj][m][n], 0, 0, 0); \
;     __builtin_amdgcn_s_setprio(0); } while (0)
; #define WAIT_V(n) asm volatile("s_waitcnt vmcnt(" #n ")" ::: "memory")
; #define WAIT_L(n) asm volatile("s_waitcnt lgkmcnt(" #n ")" ::: "memory")
; #define BAR __builtin_amdgcn_s_barrier()
; #define SCHED __builtin_amdgcn_sched_barrier(0)
; template <bool OVL, bool PANEL = false, class Epi>
; __device__ __forceinline__ void gemm_phase(const bf16_t* __restrict__ A, long lda, const bf16_t* __restrict__ Bt, long ldb, int nM, int nN, int K,
;                                            const Epi& epi, bf16_t* shm, int w0) {
;     ...
;       LDA(At, 1, 1); STAGE(SA(1, 0), A, lda, aoff, brow, t + 3);
;       BAR; WAIT_L(0); MMA(1, 0, At, B0); BAR; SCHED;
;       STAGE(SB(1, 1), Bt, ldb, boff, bcol + HALF, t + 3);
;       WAIT_V(6); BAR; MMA(1, 1, At, B1); BAR;
;     }
;     { LDB(B0, 0, 0); LDA(At, 0, 0); STAGE(SA(1, 1), A, lda, aoff, brow + HALF, nt - 1);
;       BAR; WAIT_L(0); MMA(0, 0, At, B0); BAR;
	ds_read_b128 v[168:171], v147 offset:49152
	ds_read_b128 v[172:175], v147 offset:50176
	ds_read_b128 v[176:179], v147 offset:51200
	ds_read_b128 v[194:197], v147 offset:52224
	ds_read_b128 v[198:201], v147 offset:53248
	ds_read_b128 v[202:205], v147 offset:54272
	ds_read_b128 v[206:209], v147 offset:55296
	ds_read_b128 v[210:213], v147 offset:56320
	s_mov_b32 m0, s45
	s_add_u32 s98, s40, s94
	s_addc_u32 s99, s41, s95
	global_load_lds_dwordx4 v135, s[98:99]
	s_mov_b32 m0, s46
	s_add_u32 s98, s40, s72
	s_addc_u32 s99, s41, s73
	global_load_lds_dwordx4 v135, s[98:99]
	s_barrier
	s_waitcnt lgkmcnt(0)
	s_waitcnt lgkmcnt(0)
	v_mfma_f32_16x16x32_bf16 v[62:65], v[152:155], v[168:171], v[62:65]
	v_mfma_f32_16x16x32_bf16 v[58:61], v[160:163], v[168:171], v[58:61]
	v_mfma_f32_16x16x32_bf16 v[54:57], v[152:155], v[176:179], v[54:57]
	v_mfma_f32_16x16x32_bf16 v[50:53], v[160:163], v[176:179], v[50:53]
	v_mfma_f32_16x16x32_bf16 v[46:49], v[152:155], v[198:201], v[46:49]
	v_mfma_f32_16x16x32_bf16 v[42:45], v[160:163], v[198:201], v[42:45]
	v_mfma_f32_16x16x32_bf16 v[38:41], v[152:155], v[206:209], v[38:41]
	v_mfma_f32_16x16x32_bf16 v[34:37], v[160:163], v[206:209], v[34:37]
	v_mfma_f32_16x16x32_bf16 v[62:65], v[156:159], v[172:175], v[62:65]
	v_mfma_f32_16x16x32_bf16 v[58:61], v[164:167], v[172:175], v[58:61]
	v_mfma_f32_16x16x32_bf16 v[54:57], v[156:159], v[194:197], v[54:57]
	v_mfma_f32_16x16x32_bf16 v[50:53], v[164:167], v[194:197], v[50:53]
	v_mfma_f32_16x16x32_bf16 v[46:49], v[156:159], v[202:205], v[46:49]
	v_mfma_f32_16x16x32_bf16 v[42:45], v[164:167], v[202:205], v[42:45]
	v_mfma_f32_16x16x32_bf16 v[38:41], v[156:159], v[210:213], v[38:41]
	v_mfma_f32_16x16x32_bf16 v[34:37], v[164:167], v[210:213], v[34:37]
	s_barrier
	s_mov_b32 m0, s47
	s_add_u32 s98, s42, s18
	s_addc_u32 s99, s43, s19
	global_load_lds_dwordx4 v135, s[98:99]
	s_mov_b32 m0, s48
	s_add_u32 s98, s42, s20
	s_addc_u32 s99, s43, s21
	global_load_lds_dwordx4 v135, s[98:99]
	s_add_i32 s1, s1, 2
	s_add_u32 s14, s14, 0x100
	s_addc_u32 s15, s15, 0
	s_cmp_lt_u32 s1, 12
	s_waitcnt vmcnt(10)
	s_barrier
	v_mfma_f32_16x16x32_bf16 v[30:33], v[214:217], v[168:171], v[30:33]
	v_mfma_f32_16x16x32_bf16 v[26:29], v[234:237], v[168:171], v[26:29]
	v_mfma_f32_16x16x32_bf16 v[22:25], v[214:217], v[176:179], v[22:25]
	v_mfma_f32_16x16x32_bf16 v[18:21], v[234:237], v[176:179], v[18:21]
	v_mfma_f32_16x16x32_bf16 v[14:17], v[214:217], v[198:201], v[14:17]
	v_mfma_f32_16x16x32_bf16 v[10:13], v[234:237], v[198:201], v[10:13]
	v_mfma_f32_16x16x32_bf16 v[6:9], v[214:217], v[206:209], v[6:9]
	v_mfma_f32_16x16x32_bf16 v[2:5], v[234:237], v[206:209], v[2:5]
	v_mfma_f32_16x16x32_bf16 v[30:33], v[218:221], v[172:175], v[30:33]
	v_mfma_f32_16x16x32_bf16 v[26:29], v[238:241], v[172:175], v[26:29]
	v_mfma_f32_16x16x32_bf16 v[22:25], v[218:221], v[194:197], v[22:25]
	v_mfma_f32_16x16x32_bf16 v[18:21], v[238:241], v[194:197], v[18:21]
	v_mfma_f32_16x16x32_bf16 v[14:17], v[218:221], v[202:205], v[14:17]
	v_mfma_f32_16x16x32_bf16 v[10:13], v[238:241], v[202:205], v[10:13]
	v_mfma_f32_16x16x32_bf16 v[6:9], v[218:221], v[210:213], v[6:9]
	v_mfma_f32_16x16x32_bf16 v[2:5], v[238:241], v[210:213], v[2:5]
	s_barrier
	s_cbranch_scc1 .LBB0_1053
	s_waitcnt vmcnt(6)
	s_or_b32 s8, s0, 0x80
	s_ashr_i32 s9, s8, 31
	v_readlane_b32 s40, v252, 20
	s_lshl_b64 s[8:9], s[8:9], 11
	v_readlane_b32 s46, v252, 26
	v_add_u32_e32 v182, 16, v144
	v_readlane_b32 s47, v252, 27
	s_add_u32 s8, s46, s8
	v_add_u32_e32 v0, 0x10000, v182
	s_addc_u32 s9, s47, s9
	ds_read_b128 v[130:133], v0
	ds_read_b128 v[152:155], v0 offset:1024
	ds_read_b128 v[156:159], v0 offset:2048
	ds_read_b128 v[160:163], v0 offset:3072
	ds_read_b128 v[164:167], v147
	ds_read_b128 v[168:171], v147 offset:1024
	ds_read_b128 v[172:175], v147 offset:2048
	ds_read_b128 v[176:179], v147 offset:3072
	ds_read_b128 v[194:197], v147 offset:4096
	ds_read_b128 v[198:201], v147 offset:5120
	ds_read_b128 v[202:205], v147 offset:6144
	ds_read_b128 v[206:209], v147 offset:7168
	v_mov_b32_e32 v0, v135
	v_readfirstlane_b32 s1, v150
	v_lshl_add_u64 v[148:149], s[8:9], 0, v[0:1]
	s_mov_b64 s[8:9], 0x780
	v_lshl_add_u64 v[180:181], v[148:149], 0, s[8:9]
	s_mov_b32 m0, s1
	s_mov_b64 s[8:9], 0x20780
	v_readfirstlane_b32 s1, v151
	global_load_lds_dwordx4 v[180:181], off
	v_lshl_add_u64 v[148:149], v[148:149], 0, s[8:9]
	s_mov_b32 m0, s1
	v_readlane_b32 s41, v252, 21
	global_load_lds_dwordx4 v[148:149], off
	s_barrier
	s_waitcnt lgkmcnt(0)
	v_readlane_b32 s42, v252, 22
	v_readlane_b32 s43, v252, 23
	v_readlane_b32 s44, v252, 24
	v_readlane_b32 s45, v252, 25
	v_readlane_b32 s48, v252, 28
	v_readlane_b32 s49, v252, 29
	v_readlane_b32 s50, v252, 30
	v_readlane_b32 s51, v252, 31
	v_readlane_b32 s52, v252, 32
	v_readlane_b32 s53, v252, 33
	v_readlane_b32 s54, v252, 34
	v_readlane_b32 s55, v252, 35

; #define MMA(ai, bj, At, Btf) do { __builtin_amdgcn_s_setprio(1); \
;     for (int m = 0; m < 4; ++m) for (int n = 0; n < 2; ++n) for (int k = 0; k < 2; ++k) \
;       acc[ai][bj][m][n] = __builtin_amdgcn_mfma_f32_16x16x32_bf16(Btf[n][k], At[m][k], acc[ai][bj][m][n], 0, 0, 0); \
;     __builtin_amdgcn_s_setprio(0); } while (0)
; #define WAIT_L(n) asm volatile("s_waitcnt lgkmcnt(" #n ")" ::: "memory")
; #define BAR __builtin_amdgcn_s_barrier()
; template <bool OVL, bool PANEL = false, class Epi>
; __device__ __forceinline__ void gemm_phase(const bf16_t* __restrict__ A, long lda, const bf16_t* __restrict__ Bt, long ldb, int nM, int nN, int K,
;                                            const Epi& epi, bf16_t* shm, int w0) {
;     ...
;       BAR; WAIT_L(0); MMA(0, 0, At, B0); BAR;
	s_waitcnt lgkmcnt(0)
	v_mfma_f32_16x16x32_bf16 v[126:129], v[130:133], v[164:167], v[126:129]
	v_mfma_f32_16x16x32_bf16 v[122:125], v[156:159], v[164:167], v[122:125]
	v_mfma_f32_16x16x32_bf16 v[118:121], v[130:133], v[172:175], v[118:121]
	v_mfma_f32_16x16x32_bf16 v[114:117], v[156:159], v[172:175], v[114:117]
	v_mfma_f32_16x16x32_bf16 v[110:113], v[130:133], v[194:197], v[110:113]
	v_mfma_f32_16x16x32_bf16 v[106:109], v[156:159], v[194:197], v[106:109]
	v_mfma_f32_16x16x32_bf16 v[102:105], v[130:133], v[202:205], v[102:105]
	v_mfma_f32_16x16x32_bf16 v[98:101], v[156:159], v[202:205], v[98:101]
	v_mfma_f32_16x16x32_bf16 v[126:129], v[152:155], v[168:171], v[126:129]
	v_mfma_f32_16x16x32_bf16 v[122:125], v[160:163], v[168:171], v[122:125]
	v_mfma_f32_16x16x32_bf16 v[118:121], v[152:155], v[176:179], v[118:121]
	v_mfma_f32_16x16x32_bf16 v[114:117], v[160:163], v[176:179], v[114:117]
	v_mfma_f32_16x16x32_bf16 v[110:113], v[152:155], v[198:201], v[110:113]
	v_mfma_f32_16x16x32_bf16 v[106:109], v[160:163], v[198:201], v[106:109]
	v_mfma_f32_16x16x32_bf16 v[102:105], v[152:155], v[206:209], v[102:105]
	v_mfma_f32_16x16x32_bf16 v[98:101], v[160:163], v[206:209], v[98:101]

; #define LDB(dst, b, h) for (int n = 0; n < 2; ++n) for (int k = 0; k < 2; ++k) \
;     dst[n][k] = *reinterpret_cast<const bf16x8*>((char*)SB(b, h) + b_thr + (n * 2 + k) * 1024)
; #define MMA(ai, bj, At, Btf) do { __builtin_amdgcn_s_setprio(1); \
;     for (int m = 0; m < 4; ++m) for (int n = 0; n < 2; ++n) for (int k = 0; k < 2; ++k) \
;       acc[ai][bj][m][n] = __builtin_amdgcn_mfma_f32_16x16x32_bf16(Btf[n][k], At[m][k], acc[ai][bj][m][n], 0, 0, 0); \
;     __builtin_amdgcn_s_setprio(0); } while (0)
; #define WAIT_L(n) asm volatile("s_waitcnt lgkmcnt(" #n ")" ::: "memory")
; #define BAR __builtin_amdgcn_s_barrier()
; template <bool OVL, bool PANEL = false, class Epi>
; __device__ __forceinline__ void gemm_phase(const bf16_t* __restrict__ A, long lda, const bf16_t* __restrict__ Bt, long ldb, int nM, int nN, int K,
;                                            const Epi& epi, bf16_t* shm, int w0) {
;     ...
;       LDB(B1, 0, 1); BAR; WAIT_L(0); MMA(0, 1, At, B1); BAR;
	v_add_u32_e32 v0, 0x14000, v182
	s_barrier
	ds_read_b128 v[148:151], v0
	ds_read_b128 v[210:213], v0 offset:1024
	ds_read_b128 v[214:217], v0 offset:2048
	ds_read_b128 v[218:221], v0 offset:3072
	s_barrier
	s_waitcnt lgkmcnt(0)

; #define LDB(dst, b, h) for (int n = 0; n < 2; ++n) for (int k = 0; k < 2; ++k) \
;     dst[n][k] = *reinterpret_cast<const bf16x8*>((char*)SB(b, h) + b_thr + (n * 2 + k) * 1024)
; #define MMA(ai, bj, At, Btf) do { __builtin_amdgcn_s_setprio(1); \
;     for (int m = 0; m < 4; ++m) for (int n = 0; n < 2; ++n) for (int k = 0; k < 2; ++k) \
;       acc[ai][bj][m][n] = __builtin_amdgcn_mfma_f32_16x16x32_bf16(Btf[n][k], At[m][k], acc[ai][bj][m][n], 0, 0, 0); \
;     __builtin_amdgcn_s_setprio(0); } while (0)
; #define WAIT_L(n) asm volatile("s_waitcnt lgkmcnt(" #n ")" ::: "memory")
; #define BAR __builtin_amdgcn_s_barrier()
; template <bool OVL, bool PANEL = false, class Epi>
; __device__ __forceinline__ void gemm_phase(const bf16_t* __restrict__ A, long lda, const bf16_t* __restrict__ Bt, long ldb, int nM, int nN, int K,
;                                            const Epi& epi, bf16_t* shm, int w0) {
;     ...
;       LDB(B1, 0, 1); BAR; WAIT_L(0); MMA(0, 1, At, B1); BAR;
	s_waitcnt lgkmcnt(0)
	v_mfma_f32_16x16x32_bf16 v[94:97], v[148:151], v[164:167], v[94:97]
	v_mfma_f32_16x16x32_bf16 v[90:93], v[214:217], v[164:167], v[90:93]
	v_mfma_f32_16x16x32_bf16 v[86:89], v[148:151], v[172:175], v[86:89]
	v_mfma_f32_16x16x32_bf16 v[82:85], v[214:217], v[172:175], v[82:85]
	v_mfma_f32_16x16x32_bf16 v[78:81], v[148:151], v[194:197], v[78:81]
	v_mfma_f32_16x16x32_bf16 v[74:77], v[214:217], v[194:197], v[74:77]
	v_mfma_f32_16x16x32_bf16 v[70:73], v[148:151], v[202:205], v[70:73]
	v_mfma_f32_16x16x32_bf16 v[66:69], v[214:217], v[202:205], v[66:69]
	v_mfma_f32_16x16x32_bf16 v[94:97], v[210:213], v[168:171], v[94:97]
	v_mfma_f32_16x16x32_bf16 v[90:93], v[218:221], v[168:171], v[90:93]
	v_mfma_f32_16x16x32_bf16 v[86:89], v[210:213], v[176:179], v[86:89]
	v_mfma_f32_16x16x32_bf16 v[82:85], v[218:221], v[176:179], v[82:85]
	v_mfma_f32_16x16x32_bf16 v[78:81], v[210:213], v[198:201], v[78:81]
	v_mfma_f32_16x16x32_bf16 v[74:77], v[218:221], v[198:201], v[74:77]
	v_mfma_f32_16x16x32_bf16 v[70:73], v[210:213], v[206:209], v[70:73]
	v_mfma_f32_16x16x32_bf16 v[66:69], v[218:221], v[206:209], v[66:69]

; #define LDA(dst, b, h) for (int m = 0; m < 4; ++m) for (int k = 0; k < 2; ++k) \
;     dst[m][k] = *reinterpret_cast<const bf16x8*>((char*)SA(b, h) + a_thr + (m * 2 + k) * 1024)
; #define MMA(ai, bj, At, Btf) do { __builtin_amdgcn_s_setprio(1); \
;     for (int m = 0; m < 4; ++m) for (int n = 0; n < 2; ++n) for (int k = 0; k < 2; ++k) \
;       acc[ai][bj][m][n] = __builtin_amdgcn_mfma_f32_16x16x32_bf16(Btf[n][k], At[m][k], acc[ai][bj][m][n], 0, 0, 0); \
;     __builtin_amdgcn_s_setprio(0); } while (0)
; #define WAIT_V(n) asm volatile("s_waitcnt vmcnt(" #n ")" ::: "memory")
; #define WAIT_L(n) asm volatile("s_waitcnt lgkmcnt(" #n ")" ::: "memory")
; #define BAR __builtin_amdgcn_s_barrier()
; template <bool OVL, bool PANEL = false, class Epi>
; __device__ __forceinline__ void gemm_phase(const bf16_t* __restrict__ A, long lda, const bf16_t* __restrict__ Bt, long ldb, int nM, int nN, int K,
;                                            const Epi& epi, bf16_t* shm, int w0) {
;     ...
;       LDA(At, 0, 1); WAIT_V(4); BAR; WAIT_L(0); MMA(1, 0, At, B0); MMA(1, 1, At, B1); BAR; }
	s_barrier
	ds_read_b128 v[164:167], v147 offset:16384
	ds_read_b128 v[168:171], v147 offset:17408
	ds_read_b128 v[172:175], v147 offset:18432
	ds_read_b128 v[176:179], v147 offset:19456
	ds_read_b128 v[194:197], v147 offset:20480
	ds_read_b128 v[198:201], v147 offset:21504
	ds_read_b128 v[202:205], v147 offset:22528
	ds_read_b128 v[206:209], v147 offset:23552
	s_waitcnt vmcnt(4)
	s_barrier
	s_waitcnt lgkmcnt(0)

; #define LDA(dst, b, h) for (int m = 0; m < 4; ++m) for (int k = 0; k < 2; ++k) \
;     dst[m][k] = *reinterpret_cast<const bf16x8*>((char*)SA(b, h) + a_thr + (m * 2 + k) * 1024)
; #define MMA(ai, bj, At, Btf) do { __builtin_amdgcn_s_setprio(1); \
;     for (int m = 0; m < 4; ++m) for (int n = 0; n < 2; ++n) for (int k = 0; k < 2; ++k) \
;       acc[ai][bj][m][n] = __builtin_amdgcn_mfma_f32_16x16x32_bf16(Btf[n][k], At[m][k], acc[ai][bj][m][n], 0, 0, 0); \
;     __builtin_amdgcn_s_setprio(0); } while (0)
; #define WAIT_V(n) asm volatile("s_waitcnt vmcnt(" #n ")" ::: "memory")
; #define WAIT_L(n) asm volatile("s_waitcnt lgkmcnt(" #n ")" ::: "memory")
; #define BAR __builtin_amdgcn_s_barrier()
; template <bool OVL, bool PANEL = false, class Epi>
; __device__ __forceinline__ void gemm_phase(const bf16_t* __restrict__ A, long lda, const bf16_t* __restrict__ Bt, long ldb, int nM, int nN, int K,
;                                            const Epi& epi, bf16_t* shm, int w0) {
;     ...
;       LDA(At, 0, 1); WAIT_V(4); BAR; WAIT_L(0); MMA(1, 0, At, B0); MMA(1, 1, At, B1); BAR; }
	s_waitcnt lgkmcnt(0)
	v_mfma_f32_16x16x32_bf16 v[62:65], v[130:133], v[164:167], v[62:65]
	v_mfma_f32_16x16x32_bf16 v[58:61], v[156:159], v[164:167], v[58:61]
	v_mfma_f32_16x16x32_bf16 v[54:57], v[130:133], v[172:175], v[54:57]
	v_mfma_f32_16x16x32_bf16 v[50:53], v[156:159], v[172:175], v[50:53]
	v_mfma_f32_16x16x32_bf16 v[46:49], v[130:133], v[194:197], v[46:49]
	v_mfma_f32_16x16x32_bf16 v[42:45], v[156:159], v[194:197], v[42:45]
	v_mfma_f32_16x16x32_bf16 v[38:41], v[130:133], v[202:205], v[38:41]
	v_mfma_f32_16x16x32_bf16 v[34:37], v[156:159], v[202:205], v[34:37]
	v_mfma_f32_16x16x32_bf16 v[62:65], v[152:155], v[168:171], v[62:65]
	v_mfma_f32_16x16x32_bf16 v[58:61], v[160:163], v[168:171], v[58:61]
	v_mfma_f32_16x16x32_bf16 v[54:57], v[152:155], v[176:179], v[54:57]
	v_mfma_f32_16x16x32_bf16 v[50:53], v[160:163], v[176:179], v[50:53]
	v_mfma_f32_16x16x32_bf16 v[46:49], v[152:155], v[198:201], v[46:49]
	v_mfma_f32_16x16x32_bf16 v[42:45], v[160:163], v[198:201], v[42:45]
	v_mfma_f32_16x16x32_bf16 v[38:41], v[152:155], v[206:209], v[38:41]
	v_mfma_f32_16x16x32_bf16 v[34:37], v[160:163], v[206:209], v[34:37]


; #define LDA(dst, b, h) for (int m = 0; m < 4; ++m) for (int k = 0; k < 2; ++k) \
;     dst[m][k] = *reinterpret_cast<const bf16x8*>((char*)SA(b, h) + a_thr + (m * 2 + k) * 1024)
; #define MMA(ai, bj, At, Btf) do { __builtin_amdgcn_s_setprio(1); \
;     for (int m = 0; m < 4; ++m) for (int n = 0; n < 2; ++n) for (int k = 0; k < 2; ++k) \
;       acc[ai][bj][m][n] = __builtin_amdgcn_mfma_f32_16x16x32_bf16(Btf[n][k], At[m][k], acc[ai][bj][m][n], 0, 0, 0); \
;     __builtin_amdgcn_s_setprio(0); } while (0)
; #define WAIT_V(n) asm volatile("s_waitcnt vmcnt(" #n ")" ::: "memory")
; #define WAIT_L(n) asm volatile("s_waitcnt lgkmcnt(" #n ")" ::: "memory")
; #define BAR __builtin_amdgcn_s_barrier()
; template <bool OVL, bool PANEL = false, class Epi>
; __device__ __forceinline__ void gemm_phase(const bf16_t* __restrict__ A, long lda, const bf16_t* __restrict__ Bt, long ldb, int nM, int nN, int K,
;                                            const Epi& epi, bf16_t* shm, int w0) {
;     ...
;       LDA(At, 0, 1); WAIT_V(4); BAR; WAIT_L(0); MMA(1, 0, At, B0); MMA(1, 1, At, B1); BAR; }
	v_mfma_f32_16x16x32_bf16 v[30:33], v[148:151], v[164:167], v[30:33]
	v_mfma_f32_16x16x32_bf16 v[26:29], v[214:217], v[164:167], v[26:29]
	v_mfma_f32_16x16x32_bf16 v[22:25], v[148:151], v[172:175], v[22:25]
	v_mfma_f32_16x16x32_bf16 v[18:21], v[214:217], v[172:175], v[18:21]
	v_mfma_f32_16x16x32_bf16 v[14:17], v[148:151], v[194:197], v[14:17]
	v_mfma_f32_16x16x32_bf16 v[10:13], v[214:217], v[194:197], v[10:13]
	v_mfma_f32_16x16x32_bf16 v[6:9], v[148:151], v[202:205], v[6:9]
	v_mfma_f32_16x16x32_bf16 v[2:5], v[214:217], v[202:205], v[2:5]
	v_mfma_f32_16x16x32_bf16 v[30:33], v[210:213], v[168:171], v[30:33]
	v_mfma_f32_16x16x32_bf16 v[26:29], v[218:221], v[168:171], v[26:29]
	v_mfma_f32_16x16x32_bf16 v[22:25], v[210:213], v[176:179], v[22:25]
	v_mfma_f32_16x16x32_bf16 v[18:21], v[218:221], v[176:179], v[18:21]
	v_mfma_f32_16x16x32_bf16 v[14:17], v[210:213], v[198:201], v[14:17]
	v_mfma_f32_16x16x32_bf16 v[10:13], v[218:221], v[198:201], v[10:13]
	v_mfma_f32_16x16x32_bf16 v[6:9], v[210:213], v[206:209], v[6:9]
	v_mfma_f32_16x16x32_bf16 v[2:5], v[218:221], v[206:209], v[2:5]

; #define LDA(dst, b, h) for (int m = 0; m < 4; ++m) for (int k = 0; k < 2; ++k) \
;     dst[m][k] = *reinterpret_cast<const bf16x8*>((char*)SA(b, h) + a_thr + (m * 2 + k) * 1024)
; #define LDB(dst, b, h) for (int n = 0; n < 2; ++n) for (int k = 0; k < 2; ++k) \
;     dst[n][k] = *reinterpret_cast<const bf16x8*>((char*)SB(b, h) + b_thr + (n * 2 + k) * 1024)
; #define MMA(ai, bj, At, Btf) do { __builtin_amdgcn_s_setprio(1); \
;     for (int m = 0; m < 4; ++m) for (int n = 0; n < 2; ++n) for (int k = 0; k < 2; ++k) \
;       acc[ai][bj][m][n] = __builtin_amdgcn_mfma_f32_16x16x32_bf16(Btf[n][k], At[m][k], acc[ai][bj][m][n], 0, 0, 0); \
;     __builtin_amdgcn_s_setprio(0); } while (0)
; #define WAIT_V(n) asm volatile("s_waitcnt vmcnt(" #n ")" ::: "memory")
; #define WAIT_L(n) asm volatile("s_waitcnt lgkmcnt(" #n ")" ::: "memory")
; #define BAR __builtin_amdgcn_s_barrier()
; template <bool OVL, bool PANEL = false, class Epi>
; __device__ __forceinline__ void gemm_phase(const bf16_t* __restrict__ A, long lda, const bf16_t* __restrict__ Bt, long ldb, int nM, int nN, int K,
;                                            const Epi& epi, bf16_t* shm, int w0) {
;     ...
;     { LDB(B0, 1, 0); LDA(At, 1, 0); WAIT_V(2); BAR; WAIT_L(0); MMA(0, 0, At, B0); BAR;
	v_add_u32_e32 v0, 0x18000, v182
	s_barrier
	ds_read_b128 v[130:133], v0
	ds_read_b128 v[148:151], v0 offset:1024
	ds_read_b128 v[152:155], v0 offset:2048
	ds_read_b128 v[156:159], v0 offset:3072
	ds_read_b128 v[160:163], v147 offset:32768
	ds_read_b128 v[164:167], v147 offset:33792
	ds_read_b128 v[168:171], v147 offset:34816
	ds_read_b128 v[172:175], v147 offset:35840
	ds_read_b128 v[176:179], v147 offset:36864
	ds_read_b128 v[194:197], v147 offset:37888
	ds_read_b128 v[198:201], v147 offset:38912
	ds_read_b128 v[202:205], v147 offset:39936
	s_waitcnt vmcnt(2)
	s_barrier
	s_waitcnt lgkmcnt(0)

; #define LDA(dst, b, h) for (int m = 0; m < 4; ++m) for (int k = 0; k < 2; ++k) \
;     dst[m][k] = *reinterpret_cast<const bf16x8*>((char*)SA(b, h) + a_thr + (m * 2 + k) * 1024)
; #define LDB(dst, b, h) for (int n = 0; n < 2; ++n) for (int k = 0; k < 2; ++k) \
;     dst[n][k] = *reinterpret_cast<const bf16x8*>((char*)SB(b, h) + b_thr + (n * 2 + k) * 1024)
; #define MMA(ai, bj, At, Btf) do { __builtin_amdgcn_s_setprio(1); \
;     for (int m = 0; m < 4; ++m) for (int n = 0; n < 2; ++n) for (int k = 0; k < 2; ++k) \
;       acc[ai][bj][m][n] = __builtin_amdgcn_mfma_f32_16x16x32_bf16(Btf[n][k], At[m][k], acc[ai][bj][m][n], 0, 0, 0); \
;     __builtin_amdgcn_s_setprio(0); } while (0)
; #define WAIT_V(n) asm volatile("s_waitcnt vmcnt(" #n ")" ::: "memory")
; #define WAIT_L(n) asm volatile("s_waitcnt lgkmcnt(" #n ")" ::: "memory")
; #define BAR __builtin_amdgcn_s_barrier()
; template <bool OVL, bool PANEL = false, class Epi>
; __device__ __forceinline__ void gemm_phase(const bf16_t* __restrict__ A, long lda, const bf16_t* __restrict__ Bt, long ldb, int nM, int nN, int K,
;                                            const Epi& epi, bf16_t* shm, int w0) {
;     ...
;     { LDB(B0, 1, 0); LDA(At, 1, 0); WAIT_V(2); BAR; WAIT_L(0); MMA(0, 0, At, B0); BAR;
	s_waitcnt lgkmcnt(0)
	v_mfma_f32_16x16x32_bf16 v[126:129], v[130:133], v[160:163], v[126:129]
	v_mfma_f32_16x16x32_bf16 v[122:125], v[152:155], v[160:163], v[122:125]
	v_mfma_f32_16x16x32_bf16 v[118:121], v[130:133], v[168:171], v[118:121]
	v_mfma_f32_16x16x32_bf16 v[114:117], v[152:155], v[168:171], v[114:117]
	v_mfma_f32_16x16x32_bf16 v[110:113], v[130:133], v[176:179], v[110:113]
	v_mfma_f32_16x16x32_bf16 v[106:109], v[152:155], v[176:179], v[106:109]
	v_mfma_f32_16x16x32_bf16 v[102:105], v[130:133], v[198:201], v[102:105]
	v_mfma_f32_16x16x32_bf16 v[98:101], v[152:155], v[198:201], v[98:101]
	v_mfma_f32_16x16x32_bf16 v[126:129], v[148:151], v[164:167], v[126:129]
	v_mfma_f32_16x16x32_bf16 v[122:125], v[156:159], v[164:167], v[122:125]
	v_mfma_f32_16x16x32_bf16 v[118:121], v[148:151], v[172:175], v[118:121]
	v_mfma_f32_16x16x32_bf16 v[114:117], v[156:159], v[172:175], v[114:117]
	v_mfma_f32_16x16x32_bf16 v[110:113], v[148:151], v[194:197], v[110:113]
	v_mfma_f32_16x16x32_bf16 v[106:109], v[156:159], v[194:197], v[106:109]
	v_mfma_f32_16x16x32_bf16 v[102:105], v[148:151], v[202:205], v[102:105]
	v_mfma_f32_16x16x32_bf16 v[98:101], v[156:159], v[202:205], v[98:101]

; #define LDB(dst, b, h) for (int n = 0; n < 2; ++n) for (int k = 0; k < 2; ++k) \
;     dst[n][k] = *reinterpret_cast<const bf16x8*>((char*)SB(b, h) + b_thr + (n * 2 + k) * 1024)
; #define MMA(ai, bj, At, Btf) do { __builtin_amdgcn_s_setprio(1); \
;     for (int m = 0; m < 4; ++m) for (int n = 0; n < 2; ++n) for (int k = 0; k < 2; ++k) \
;       acc[ai][bj][m][n] = __builtin_amdgcn_mfma_f32_16x16x32_bf16(Btf[n][k], At[m][k], acc[ai][bj][m][n], 0, 0, 0); \
;     __builtin_amdgcn_s_setprio(0); } while (0)
; #define WAIT_V(n) asm volatile("s_waitcnt vmcnt(" #n ")" ::: "memory")
; #define WAIT_L(n) asm volatile("s_waitcnt lgkmcnt(" #n ")" ::: "memory")
; #define BAR __builtin_amdgcn_s_barrier()
; template <bool OVL, bool PANEL = false, class Epi>
; __device__ __forceinline__ void gemm_phase(const bf16_t* __restrict__ A, long lda, const bf16_t* __restrict__ Bt, long ldb, int nM, int nN, int K,
;                                            const Epi& epi, bf16_t* shm, int w0) {
;     ...
;       LDB(B1, 1, 1); WAIT_V(0); BAR; WAIT_L(0); MMA(0, 1, At, B1); BAR;
	v_add_u32_e32 v0, 0x1c000, v182
	s_barrier
	ds_read_b128 v[206:209], v0
	ds_read_b128 v[210:213], v0 offset:1024
	ds_read_b128 v[214:217], v0 offset:2048
	ds_read_b128 v[218:221], v0 offset:3072
	s_waitcnt vmcnt(0)
	s_barrier
	s_waitcnt lgkmcnt(0)

; #define LDB(dst, b, h) for (int n = 0; n < 2; ++n) for (int k = 0; k < 2; ++k) \
;     dst[n][k] = *reinterpret_cast<const bf16x8*>((char*)SB(b, h) + b_thr + (n * 2 + k) * 1024)
; #define MMA(ai, bj, At, Btf) do { __builtin_amdgcn_s_setprio(1); \
;     for (int m = 0; m < 4; ++m) for (int n = 0; n < 2; ++n) for (int k = 0; k < 2; ++k) \
;       acc[ai][bj][m][n] = __builtin_amdgcn_mfma_f32_16x16x32_bf16(Btf[n][k], At[m][k], acc[ai][bj][m][n], 0, 0, 0); \
;     __builtin_amdgcn_s_setprio(0); } while (0)
; #define WAIT_V(n) asm volatile("s_waitcnt vmcnt(" #n ")" ::: "memory")
; #define WAIT_L(n) asm volatile("s_waitcnt lgkmcnt(" #n ")" ::: "memory")
; #define BAR __builtin_amdgcn_s_barrier()
; template <bool OVL, bool PANEL = false, class Epi>
; __device__ __forceinline__ void gemm_phase(const bf16_t* __restrict__ A, long lda, const bf16_t* __restrict__ Bt, long ldb, int nM, int nN, int K,
;                                            const Epi& epi, bf16_t* shm, int w0) {
;     ...
;       LDB(B1, 1, 1); WAIT_V(0); BAR; WAIT_L(0); MMA(0, 1, At, B1); BAR;
	s_waitcnt lgkmcnt(0)
	v_mfma_f32_16x16x32_bf16 v[94:97], v[206:209], v[160:163], v[94:97]
	v_mfma_f32_16x16x32_bf16 v[90:93], v[214:217], v[160:163], v[90:93]
	v_mfma_f32_16x16x32_bf16 v[86:89], v[206:209], v[168:171], v[86:89]
	v_mfma_f32_16x16x32_bf16 v[82:85], v[214:217], v[168:171], v[82:85]
	v_mfma_f32_16x16x32_bf16 v[78:81], v[206:209], v[176:179], v[78:81]
	v_mfma_f32_16x16x32_bf16 v[74:77], v[214:217], v[176:179], v[74:77]
	v_mfma_f32_16x16x32_bf16 v[70:73], v[206:209], v[198:201], v[70:73]
	v_mfma_f32_16x16x32_bf16 v[66:69], v[214:217], v[198:201], v[66:69]
	v_mfma_f32_16x16x32_bf16 v[94:97], v[210:213], v[164:167], v[94:97]
	v_mfma_f32_16x16x32_bf16 v[90:93], v[218:221], v[164:167], v[90:93]
	v_mfma_f32_16x16x32_bf16 v[86:89], v[210:213], v[172:175], v[86:89]
	v_mfma_f32_16x16x32_bf16 v[82:85], v[218:221], v[172:175], v[82:85]
	v_mfma_f32_16x16x32_bf16 v[78:81], v[210:213], v[194:197], v[78:81]
	v_mfma_f32_16x16x32_bf16 v[74:77], v[218:221], v[194:197], v[74:77]
	v_mfma_f32_16x16x32_bf16 v[70:73], v[210:213], v[202:205], v[70:73]
	v_mfma_f32_16x16x32_bf16 v[66:69], v[218:221], v[202:205], v[66:69]

; #define LDA(dst, b, h) for (int m = 0; m < 4; ++m) for (int k = 0; k < 2; ++k) \
;     dst[m][k] = *reinterpret_cast<const bf16x8*>((char*)SA(b, h) + a_thr + (m * 2 + k) * 1024)
; #define MMA(ai, bj, At, Btf) do { __builtin_amdgcn_s_setprio(1); \
;     for (int m = 0; m < 4; ++m) for (int n = 0; n < 2; ++n) for (int k = 0; k < 2; ++k) \
;       acc[ai][bj][m][n] = __builtin_amdgcn_mfma_f32_16x16x32_bf16(Btf[n][k], At[m][k], acc[ai][bj][m][n], 0, 0, 0); \
;     __builtin_amdgcn_s_setprio(0); } while (0)
; #define WAIT_L(n) asm volatile("s_waitcnt lgkmcnt(" #n ")" ::: "memory")
; #define BAR __builtin_amdgcn_s_barrier()
; template <bool OVL, bool PANEL = false, class Epi>
; __device__ __forceinline__ void gemm_phase(const bf16_t* __restrict__ A, long lda, const bf16_t* __restrict__ Bt, long ldb, int nM, int nN, int K,
;                                            const Epi& epi, bf16_t* shm, int w0) {
;     ...
;       LDA(At, 1, 1); BAR; WAIT_L(0); MMA(1, 0, At, B0); MMA(1, 1, At, B1); BAR; }
	s_barrier
	ds_read_b128 v[160:163], v147 offset:49152
	ds_read_b128 v[164:167], v147 offset:50176
	ds_read_b128 v[168:171], v147 offset:51200
	ds_read_b128 v[172:175], v147 offset:52224
	ds_read_b128 v[176:179], v147 offset:53248
	ds_read_b128 v[194:197], v147 offset:54272
	ds_read_b128 v[198:201], v147 offset:55296
	ds_read_b128 v[202:205], v147 offset:56320
	s_barrier
	s_waitcnt lgkmcnt(0)

; #define LDA(dst, b, h) for (int m = 0; m < 4; ++m) for (int k = 0; k < 2; ++k) \
;     dst[m][k] = *reinterpret_cast<const bf16x8*>((char*)SA(b, h) + a_thr + (m * 2 + k) * 1024)
; #define MMA(ai, bj, At, Btf) do { __builtin_amdgcn_s_setprio(1); \
;     for (int m = 0; m < 4; ++m) for (int n = 0; n < 2; ++n) for (int k = 0; k < 2; ++k) \
;       acc[ai][bj][m][n] = __builtin_amdgcn_mfma_f32_16x16x32_bf16(Btf[n][k], At[m][k], acc[ai][bj][m][n], 0, 0, 0); \
;     __builtin_amdgcn_s_setprio(0); } while (0)
; #define WAIT_L(n) asm volatile("s_waitcnt lgkmcnt(" #n ")" ::: "memory")
; #define BAR __builtin_amdgcn_s_barrier()
; template <bool OVL, bool PANEL = false, class Epi>
; __device__ __forceinline__ void gemm_phase(const bf16_t* __restrict__ A, long lda, const bf16_t* __restrict__ Bt, long ldb, int nM, int nN, int K,
;                                            const Epi& epi, bf16_t* shm, int w0) {
;     ...
;       LDA(At, 1, 1); BAR; WAIT_L(0); MMA(1, 0, At, B0); MMA(1, 1, At, B1); BAR; }
	s_waitcnt lgkmcnt(0)
	v_mfma_f32_16x16x32_bf16 v[62:65], v[130:133], v[160:163], v[62:65]
	v_mfma_f32_16x16x32_bf16 v[58:61], v[152:155], v[160:163], v[58:61]
	v_mfma_f32_16x16x32_bf16 v[54:57], v[130:133], v[168:171], v[54:57]
	v_mfma_f32_16x16x32_bf16 v[50:53], v[152:155], v[168:171], v[50:53]
	v_mfma_f32_16x16x32_bf16 v[46:49], v[130:133], v[176:179], v[46:49]
	v_mfma_f32_16x16x32_bf16 v[42:45], v[152:155], v[176:179], v[42:45]
	v_mfma_f32_16x16x32_bf16 v[38:41], v[130:133], v[198:201], v[38:41]
	v_mfma_f32_16x16x32_bf16 v[34:37], v[152:155], v[198:201], v[34:37]
	v_mfma_f32_16x16x32_bf16 v[62:65], v[148:151], v[164:167], v[62:65]
	v_mfma_f32_16x16x32_bf16 v[58:61], v[156:159], v[164:167], v[58:61]
	v_mfma_f32_16x16x32_bf16 v[54:57], v[148:151], v[172:175], v[54:57]
	v_mfma_f32_16x16x32_bf16 v[50:53], v[156:159], v[172:175], v[50:53]
	v_mfma_f32_16x16x32_bf16 v[46:49], v[148:151], v[194:197], v[46:49]
	v_mfma_f32_16x16x32_bf16 v[42:45], v[156:159], v[194:197], v[42:45]
	v_mfma_f32_16x16x32_bf16 v[38:41], v[148:151], v[202:205], v[38:41]
	v_mfma_f32_16x16x32_bf16 v[34:37], v[156:159], v[202:205], v[34:37]


; #define LDA(dst, b, h) for (int m = 0; m < 4; ++m) for (int k = 0; k < 2; ++k) \
;     dst[m][k] = *reinterpret_cast<const bf16x8*>((char*)SA(b, h) + a_thr + (m * 2 + k) * 1024)
; #define MMA(ai, bj, At, Btf) do { __builtin_amdgcn_s_setprio(1); \
;     for (int m = 0; m < 4; ++m) for (int n = 0; n < 2; ++n) for (int k = 0; k < 2; ++k) \
;       acc[ai][bj][m][n] = __builtin_amdgcn_mfma_f32_16x16x32_bf16(Btf[n][k], At[m][k], acc[ai][bj][m][n], 0, 0, 0); \
;     __builtin_amdgcn_s_setprio(0); } while (0)
; #define WAIT_L(n) asm volatile("s_waitcnt lgkmcnt(" #n ")" ::: "memory")
; #define BAR __builtin_amdgcn_s_barrier()
; template <bool OVL, bool PANEL = false, class Epi>
; __device__ __forceinline__ void gemm_phase(const bf16_t* __restrict__ A, long lda, const bf16_t* __restrict__ Bt, long ldb, int nM, int nN, int K,
;                                            const Epi& epi, bf16_t* shm, int w0) {
;     ...
;       LDA(At, 1, 1); BAR; WAIT_L(0); MMA(1, 0, At, B0); MMA(1, 1, At, B1); BAR; }
	v_mfma_f32_16x16x32_bf16 v[30:33], v[206:209], v[160:163], v[30:33]
	v_mfma_f32_16x16x32_bf16 v[26:29], v[214:217], v[160:163], v[26:29]
	v_mfma_f32_16x16x32_bf16 v[22:25], v[206:209], v[168:171], v[22:25]
	v_mfma_f32_16x16x32_bf16 v[18:21], v[214:217], v[168:171], v[18:21]
	v_mfma_f32_16x16x32_bf16 v[14:17], v[206:209], v[176:179], v[14:17]
	v_mfma_f32_16x16x32_bf16 v[10:13], v[214:217], v[176:179], v[10:13]
	v_mfma_f32_16x16x32_bf16 v[6:9], v[206:209], v[198:201], v[6:9]
	v_mfma_f32_16x16x32_bf16 v[2:5], v[214:217], v[198:201], v[2:5]
	v_mfma_f32_16x16x32_bf16 v[30:33], v[210:213], v[164:167], v[30:33]
	v_mfma_f32_16x16x32_bf16 v[26:29], v[218:221], v[164:167], v[26:29]
	v_mfma_f32_16x16x32_bf16 v[22:25], v[210:213], v[172:175], v[22:25]
	v_mfma_f32_16x16x32_bf16 v[18:21], v[218:221], v[172:175], v[18:21]
	v_mfma_f32_16x16x32_bf16 v[14:17], v[210:213], v[194:197], v[14:17]
	v_mfma_f32_16x16x32_bf16 v[10:13], v[218:221], v[194:197], v[10:13]
	v_mfma_f32_16x16x32_bf16 v[6:9], v[210:213], v[202:205], v[6:9]
	v_mfma_f32_16x16x32_bf16 v[2:5], v[218:221], v[202:205], v[2:5]

; #define LDA(dst, b, h) for (int m = 0; m < 4; ++m) for (int k = 0; k < 2; ++k) \
;     dst[m][k] = *reinterpret_cast<const bf16x8*>((char*)SA(b, h) + a_thr + (m * 2 + k) * 1024)
; #define MMA(ai, bj, At, Btf) do { __builtin_amdgcn_s_setprio(1); \
;     for (int m = 0; m < 4; ++m) for (int n = 0; n < 2; ++n) for (int k = 0; k < 2; ++k) \
;       acc[ai][bj][m][n] = __builtin_amdgcn_mfma_f32_16x16x32_bf16(Btf[n][k], At[m][k], acc[ai][bj][m][n], 0, 0, 0); \
;     __builtin_amdgcn_s_setprio(0); } while (0)
; #define WAIT_L(n) asm volatile("s_waitcnt lgkmcnt(" #n ")" ::: "memory")
; #define BAR __builtin_amdgcn_s_barrier()
; template <bool OVL, bool PANEL = false, class Epi>
; __device__ __forceinline__ void gemm_phase(const bf16_t* __restrict__ A, long lda, const bf16_t* __restrict__ Bt, long ldb, int nM, int nN, int K,
;                                            const Epi& epi, bf16_t* shm, int w0) {
;     ...
;       LDA(At, 1, 1); BAR; WAIT_L(0); MMA(1, 0, At, B0); MMA(1, 1, At, B1); BAR; }
;     if (wr == 0) BAR;
	s_barrier
	s_and_saveexec_b64 s[8:9], s[6:7]
	s_cbranch_execz .LBB0_1056
	s_barrier
